# speedup vs baseline: 1.0359x; 1.0090x over previous
; #define LDA(dst, b, h)                                                                                     \
;   _Pragma("unroll") for (int m = 0; m < 4; ++m) _Pragma("unroll") for (int k = 0; k < 2; ++k) dst[m][k] = \
;       *reinterpret_cast<const bf16x8*>(shmc + aL + (((b) * 2 + (h)) * 16384 + (m * 2 + k) * 1024))
; #define LDB(dst, b, h)                                                                                     \
;   _Pragma("unroll") for (int n = 0; n < 2; ++n) _Pragma("unroll") for (int k = 0; k < 2; ++k) dst[n][k] = \
;       *reinterpret_cast<const bf16x8*>(shmc + bL + (((b) * 2 + (h)) * 16384 + (n * 2 + k) * 1024))
; #define OPAQ asm volatile("" : "+v"(aL), "+v"(bL))
; #define WAIT_V(n) asm volatile("s_waitcnt vmcnt(" #n ")" ::: "memory")
; #define WAIT_L(n) asm volatile("s_waitcnt lgkmcnt(" #n ")" ::: "memory")
; #define BAR __builtin_amdgcn_s_barrier()
; #define SCHED __builtin_amdgcn_sched_barrier(0)
; template <int EPI>
; __device__ __forceinline__ void phase_gemm(const Params& p, const GemmDesc& d, char* shmc) {
;     ...
;     for (int t = 0; t < nt - 2; t += 2) {
;       OPAQ;
;       LDB(B0, 0, 0); SCHED; LDA(At, 0, 0); STAGE_A(SA(1, 1), 1, t + 1);
;       WAIT_L(8); BAR; WAIT_L(0); MMA(0, 0, At, B0); BAR; SCHED;
;       LDB(B1, 0, 1); STAGE_B(SB(0, 0), 0, t + 2);
;       BAR; WAIT_L(0); MMA(0, 1, At, B1); BAR;
;       LDA(At, 0, 1); STAGE_A(SA(0, 0), 0, t + 2);
;       BAR; WAIT_L(0); MMA(1, 0, At, B0); BAR; SCHED;
;       STAGE_B(SB(0, 1), 1, t + 2);
;       WAIT_V(6); BAR; MMA(1, 1, At, B1); BAR;
;       LDB(B0, 1, 0); SCHED; LDA(At, 1, 0); STAGE_A(SA(0, 1), 1, t + 2);
;       WAIT_L(8); BAR; WAIT_L(0); MMA(0, 0, At, B0); BAR; SCHED;
;       LDB(B1, 1, 1); STAGE_B(SB(1, 0), 0, t + 3);
;       BAR; WAIT_L(0); MMA(0, 1, At, B1); BAR;
;       LDA(At, 1, 1); STAGE_A(SA(1, 0), 0, t + 3);
;       BAR; WAIT_L(0); MMA(1, 0, At, B0); BAR; SCHED;
;       STAGE_B(SB(1, 1), 1, t + 3);
;       WAIT_V(6); BAR; MMA(1, 1, At, B1); BAR;
;     }
.LBB0_296:
	s_nop 0
	v_add_u32_e32 v162, 0, v205
	v_add_u32_e32 v175, 0, v204
	s_setprio 0
	ds_read_b128 v[138:141], v162
	ds_read_b128 v[142:145], v162 offset:1024
	ds_read_b128 v[146:149], v162 offset:2048
	ds_read_b128 v[150:153], v162 offset:3072
	ds_read_b128 v[208:211], v162 offset:16384
	ds_read_b128 v[212:215], v162 offset:17408
	ds_read_b128 v[216:219], v162 offset:18432
	ds_read_b128 v[220:223], v162 offset:19456
	v_lshl_add_u64 v[202:203], v[134:135], 0, s[10:11]
	v_lshl_add_u64 v[224:225], v[136:137], 0, s[10:11]
	v_lshl_add_u64 v[226:227], v[130:131], 0, s[10:11]
	v_lshl_add_u64 v[228:229], v[132:133], 0, s[10:11]
	ds_read_b128 v[154:157], v175
	ds_read_b128 v[158:161], v175 offset:1024
	ds_read_b128 v[178:181], v175 offset:2048
	ds_read_b128 v[182:185], v175 offset:3072
	ds_read_b128 v[186:189], v175 offset:4096
	ds_read_b128 v[190:193], v175 offset:5120
	ds_read_b128 v[194:197], v175 offset:6144
	ds_read_b128 v[198:201], v175 offset:7168
	s_mov_b32 m0, s93
	v_lshl_add_u64 v[230:231], v[202:203], 0, s[38:39]
	global_load_lds_dwordx4 v[230:231], off
	v_lshl_add_u64 v[230:231], v[224:225], 0, s[38:39]
	s_mov_b32 m0, s94
	s_nop 0
	global_load_lds_dwordx4 v[230:231], off
	s_waitcnt vmcnt(8)
	s_waitcnt lgkmcnt(0)
	s_setprio 1
	s_barrier
	v_mfma_f32_16x16x32_bf16 v[2:5], v[154:157], v[138:141], v[2:5]
	v_mfma_f32_16x16x32_bf16 v[6:9], v[154:157], v[146:149], v[6:9]
	v_mfma_f32_16x16x32_bf16 v[10:13], v[178:181], v[138:141], v[10:13]
	v_mfma_f32_16x16x32_bf16 v[18:21], v[178:181], v[146:149], v[18:21]
	v_mfma_f32_16x16x32_bf16 v[30:33], v[186:189], v[138:141], v[30:33]
	v_mfma_f32_16x16x32_bf16 v[42:45], v[186:189], v[146:149], v[42:45]
	v_mfma_f32_16x16x32_bf16 v[54:57], v[194:197], v[138:141], v[54:57]
	v_mfma_f32_16x16x32_bf16 v[66:69], v[194:197], v[146:149], v[66:69]
	v_mfma_f32_16x16x32_bf16 v[2:5], v[158:161], v[142:145], v[2:5]
	v_mfma_f32_16x16x32_bf16 v[6:9], v[158:161], v[150:153], v[6:9]
	v_mfma_f32_16x16x32_bf16 v[10:13], v[182:185], v[142:145], v[10:13]
	v_mfma_f32_16x16x32_bf16 v[18:21], v[182:185], v[150:153], v[18:21]
	v_mfma_f32_16x16x32_bf16 v[30:33], v[190:193], v[142:145], v[30:33]
	v_mfma_f32_16x16x32_bf16 v[42:45], v[190:193], v[150:153], v[42:45]
	v_mfma_f32_16x16x32_bf16 v[54:57], v[198:201], v[142:145], v[54:57]
	v_mfma_f32_16x16x32_bf16 v[66:69], v[198:201], v[150:153], v[66:69]
	v_mfma_f32_16x16x32_bf16 v[14:17], v[154:157], v[208:211], v[14:17]
	v_mfma_f32_16x16x32_bf16 v[22:25], v[154:157], v[216:219], v[22:25]
	v_mfma_f32_16x16x32_bf16 v[34:37], v[178:181], v[208:211], v[34:37]
	v_mfma_f32_16x16x32_bf16 v[46:49], v[178:181], v[216:219], v[46:49]
	v_mfma_f32_16x16x32_bf16 v[58:61], v[186:189], v[208:211], v[58:61]
	v_mfma_f32_16x16x32_bf16 v[70:73], v[186:189], v[216:219], v[70:73]
	v_mfma_f32_16x16x32_bf16 v[78:81], v[194:197], v[208:211], v[78:81]
	v_mfma_f32_16x16x32_bf16 v[86:89], v[194:197], v[216:219], v[86:89]
	v_mfma_f32_16x16x32_bf16 v[14:17], v[158:161], v[212:215], v[14:17]
	v_mfma_f32_16x16x32_bf16 v[22:25], v[158:161], v[220:223], v[22:25]
	v_mfma_f32_16x16x32_bf16 v[34:37], v[182:185], v[212:215], v[34:37]
	v_mfma_f32_16x16x32_bf16 v[46:49], v[182:185], v[220:223], v[46:49]
	v_mfma_f32_16x16x32_bf16 v[58:61], v[190:193], v[212:215], v[58:61]
	v_mfma_f32_16x16x32_bf16 v[70:73], v[190:193], v[220:223], v[70:73]
	v_mfma_f32_16x16x32_bf16 v[78:81], v[198:201], v[212:215], v[78:81]
	v_mfma_f32_16x16x32_bf16 v[86:89], v[198:201], v[220:223], v[86:89]
	s_barrier
	s_setprio 0
	ds_read_b128 v[154:157], v175 offset:16384
	ds_read_b128 v[158:161], v175 offset:17408
	ds_read_b128 v[178:181], v175 offset:18432
	ds_read_b128 v[182:185], v175 offset:19456
	ds_read_b128 v[186:189], v175 offset:20480
	ds_read_b128 v[190:193], v175 offset:21504
	ds_read_b128 v[194:197], v175 offset:22528
	ds_read_b128 v[198:201], v175 offset:23552
	s_mov_b32 m0, s80
	v_lshl_add_u64 v[230:231], v[226:227], 0, s[40:41]
	global_load_lds_dwordx4 v[230:231], off
	v_lshl_add_u64 v[230:231], v[228:229], 0, s[40:41]
	s_mov_b32 m0, s81
	s_nop 0
	global_load_lds_dwordx4 v[230:231], off
	s_mov_b32 m0, s77
	v_lshl_add_u64 v[230:231], v[202:203], 0, s[42:43]
	global_load_lds_dwordx4 v[230:231], off
	v_lshl_add_u64 v[230:231], v[224:225], 0, s[42:43]
	s_mov_b32 m0, s82
	s_nop 0
	global_load_lds_dwordx4 v[230:231], off
	s_mov_b32 m0, s83
	v_lshl_add_u64 v[230:231], v[226:227], 0, s[48:49]
	global_load_lds_dwordx4 v[230:231], off
	v_lshl_add_u64 v[230:231], v[228:229], 0, s[48:49]
	s_mov_b32 m0, s84
	s_nop 0
	global_load_lds_dwordx4 v[230:231], off
	s_waitcnt vmcnt(8)
	s_waitcnt lgkmcnt(0)
	s_setprio 1
	s_barrier
; #define LDA(dst, b, h)                                                                                     \
;   _Pragma("unroll") for (int m = 0; m < 4; ++m) _Pragma("unroll") for (int k = 0; k < 2; ++k) dst[m][k] = \
;       *reinterpret_cast<const bf16x8*>(shmc + aL + (((b) * 2 + (h)) * 16384 + (m * 2 + k) * 1024))
; #define LDB(dst, b, h)                                                                                     \
;   _Pragma("unroll") for (int n = 0; n < 2; ++n) _Pragma("unroll") for (int k = 0; k < 2; ++k) dst[n][k] = \
;       *reinterpret_cast<const bf16x8*>(shmc + bL + (((b) * 2 + (h)) * 16384 + (n * 2 + k) * 1024))
; #define OPAQ asm volatile("" : "+v"(aL), "+v"(bL))
; #define WAIT_V(n) asm volatile("s_waitcnt vmcnt(" #n ")" ::: "memory")
; #define WAIT_L(n) asm volatile("s_waitcnt lgkmcnt(" #n ")" ::: "memory")
; #define BAR __builtin_amdgcn_s_barrier()
; #define SCHED __builtin_amdgcn_sched_barrier(0)
; template <int EPI>
; __device__ __forceinline__ void phase_gemm(const Params& p, const GemmDesc& d, char* shmc) {
;     ...
;     for (int t = 0; t < nt - 2; t += 2) {
;       OPAQ;
;       LDB(B0, 0, 0); SCHED; LDA(At, 0, 0); STAGE_A(SA(1, 1), 1, t + 1);
;       WAIT_L(8); BAR; WAIT_L(0); MMA(0, 0, At, B0); BAR; SCHED;
;       LDB(B1, 0, 1); STAGE_B(SB(0, 0), 0, t + 2);
;       BAR; WAIT_L(0); MMA(0, 1, At, B1); BAR;
;       LDA(At, 0, 1); STAGE_A(SA(0, 0), 0, t + 2);
;       BAR; WAIT_L(0); MMA(1, 0, At, B0); BAR; SCHED;
;       STAGE_B(SB(0, 1), 1, t + 2);
;       WAIT_V(6); BAR; MMA(1, 1, At, B1); BAR;
;       LDB(B0, 1, 0); SCHED; LDA(At, 1, 0); STAGE_A(SA(0, 1), 1, t + 2);
;       WAIT_L(8); BAR; WAIT_L(0); MMA(0, 0, At, B0); BAR; SCHED;
;       LDB(B1, 1, 1); STAGE_B(SB(1, 0), 0, t + 3);
;       BAR; WAIT_L(0); MMA(0, 1, At, B1); BAR;
;       LDA(At, 1, 1); STAGE_A(SA(1, 0), 0, t + 3);
;       BAR; WAIT_L(0); MMA(1, 0, At, B0); BAR; SCHED;
;       STAGE_B(SB(1, 1), 1, t + 3);
;       WAIT_V(6); BAR; MMA(1, 1, At, B1); BAR;
;     }
	v_mfma_f32_16x16x32_bf16 v[26:29], v[154:157], v[138:141], v[26:29]
	v_mfma_f32_16x16x32_bf16 v[38:41], v[154:157], v[146:149], v[38:41]
	v_mfma_f32_16x16x32_bf16 v[50:53], v[178:181], v[138:141], v[50:53]
	v_mfma_f32_16x16x32_bf16 v[62:65], v[178:181], v[146:149], v[62:65]
	v_mfma_f32_16x16x32_bf16 v[74:77], v[186:189], v[138:141], v[74:77]
	v_mfma_f32_16x16x32_bf16 v[82:85], v[186:189], v[146:149], v[82:85]
	v_mfma_f32_16x16x32_bf16 v[90:93], v[194:197], v[138:141], v[90:93]
	v_mfma_f32_16x16x32_bf16 v[94:97], v[194:197], v[146:149], v[94:97]
	v_mfma_f32_16x16x32_bf16 v[26:29], v[158:161], v[142:145], v[26:29]
	v_mfma_f32_16x16x32_bf16 v[38:41], v[158:161], v[150:153], v[38:41]
	v_mfma_f32_16x16x32_bf16 v[50:53], v[182:185], v[142:145], v[50:53]
	v_mfma_f32_16x16x32_bf16 v[62:65], v[182:185], v[150:153], v[62:65]
	v_mfma_f32_16x16x32_bf16 v[74:77], v[190:193], v[142:145], v[74:77]
	v_mfma_f32_16x16x32_bf16 v[82:85], v[190:193], v[150:153], v[82:85]
	v_mfma_f32_16x16x32_bf16 v[90:93], v[198:201], v[142:145], v[90:93]
	v_mfma_f32_16x16x32_bf16 v[94:97], v[198:201], v[150:153], v[94:97]
	v_mfma_f32_16x16x32_bf16 v[98:101], v[154:157], v[208:211], v[98:101]
	v_mfma_f32_16x16x32_bf16 v[102:105], v[154:157], v[216:219], v[102:105]
	v_mfma_f32_16x16x32_bf16 v[106:109], v[178:181], v[208:211], v[106:109]
	v_mfma_f32_16x16x32_bf16 v[110:113], v[178:181], v[216:219], v[110:113]
	v_mfma_f32_16x16x32_bf16 v[114:117], v[186:189], v[208:211], v[114:117]
	v_mfma_f32_16x16x32_bf16 v[118:121], v[186:189], v[216:219], v[118:121]
	v_mfma_f32_16x16x32_bf16 v[122:125], v[194:197], v[208:211], v[122:125]
	v_mfma_f32_16x16x32_bf16 v[126:129], v[194:197], v[216:219], v[126:129]
	v_mfma_f32_16x16x32_bf16 v[98:101], v[158:161], v[212:215], v[98:101]
	v_mfma_f32_16x16x32_bf16 v[102:105], v[158:161], v[220:223], v[102:105]
	v_mfma_f32_16x16x32_bf16 v[106:109], v[182:185], v[212:215], v[106:109]
	v_mfma_f32_16x16x32_bf16 v[110:113], v[182:185], v[220:223], v[110:113]
	v_mfma_f32_16x16x32_bf16 v[114:117], v[190:193], v[212:215], v[114:117]
	v_mfma_f32_16x16x32_bf16 v[118:121], v[190:193], v[220:223], v[118:121]
	v_mfma_f32_16x16x32_bf16 v[122:125], v[198:201], v[212:215], v[122:125]
	v_mfma_f32_16x16x32_bf16 v[126:129], v[198:201], v[220:223], v[126:129]
	s_barrier
	s_setprio 0
	ds_read_b128 v[138:141], v162 offset:32768
	ds_read_b128 v[142:145], v162 offset:33792
	ds_read_b128 v[146:149], v162 offset:34816
	ds_read_b128 v[150:153], v162 offset:35840
	ds_read_b128 v[208:211], v162 offset:49152
	ds_read_b128 v[212:215], v162 offset:50176
	ds_read_b128 v[216:219], v162 offset:51200
	ds_read_b128 v[220:223], v162 offset:52224
	ds_read_b128 v[154:157], v175 offset:32768
	ds_read_b128 v[158:161], v175 offset:33792
	ds_read_b128 v[178:181], v175 offset:34816
	ds_read_b128 v[182:185], v175 offset:35840
	ds_read_b128 v[186:189], v175 offset:36864
	ds_read_b128 v[190:193], v175 offset:37888
	ds_read_b128 v[194:197], v175 offset:38912
	ds_read_b128 v[198:201], v175 offset:39936
	s_mov_b32 m0, s85
	v_lshl_add_u64 v[230:231], v[202:203], 0, s[52:53]
	global_load_lds_dwordx4 v[230:231], off
	v_lshl_add_u64 v[230:231], v[224:225], 0, s[52:53]
	s_mov_b32 m0, s86
	s_nop 0
	global_load_lds_dwordx4 v[230:231], off
	s_waitcnt vmcnt(8)
	s_waitcnt lgkmcnt(0)
	s_setprio 1
	s_barrier
	v_mfma_f32_16x16x32_bf16 v[2:5], v[154:157], v[138:141], v[2:5]
	v_mfma_f32_16x16x32_bf16 v[6:9], v[154:157], v[146:149], v[6:9]
	v_mfma_f32_16x16x32_bf16 v[10:13], v[178:181], v[138:141], v[10:13]
	v_mfma_f32_16x16x32_bf16 v[18:21], v[178:181], v[146:149], v[18:21]
	v_mfma_f32_16x16x32_bf16 v[30:33], v[186:189], v[138:141], v[30:33]
	v_mfma_f32_16x16x32_bf16 v[42:45], v[186:189], v[146:149], v[42:45]
	v_mfma_f32_16x16x32_bf16 v[54:57], v[194:197], v[138:141], v[54:57]
	v_mfma_f32_16x16x32_bf16 v[66:69], v[194:197], v[146:149], v[66:69]
	v_mfma_f32_16x16x32_bf16 v[2:5], v[158:161], v[142:145], v[2:5]
	v_mfma_f32_16x16x32_bf16 v[6:9], v[158:161], v[150:153], v[6:9]
	v_mfma_f32_16x16x32_bf16 v[10:13], v[182:185], v[142:145], v[10:13]
	v_mfma_f32_16x16x32_bf16 v[18:21], v[182:185], v[150:153], v[18:21]
	v_mfma_f32_16x16x32_bf16 v[30:33], v[190:193], v[142:145], v[30:33]
	v_mfma_f32_16x16x32_bf16 v[42:45], v[190:193], v[150:153], v[42:45]
	v_mfma_f32_16x16x32_bf16 v[54:57], v[198:201], v[142:145], v[54:57]
	v_mfma_f32_16x16x32_bf16 v[66:69], v[198:201], v[150:153], v[66:69]
	v_mfma_f32_16x16x32_bf16 v[14:17], v[154:157], v[208:211], v[14:17]
	v_mfma_f32_16x16x32_bf16 v[22:25], v[154:157], v[216:219], v[22:25]
	v_mfma_f32_16x16x32_bf16 v[34:37], v[178:181], v[208:211], v[34:37]
	v_mfma_f32_16x16x32_bf16 v[46:49], v[178:181], v[216:219], v[46:49]
	v_mfma_f32_16x16x32_bf16 v[58:61], v[186:189], v[208:211], v[58:61]
	v_mfma_f32_16x16x32_bf16 v[70:73], v[186:189], v[216:219], v[70:73]
	v_mfma_f32_16x16x32_bf16 v[78:81], v[194:197], v[208:211], v[78:81]
	v_mfma_f32_16x16x32_bf16 v[86:89], v[194:197], v[216:219], v[86:89]
	v_mfma_f32_16x16x32_bf16 v[14:17], v[158:161], v[212:215], v[14:17]
	v_mfma_f32_16x16x32_bf16 v[22:25], v[158:161], v[220:223], v[22:25]
	v_mfma_f32_16x16x32_bf16 v[34:37], v[182:185], v[212:215], v[34:37]
	v_mfma_f32_16x16x32_bf16 v[46:49], v[182:185], v[220:223], v[46:49]
	v_mfma_f32_16x16x32_bf16 v[58:61], v[190:193], v[212:215], v[58:61]
	v_mfma_f32_16x16x32_bf16 v[70:73], v[190:193], v[220:223], v[70:73]
	v_mfma_f32_16x16x32_bf16 v[78:81], v[198:201], v[212:215], v[78:81]
	v_mfma_f32_16x16x32_bf16 v[86:89], v[198:201], v[220:223], v[86:89]
	s_barrier
; #define LDA(dst, b, h)                                                                                     \
;   _Pragma("unroll") for (int m = 0; m < 4; ++m) _Pragma("unroll") for (int k = 0; k < 2; ++k) dst[m][k] = \
;       *reinterpret_cast<const bf16x8*>(shmc + aL + (((b) * 2 + (h)) * 16384 + (m * 2 + k) * 1024))
; #define LDB(dst, b, h)                                                                                     \
;   _Pragma("unroll") for (int n = 0; n < 2; ++n) _Pragma("unroll") for (int k = 0; k < 2; ++k) dst[n][k] = \
;       *reinterpret_cast<const bf16x8*>(shmc + bL + (((b) * 2 + (h)) * 16384 + (n * 2 + k) * 1024))
; #define OPAQ asm volatile("" : "+v"(aL), "+v"(bL))
; #define WAIT_V(n) asm volatile("s_waitcnt vmcnt(" #n ")" ::: "memory")
; #define WAIT_L(n) asm volatile("s_waitcnt lgkmcnt(" #n ")" ::: "memory")
; #define BAR __builtin_amdgcn_s_barrier()
; #define SCHED __builtin_amdgcn_sched_barrier(0)
; template <int EPI>
; __device__ __forceinline__ void phase_gemm(const Params& p, const GemmDesc& d, char* shmc) {
;     ...
;     for (int t = 0; t < nt - 2; t += 2) {
;       OPAQ;
;       LDB(B0, 0, 0); SCHED; LDA(At, 0, 0); STAGE_A(SA(1, 1), 1, t + 1);
;       WAIT_L(8); BAR; WAIT_L(0); MMA(0, 0, At, B0); BAR; SCHED;
;       LDB(B1, 0, 1); STAGE_B(SB(0, 0), 0, t + 2);
;       BAR; WAIT_L(0); MMA(0, 1, At, B1); BAR;
;       LDA(At, 0, 1); STAGE_A(SA(0, 0), 0, t + 2);
;       BAR; WAIT_L(0); MMA(1, 0, At, B0); BAR; SCHED;
;       STAGE_B(SB(0, 1), 1, t + 2);
;       WAIT_V(6); BAR; MMA(1, 1, At, B1); BAR;
;       LDB(B0, 1, 0); SCHED; LDA(At, 1, 0); STAGE_A(SA(0, 1), 1, t + 2);
;       WAIT_L(8); BAR; WAIT_L(0); MMA(0, 0, At, B0); BAR; SCHED;
;       LDB(B1, 1, 1); STAGE_B(SB(1, 0), 0, t + 3);
;       BAR; WAIT_L(0); MMA(0, 1, At, B1); BAR;
;       LDA(At, 1, 1); STAGE_A(SA(1, 0), 0, t + 3);
;       BAR; WAIT_L(0); MMA(1, 0, At, B0); BAR; SCHED;
;       STAGE_B(SB(1, 1), 1, t + 3);
;       WAIT_V(6); BAR; MMA(1, 1, At, B1); BAR;
;     }
;     {
;       OPAQ;
;       LDB(B0, 0, 0); LDA(At, 0, 0); STAGE_A(SA(1, 1), 1, nt - 1);
;       BAR; WAIT_L(0); MMA(0, 0, At, B0); BAR;
;       LDB(B1, 0, 1); BAR; WAIT_L(0); MMA(0, 1, At, B1); BAR;
;       LDA(At, 0, 1); WAIT_V(4); BAR; WAIT_L(0); MMA(1, 0, At, B0); MMA(1, 1, At, B1); BAR;
	s_setprio 0
	ds_read_b128 v[154:157], v175 offset:49152
	ds_read_b128 v[158:161], v175 offset:50176
	ds_read_b128 v[178:181], v175 offset:51200
	ds_read_b128 v[182:185], v175 offset:52224
	ds_read_b128 v[186:189], v175 offset:53248
	ds_read_b128 v[190:193], v175 offset:54272
	ds_read_b128 v[194:197], v175 offset:55296
	ds_read_b128 v[198:201], v175 offset:56320
	s_mov_b32 m0, s87
	v_lshl_add_u64 v[230:231], v[226:227], 0, s[54:55]
	global_load_lds_dwordx4 v[230:231], off
	v_lshl_add_u64 v[230:231], v[228:229], 0, s[54:55]
	s_mov_b32 m0, s88
	s_nop 0
	global_load_lds_dwordx4 v[230:231], off
	s_mov_b32 m0, s89
	v_lshl_add_u64 v[230:231], v[202:203], 0, s[56:57]
	global_load_lds_dwordx4 v[230:231], off
	v_lshl_add_u64 v[230:231], v[224:225], 0, s[56:57]
	s_mov_b32 m0, s90
	s_nop 0
	global_load_lds_dwordx4 v[230:231], off
	s_mov_b32 m0, s91
	v_lshl_add_u64 v[230:231], v[226:227], 0, s[58:59]
	global_load_lds_dwordx4 v[230:231], off
	v_lshl_add_u64 v[230:231], v[228:229], 0, s[58:59]
	s_mov_b32 m0, s92
	s_nop 0
	global_load_lds_dwordx4 v[230:231], off
	s_add_i32 s35, s35, 2
	s_add_u32 s10, s10, 0x100
	s_addc_u32 s11, s11, 0
	s_cmp_gt_u32 s35, 27
	s_waitcnt vmcnt(8)
	s_waitcnt lgkmcnt(0)
	s_setprio 1
	s_barrier
	v_mfma_f32_16x16x32_bf16 v[26:29], v[154:157], v[138:141], v[26:29]
	v_mfma_f32_16x16x32_bf16 v[38:41], v[154:157], v[146:149], v[38:41]
	v_mfma_f32_16x16x32_bf16 v[50:53], v[178:181], v[138:141], v[50:53]
	v_mfma_f32_16x16x32_bf16 v[62:65], v[178:181], v[146:149], v[62:65]
	v_mfma_f32_16x16x32_bf16 v[74:77], v[186:189], v[138:141], v[74:77]
	v_mfma_f32_16x16x32_bf16 v[82:85], v[186:189], v[146:149], v[82:85]
	v_mfma_f32_16x16x32_bf16 v[90:93], v[194:197], v[138:141], v[90:93]
	v_mfma_f32_16x16x32_bf16 v[94:97], v[194:197], v[146:149], v[94:97]
	v_mfma_f32_16x16x32_bf16 v[26:29], v[158:161], v[142:145], v[26:29]
	v_mfma_f32_16x16x32_bf16 v[38:41], v[158:161], v[150:153], v[38:41]
	v_mfma_f32_16x16x32_bf16 v[50:53], v[182:185], v[142:145], v[50:53]
	v_mfma_f32_16x16x32_bf16 v[62:65], v[182:185], v[150:153], v[62:65]
	v_mfma_f32_16x16x32_bf16 v[74:77], v[190:193], v[142:145], v[74:77]
	v_mfma_f32_16x16x32_bf16 v[82:85], v[190:193], v[150:153], v[82:85]
	v_mfma_f32_16x16x32_bf16 v[90:93], v[198:201], v[142:145], v[90:93]
	v_mfma_f32_16x16x32_bf16 v[94:97], v[198:201], v[150:153], v[94:97]
	v_mfma_f32_16x16x32_bf16 v[98:101], v[154:157], v[208:211], v[98:101]
	v_mfma_f32_16x16x32_bf16 v[102:105], v[154:157], v[216:219], v[102:105]
	v_mfma_f32_16x16x32_bf16 v[106:109], v[178:181], v[208:211], v[106:109]
	v_mfma_f32_16x16x32_bf16 v[110:113], v[178:181], v[216:219], v[110:113]
	v_mfma_f32_16x16x32_bf16 v[114:117], v[186:189], v[208:211], v[114:117]
	v_mfma_f32_16x16x32_bf16 v[118:121], v[186:189], v[216:219], v[118:121]
	v_mfma_f32_16x16x32_bf16 v[122:125], v[194:197], v[208:211], v[122:125]
	v_mfma_f32_16x16x32_bf16 v[126:129], v[194:197], v[216:219], v[126:129]
	v_mfma_f32_16x16x32_bf16 v[98:101], v[158:161], v[212:215], v[98:101]
	v_mfma_f32_16x16x32_bf16 v[102:105], v[158:161], v[220:223], v[102:105]
	v_mfma_f32_16x16x32_bf16 v[106:109], v[182:185], v[212:215], v[106:109]
	v_mfma_f32_16x16x32_bf16 v[110:113], v[182:185], v[220:223], v[110:113]
	v_mfma_f32_16x16x32_bf16 v[114:117], v[190:193], v[212:215], v[114:117]
	v_mfma_f32_16x16x32_bf16 v[118:121], v[190:193], v[220:223], v[118:121]
	v_mfma_f32_16x16x32_bf16 v[122:125], v[198:201], v[212:215], v[122:125]
	v_mfma_f32_16x16x32_bf16 v[126:129], v[198:201], v[220:223], v[126:129]
	s_barrier
	s_cbranch_scc0 .LBB0_296
	s_setprio 0
	s_add_u32 s8, s8, 0x80f80
	s_addc_u32 s9, s9, 0
	v_add_u32_e32 v162, 0, v205
	v_add_u32_e32 v175, 0, v204
	s_mov_b32 m0, s93
	ds_read_b128 v[130:133], v162
	ds_read_b128 v[134:137], v162 offset:1024
	ds_read_b128 v[138:141], v162 offset:2048
	ds_read_b128 v[142:145], v162 offset:3072
	ds_read_b128 v[146:149], v175
	ds_read_b128 v[150:153], v175 offset:1024
	ds_read_b128 v[154:157], v175 offset:2048
	ds_read_b128 v[158:161], v175 offset:3072
	ds_read_b128 v[178:181], v175 offset:4096
	ds_read_b128 v[182:185], v175 offset:5120
	ds_read_b128 v[186:189], v175 offset:6144
	ds_read_b128 v[190:193], v175 offset:7168
	global_load_lds_dwordx4 v174, s[8:9]
	s_mov_b32 m0, s94
	s_nop 0
	global_load_lds_dwordx4 v176, s[8:9]
	s_waitcnt vmcnt(8)
	s_barrier
	s_waitcnt lgkmcnt(0)
	s_setprio 1
	s_waitcnt lgkmcnt(0)
	v_mfma_f32_16x16x32_bf16 v[2:5], v[146:149], v[130:133], v[2:5]
	v_mfma_f32_16x16x32_bf16 v[6:9], v[146:149], v[138:141], v[6:9]
	v_mfma_f32_16x16x32_bf16 v[10:13], v[154:157], v[130:133], v[10:13]
	v_mfma_f32_16x16x32_bf16 v[18:21], v[154:157], v[138:141], v[18:21]
	v_mfma_f32_16x16x32_bf16 v[66:69], v[186:189], v[138:141], v[66:69]
	v_mfma_f32_16x16x32_bf16 v[2:5], v[150:153], v[134:137], v[2:5]
	v_mfma_f32_16x16x32_bf16 v[6:9], v[150:153], v[142:145], v[6:9]
	v_mfma_f32_16x16x32_bf16 v[10:13], v[158:161], v[134:137], v[10:13]
	v_mfma_f32_16x16x32_bf16 v[18:21], v[158:161], v[142:145], v[18:21]
	v_mfma_f32_16x16x32_bf16 v[30:33], v[178:181], v[130:133], v[30:33]
	v_mfma_f32_16x16x32_bf16 v[42:45], v[178:181], v[138:141], v[42:45]
	v_mfma_f32_16x16x32_bf16 v[54:57], v[186:189], v[130:133], v[54:57]
	v_mfma_f32_16x16x32_bf16 v[66:69], v[190:193], v[142:145], v[66:69]
	v_mfma_f32_16x16x32_bf16 v[30:33], v[182:185], v[134:137], v[30:33]
	v_mfma_f32_16x16x32_bf16 v[42:45], v[182:185], v[142:145], v[42:45]
	v_mfma_f32_16x16x32_bf16 v[54:57], v[190:193], v[134:137], v[54:57]
	s_setprio 0
	s_barrier
	ds_read_b128 v[194:197], v162 offset:16384
	ds_read_b128 v[198:201], v162 offset:17408
	ds_read_b128 v[208:211], v162 offset:18432
	ds_read_b128 v[212:215], v162 offset:19456
	s_barrier
; #define LDA(dst, b, h)                                                                                     \
;   _Pragma("unroll") for (int m = 0; m < 4; ++m) _Pragma("unroll") for (int k = 0; k < 2; ++k) dst[m][k] = \
;       *reinterpret_cast<const bf16x8*>(shmc + aL + (((b) * 2 + (h)) * 16384 + (m * 2 + k) * 1024))
; #define LDB(dst, b, h)                                                                                     \
;   _Pragma("unroll") for (int n = 0; n < 2; ++n) _Pragma("unroll") for (int k = 0; k < 2; ++k) dst[n][k] = \
;       *reinterpret_cast<const bf16x8*>(shmc + bL + (((b) * 2 + (h)) * 16384 + (n * 2 + k) * 1024))
; #define WAIT_V(n) asm volatile("s_waitcnt vmcnt(" #n ")" ::: "memory")
; #define WAIT_L(n) asm volatile("s_waitcnt lgkmcnt(" #n ")" ::: "memory")
; #define BAR __builtin_amdgcn_s_barrier()
; template <int EPI>
; __device__ __forceinline__ void phase_gemm(const Params& p, const GemmDesc& d, char* shmc) {
;     ...
;       BAR; WAIT_L(0); MMA(0, 0, At, B0); BAR;
;       LDB(B1, 0, 1); BAR; WAIT_L(0); MMA(0, 1, At, B1); BAR;
;       LDA(At, 0, 1); WAIT_V(4); BAR; WAIT_L(0); MMA(1, 0, At, B0); MMA(1, 1, At, B1); BAR;
;     }
;     {
;       LDB(B0, 1, 0); LDA(At, 1, 0); WAIT_V(2); BAR; WAIT_L(0); MMA(0, 0, At, B0); BAR;
	s_waitcnt lgkmcnt(0)
	s_setprio 1
	s_waitcnt lgkmcnt(0)
	v_mfma_f32_16x16x32_bf16 v[14:17], v[146:149], v[194:197], v[14:17]
	v_mfma_f32_16x16x32_bf16 v[22:25], v[146:149], v[208:211], v[22:25]
	v_mfma_f32_16x16x32_bf16 v[58:61], v[178:181], v[194:197], v[58:61]
	v_mfma_f32_16x16x32_bf16 v[14:17], v[150:153], v[198:201], v[14:17]
	v_mfma_f32_16x16x32_bf16 v[22:25], v[150:153], v[212:215], v[22:25]
	v_mfma_f32_16x16x32_bf16 v[150:153], v[182:185], v[198:201], v[58:61]
	v_mfma_f32_16x16x32_bf16 v[58:61], v[178:181], v[208:211], v[70:73]
	v_mfma_f32_16x16x32_bf16 v[34:37], v[154:157], v[194:197], v[34:37]
	v_mfma_f32_16x16x32_bf16 v[46:49], v[154:157], v[208:211], v[46:49]
	v_mfma_f32_16x16x32_bf16 v[154:157], v[182:185], v[212:215], v[58:61]
	v_mfma_f32_16x16x32_bf16 v[58:61], v[186:189], v[194:197], v[78:81]
	v_mfma_f32_16x16x32_bf16 v[78:81], v[190:193], v[198:201], v[58:61]
	v_mfma_f32_16x16x32_bf16 v[58:61], v[186:189], v[208:211], v[86:89]
	v_mfma_f32_16x16x32_bf16 v[86:89], v[190:193], v[212:215], v[58:61]
	v_mfma_f32_16x16x32_bf16 v[34:37], v[158:161], v[198:201], v[34:37]
	v_mfma_f32_16x16x32_bf16 v[46:49], v[158:161], v[212:215], v[46:49]
	s_setprio 0
	s_barrier
	s_nop 2
	ds_read_b128 v[58:61], v175 offset:16384
	ds_read_b128 v[70:73], v175 offset:17408
	ds_read_b128 v[146:149], v175 offset:18432
	ds_read_b128 v[158:161], v175 offset:19456
	ds_read_b128 v[178:181], v175 offset:20480
	ds_read_b128 v[182:185], v175 offset:21504
	ds_read_b128 v[186:189], v175 offset:22528
	ds_read_b128 v[190:193], v175 offset:23552
	s_waitcnt vmcnt(4)
	s_barrier
	s_waitcnt lgkmcnt(0)
	s_setprio 1
	s_waitcnt lgkmcnt(0)
	v_mfma_f32_16x16x32_bf16 v[74:77], v[178:181], v[130:133], v[74:77]
	v_mfma_f32_16x16x32_bf16 v[216:219], v[182:185], v[134:137], v[74:77]
	v_mfma_f32_16x16x32_bf16 v[74:77], v[178:181], v[138:141], v[82:85]
	v_mfma_f32_16x16x32_bf16 v[26:29], v[58:61], v[130:133], v[26:29]
	v_mfma_f32_16x16x32_bf16 v[82:85], v[182:185], v[142:145], v[74:77]
	v_mfma_f32_16x16x32_bf16 v[74:77], v[186:189], v[130:133], v[90:93]
	v_mfma_f32_16x16x32_bf16 v[26:29], v[70:73], v[134:137], v[26:29]
	v_mfma_f32_16x16x32_bf16 v[38:41], v[58:61], v[138:141], v[38:41]
	v_mfma_f32_16x16x32_bf16 v[50:53], v[146:149], v[130:133], v[50:53]
	v_mfma_f32_16x16x32_bf16 v[62:65], v[146:149], v[138:141], v[62:65]
	v_mfma_f32_16x16x32_bf16 v[90:93], v[190:193], v[134:137], v[74:77]
	v_mfma_f32_16x16x32_bf16 v[74:77], v[186:189], v[138:141], v[94:97]
	v_mfma_f32_16x16x32_bf16 v[38:41], v[70:73], v[142:145], v[38:41]
	v_mfma_f32_16x16x32_bf16 v[50:53], v[158:161], v[134:137], v[50:53]
	v_mfma_f32_16x16x32_bf16 v[62:65], v[158:161], v[142:145], v[62:65]
	v_mfma_f32_16x16x32_bf16 v[220:223], v[190:193], v[142:145], v[74:77]
	s_setprio 0
	s_setprio 1
	v_mfma_f32_16x16x32_bf16 v[74:77], v[58:61], v[194:197], v[98:101]
	v_mfma_f32_16x16x32_bf16 v[58:61], v[58:61], v[208:211], v[102:105]
	v_mfma_f32_16x16x32_bf16 v[228:231], v[70:73], v[212:215], v[58:61]
	v_mfma_f32_16x16x32_bf16 v[58:61], v[146:149], v[194:197], v[106:109]
	v_mfma_f32_16x16x32_bf16 v[232:235], v[158:161], v[198:201], v[58:61]
	v_mfma_f32_16x16x32_bf16 v[58:61], v[146:149], v[208:211], v[110:113]
	v_mfma_f32_16x16x32_bf16 v[236:239], v[158:161], v[212:215], v[58:61]
	v_mfma_f32_16x16x32_bf16 v[58:61], v[178:181], v[194:197], v[114:117]
	v_mfma_f32_16x16x32_bf16 v[240:243], v[182:185], v[198:201], v[58:61]
	v_mfma_f32_16x16x32_bf16 v[58:61], v[178:181], v[208:211], v[118:121]
	v_mfma_f32_16x16x32_bf16 v[178:181], v[182:185], v[212:215], v[58:61]
	v_mfma_f32_16x16x32_bf16 v[58:61], v[186:189], v[194:197], v[122:125]
	v_mfma_f32_16x16x32_bf16 v[182:185], v[190:193], v[198:201], v[58:61]
	v_mfma_f32_16x16x32_bf16 v[58:61], v[186:189], v[208:211], v[126:129]
	v_mfma_f32_16x16x32_bf16 v[224:227], v[70:73], v[198:201], v[74:77]
	v_mfma_f32_16x16x32_bf16 v[186:189], v[190:193], v[212:215], v[58:61]
	s_setprio 0
	s_barrier
	ds_read_b128 v[98:101], v162 offset:32768
	ds_read_b128 v[106:109], v162 offset:33792
	ds_read_b128 v[190:193], v162 offset:34816
	ds_read_b128 v[194:197], v162 offset:35840
	ds_read_b128 v[58:61], v175 offset:32768
	ds_read_b128 v[70:73], v175 offset:33792
	ds_read_b128 v[114:117], v175 offset:34816
	ds_read_b128 v[122:125], v175 offset:35840
	ds_read_b128 v[130:133], v175 offset:36864
	ds_read_b128 v[138:141], v175 offset:37888
	ds_read_b128 v[198:201], v175 offset:38912
	ds_read_b128 v[208:211], v175 offset:39936
	s_waitcnt vmcnt(2)
	s_barrier
; #define LDA(dst, b, h)                                                                                     \
;   _Pragma("unroll") for (int m = 0; m < 4; ++m) _Pragma("unroll") for (int k = 0; k < 2; ++k) dst[m][k] = \
;       *reinterpret_cast<const bf16x8*>(shmc + aL + (((b) * 2 + (h)) * 16384 + (m * 2 + k) * 1024))
; #define LDB(dst, b, h)                                                                                     \
;   _Pragma("unroll") for (int n = 0; n < 2; ++n) _Pragma("unroll") for (int k = 0; k < 2; ++k) dst[n][k] = \
;       *reinterpret_cast<const bf16x8*>(shmc + bL + (((b) * 2 + (h)) * 16384 + (n * 2 + k) * 1024))
; #define WAIT_V(n) asm volatile("s_waitcnt vmcnt(" #n ")" ::: "memory")
; #define WAIT_L(n) asm volatile("s_waitcnt lgkmcnt(" #n ")" ::: "memory")
; #define BAR __builtin_amdgcn_s_barrier()
; template <int EPI>
; __device__ __forceinline__ void phase_gemm(const Params& p, const GemmDesc& d, char* shmc) {
;     ...
;       LDB(B0, 1, 0); LDA(At, 1, 0); WAIT_V(2); BAR; WAIT_L(0); MMA(0, 0, At, B0); BAR;
;       LDB(B1, 1, 1); WAIT_V(0); BAR; WAIT_L(0); MMA(0, 1, At, B1); BAR;
;       LDA(At, 1, 1); BAR; WAIT_L(0); MMA(1, 0, At, B0); MMA(1, 1, At, B1); BAR;
;     }
;     if (wr == 0) BAR;
	s_waitcnt lgkmcnt(0)
	s_setprio 1
	s_waitcnt lgkmcnt(0)
	v_mfma_f32_16x16x32_bf16 v[2:5], v[58:61], v[98:101], v[2:5]
	v_mfma_f32_16x16x32_bf16 v[158:161], v[70:73], v[106:109], v[2:5]
	v_mfma_f32_16x16x32_bf16 v[2:5], v[58:61], v[190:193], v[6:9]
	v_mfma_f32_16x16x32_bf16 v[146:149], v[70:73], v[194:197], v[2:5]
	v_mfma_f32_16x16x32_bf16 v[2:5], v[114:117], v[98:101], v[10:13]
	v_mfma_f32_16x16x32_bf16 v[142:145], v[122:125], v[106:109], v[2:5]
	v_mfma_f32_16x16x32_bf16 v[2:5], v[114:117], v[190:193], v[18:21]
	v_mfma_f32_16x16x32_bf16 v[134:137], v[122:125], v[194:197], v[2:5]
	v_mfma_f32_16x16x32_bf16 v[2:5], v[130:133], v[98:101], v[30:33]
	v_mfma_f32_16x16x32_bf16 v[126:129], v[138:141], v[106:109], v[2:5]
	v_mfma_f32_16x16x32_bf16 v[2:5], v[130:133], v[190:193], v[42:45]
	v_mfma_f32_16x16x32_bf16 v[118:121], v[138:141], v[194:197], v[2:5]
	v_mfma_f32_16x16x32_bf16 v[2:5], v[198:201], v[98:101], v[54:57]
	v_mfma_f32_16x16x32_bf16 v[110:113], v[208:211], v[106:109], v[2:5]
	v_mfma_f32_16x16x32_bf16 v[2:5], v[198:201], v[190:193], v[66:69]
	v_mfma_f32_16x16x32_bf16 v[102:105], v[208:211], v[194:197], v[2:5]
	s_setprio 0
	s_barrier
	ds_read_b128 v[30:33], v162 offset:49152
	ds_read_b128 v[42:45], v162 offset:50176
	ds_read_b128 v[54:57], v162 offset:51200
	ds_read_b128 v[212:215], v162 offset:52224
	s_waitcnt vmcnt(0)
	s_barrier
	s_waitcnt lgkmcnt(0)
	s_setprio 1
	s_waitcnt lgkmcnt(0)
	v_mfma_f32_16x16x32_bf16 v[2:5], v[58:61], v[30:33], v[14:17]
	v_mfma_f32_16x16x32_bf16 v[94:97], v[70:73], v[42:45], v[2:5]
	v_mfma_f32_16x16x32_bf16 v[2:5], v[58:61], v[54:57], v[22:25]
	v_mfma_f32_16x16x32_bf16 v[58:61], v[70:73], v[212:215], v[2:5]
	v_mfma_f32_16x16x32_bf16 v[2:5], v[114:117], v[30:33], v[34:37]
	v_mfma_f32_16x16x32_bf16 v[74:77], v[122:125], v[42:45], v[2:5]
	v_mfma_f32_16x16x32_bf16 v[2:5], v[114:117], v[54:57], v[46:49]
	v_mfma_f32_16x16x32_bf16 v[10:13], v[122:125], v[212:215], v[2:5]
	v_mfma_f32_16x16x32_bf16 v[2:5], v[130:133], v[30:33], v[150:153]
	v_mfma_f32_16x16x32_bf16 v[70:73], v[138:141], v[42:45], v[2:5]
	v_mfma_f32_16x16x32_bf16 v[2:5], v[130:133], v[54:57], v[154:157]
	v_mfma_f32_16x16x32_bf16 v[6:9], v[138:141], v[212:215], v[2:5]
	v_mfma_f32_16x16x32_bf16 v[2:5], v[198:201], v[30:33], v[78:81]
	v_mfma_f32_16x16x32_bf16 v[66:69], v[208:211], v[42:45], v[2:5]
	v_mfma_f32_16x16x32_bf16 v[2:5], v[198:201], v[54:57], v[86:89]
	v_mfma_f32_16x16x32_bf16 v[2:5], v[208:211], v[212:215], v[2:5]
	s_setprio 0
	s_barrier
	ds_read_b128 v[14:17], v175 offset:49152
	ds_read_b128 v[18:21], v175 offset:50176
	ds_read_b128 v[22:25], v175 offset:51200
	ds_read_b128 v[34:37], v175 offset:52224
	ds_read_b128 v[46:49], v175 offset:53248
	ds_read_b128 v[78:81], v175 offset:54272
	ds_read_b128 v[198:201], v175 offset:55296
	ds_read_b128 v[208:211], v175 offset:56320
	s_barrier
	s_waitcnt lgkmcnt(0)
	s_setprio 1
	s_waitcnt lgkmcnt(0)
	v_mfma_f32_16x16x32_bf16 v[26:29], v[14:17], v[98:101], v[26:29]
	v_mfma_f32_16x16x32_bf16 v[154:157], v[18:21], v[106:109], v[26:29]
	v_mfma_f32_16x16x32_bf16 v[26:29], v[14:17], v[190:193], v[38:41]
	v_mfma_f32_16x16x32_bf16 v[150:153], v[18:21], v[194:197], v[26:29]
	v_mfma_f32_16x16x32_bf16 v[26:29], v[22:25], v[98:101], v[50:53]
	v_mfma_f32_16x16x32_bf16 v[138:141], v[34:37], v[106:109], v[26:29]
	v_mfma_f32_16x16x32_bf16 v[26:29], v[22:25], v[190:193], v[62:65]
	v_mfma_f32_16x16x32_bf16 v[130:133], v[34:37], v[194:197], v[26:29]
	v_mfma_f32_16x16x32_bf16 v[26:29], v[46:49], v[98:101], v[216:219]
	v_mfma_f32_16x16x32_bf16 v[122:125], v[78:81], v[106:109], v[26:29]
	v_mfma_f32_16x16x32_bf16 v[26:29], v[46:49], v[190:193], v[82:85]
	v_mfma_f32_16x16x32_bf16 v[114:117], v[78:81], v[194:197], v[26:29]
	v_mfma_f32_16x16x32_bf16 v[26:29], v[198:201], v[98:101], v[90:93]
	v_mfma_f32_16x16x32_bf16 v[106:109], v[208:211], v[106:109], v[26:29]
	v_mfma_f32_16x16x32_bf16 v[26:29], v[198:201], v[190:193], v[220:223]
	v_mfma_f32_16x16x32_bf16 v[98:101], v[208:211], v[194:197], v[26:29]
	s_setprio 0
	s_setprio 1
	v_mfma_f32_16x16x32_bf16 v[26:29], v[14:17], v[30:33], v[224:227]
	v_mfma_f32_16x16x32_bf16 v[14:17], v[14:17], v[54:57], v[228:231]
	v_mfma_f32_16x16x32_bf16 v[90:93], v[18:21], v[42:45], v[26:29]
	v_mfma_f32_16x16x32_bf16 v[26:29], v[18:21], v[212:215], v[14:17]
	v_mfma_f32_16x16x32_bf16 v[14:17], v[22:25], v[30:33], v[232:235]
	v_mfma_f32_16x16x32_bf16 v[86:89], v[34:37], v[42:45], v[14:17]
	v_mfma_f32_16x16x32_bf16 v[14:17], v[22:25], v[54:57], v[236:239]
	v_mfma_f32_16x16x32_bf16 v[22:25], v[34:37], v[212:215], v[14:17]
	v_mfma_f32_16x16x32_bf16 v[14:17], v[46:49], v[30:33], v[240:243]
	v_mfma_f32_16x16x32_bf16 v[82:85], v[78:81], v[42:45], v[14:17]
	v_mfma_f32_16x16x32_bf16 v[14:17], v[46:49], v[54:57], v[178:181]
	v_mfma_f32_16x16x32_bf16 v[18:21], v[78:81], v[212:215], v[14:17]
	v_mfma_f32_16x16x32_bf16 v[14:17], v[198:201], v[30:33], v[182:185]
	v_mfma_f32_16x16x32_bf16 v[78:81], v[208:211], v[42:45], v[14:17]
	v_mfma_f32_16x16x32_bf16 v[14:17], v[198:201], v[54:57], v[186:189]
	v_mfma_f32_16x16x32_bf16 v[14:17], v[208:211], v[212:215], v[14:17]
	s_setprio 0
	s_barrier
	s_and_saveexec_b64 s[8:9], s[6:7]
	s_cbranch_execz .LBB0_299
	s_barrier

; #define LDA(dst, b, h)                                                                                     \
;   _Pragma("unroll") for (int m = 0; m < 4; ++m) _Pragma("unroll") for (int k = 0; k < 2; ++k) dst[m][k] = \
;       *reinterpret_cast<const bf16x8*>(shmc + aL + (((b) * 2 + (h)) * 16384 + (m * 2 + k) * 1024))
; #define LDB(dst, b, h)                                                                                     \
;   _Pragma("unroll") for (int n = 0; n < 2; ++n) _Pragma("unroll") for (int k = 0; k < 2; ++k) dst[n][k] = \
;       *reinterpret_cast<const bf16x8*>(shmc + bL + (((b) * 2 + (h)) * 16384 + (n * 2 + k) * 1024))
; #define OPAQ asm volatile("" : "+v"(aL), "+v"(bL))
; #define WAIT_V(n) asm volatile("s_waitcnt vmcnt(" #n ")" ::: "memory")
; #define WAIT_L(n) asm volatile("s_waitcnt lgkmcnt(" #n ")" ::: "memory")
; #define BAR __builtin_amdgcn_s_barrier()
; #define SCHED __builtin_amdgcn_sched_barrier(0)
; template <int EPI>
; __device__ __forceinline__ void phase_gemm(const Params& p, const GemmDesc& d, char* shmc) {
;     ...
;     for (int t = 0; t < nt - 2; t += 2) {
;       OPAQ;
;       LDB(B0, 0, 0); SCHED; LDA(At, 0, 0); STAGE_A(SA(1, 1), 1, t + 1);
;       WAIT_L(8); BAR; WAIT_L(0); MMA(0, 0, At, B0); BAR; SCHED;
;       LDB(B1, 0, 1); STAGE_B(SB(0, 0), 0, t + 2);
;       BAR; WAIT_L(0); MMA(0, 1, At, B1); BAR;
;       LDA(At, 0, 1); STAGE_A(SA(0, 0), 0, t + 2);
;       BAR; WAIT_L(0); MMA(1, 0, At, B0); BAR; SCHED;
;       STAGE_B(SB(0, 1), 1, t + 2);
;       WAIT_V(6); BAR; MMA(1, 1, At, B1); BAR;
;       LDB(B0, 1, 0); SCHED; LDA(At, 1, 0); STAGE_A(SA(0, 1), 1, t + 2);
;       WAIT_L(8); BAR; WAIT_L(0); MMA(0, 0, At, B0); BAR; SCHED;
;       LDB(B1, 1, 1); STAGE_B(SB(1, 0), 0, t + 3);
;       BAR; WAIT_L(0); MMA(0, 1, At, B1); BAR;
;       LDA(At, 1, 1); STAGE_A(SA(1, 0), 0, t + 3);
;       BAR; WAIT_L(0); MMA(1, 0, At, B0); BAR; SCHED;
;       STAGE_B(SB(1, 1), 1, t + 3);
;       WAIT_V(6); BAR; MMA(1, 1, At, B1); BAR;
;     }
.LBB0_455:
	s_nop 0
	v_add_u32_e32 v130, 0, v153
	v_add_u32_e32 v141, 0, v152
	s_setprio 0
	ds_read_b128 v[156:159], v130
	ds_read_b128 v[160:163], v130 offset:1024
	ds_read_b128 v[164:167], v130 offset:2048
	ds_read_b128 v[168:171], v130 offset:3072
	ds_read_b128 v[204:207], v130 offset:16384
	ds_read_b128 v[208:211], v130 offset:17408
	ds_read_b128 v[212:215], v130 offset:18432
	ds_read_b128 v[216:219], v130 offset:19456
	v_lshl_add_u64 v[220:221], v[148:149], 0, s[52:53]
	v_lshl_add_u64 v[222:223], v[150:151], 0, s[52:53]
	v_lshl_add_u64 v[224:225], v[144:145], 0, s[52:53]
	v_lshl_add_u64 v[226:227], v[146:147], 0, s[52:53]
	ds_read_b128 v[172:175], v141
	ds_read_b128 v[176:179], v141 offset:1024
	ds_read_b128 v[180:183], v141 offset:2048
	ds_read_b128 v[184:187], v141 offset:3072
	ds_read_b128 v[188:191], v141 offset:4096
	ds_read_b128 v[192:195], v141 offset:5120
	ds_read_b128 v[196:199], v141 offset:6144
	ds_read_b128 v[200:203], v141 offset:7168
	s_mov_b32 m0, s70
	v_lshl_add_u64 v[228:229], v[220:221], 0, s[10:11]
	global_load_lds_dwordx4 v[228:229], off
	v_lshl_add_u64 v[228:229], v[222:223], 0, s[10:11]
	s_mov_b32 m0, s71
	s_nop 0
	global_load_lds_dwordx4 v[228:229], off
	s_waitcnt vmcnt(8)
	s_waitcnt lgkmcnt(0)
	s_setprio 1
	s_barrier
	v_mfma_f32_16x16x32_bf16 v[126:129], v[156:159], v[172:175], v[126:129]
	v_mfma_f32_16x16x32_bf16 v[122:125], v[164:167], v[172:175], v[122:125]
	v_mfma_f32_16x16x32_bf16 v[118:121], v[156:159], v[180:183], v[118:121]
	v_mfma_f32_16x16x32_bf16 v[114:117], v[164:167], v[180:183], v[114:117]
	v_mfma_f32_16x16x32_bf16 v[110:113], v[156:159], v[188:191], v[110:113]
	v_mfma_f32_16x16x32_bf16 v[106:109], v[164:167], v[188:191], v[106:109]
	v_mfma_f32_16x16x32_bf16 v[102:105], v[156:159], v[196:199], v[102:105]
	v_mfma_f32_16x16x32_bf16 v[98:101], v[164:167], v[196:199], v[98:101]
	v_mfma_f32_16x16x32_bf16 v[126:129], v[160:163], v[176:179], v[126:129]
	v_mfma_f32_16x16x32_bf16 v[122:125], v[168:171], v[176:179], v[122:125]
	v_mfma_f32_16x16x32_bf16 v[118:121], v[160:163], v[184:187], v[118:121]
	v_mfma_f32_16x16x32_bf16 v[114:117], v[168:171], v[184:187], v[114:117]
	v_mfma_f32_16x16x32_bf16 v[110:113], v[160:163], v[192:195], v[110:113]
	v_mfma_f32_16x16x32_bf16 v[106:109], v[168:171], v[192:195], v[106:109]
	v_mfma_f32_16x16x32_bf16 v[102:105], v[160:163], v[200:203], v[102:105]
	v_mfma_f32_16x16x32_bf16 v[98:101], v[168:171], v[200:203], v[98:101]
	v_mfma_f32_16x16x32_bf16 v[86:89], v[204:207], v[172:175], v[86:89]
	v_mfma_f32_16x16x32_bf16 v[70:73], v[212:215], v[172:175], v[70:73]
	v_mfma_f32_16x16x32_bf16 v[54:57], v[204:207], v[180:183], v[54:57]
	v_mfma_f32_16x16x32_bf16 v[50:53], v[212:215], v[180:183], v[50:53]
	v_mfma_f32_16x16x32_bf16 v[46:49], v[204:207], v[188:191], v[46:49]
	v_mfma_f32_16x16x32_bf16 v[42:45], v[212:215], v[188:191], v[42:45]
	v_mfma_f32_16x16x32_bf16 v[38:41], v[204:207], v[196:199], v[38:41]
	v_mfma_f32_16x16x32_bf16 v[34:37], v[212:215], v[196:199], v[34:37]
	v_mfma_f32_16x16x32_bf16 v[86:89], v[208:211], v[176:179], v[86:89]
	v_mfma_f32_16x16x32_bf16 v[70:73], v[216:219], v[176:179], v[70:73]
	v_mfma_f32_16x16x32_bf16 v[54:57], v[208:211], v[184:187], v[54:57]
	v_mfma_f32_16x16x32_bf16 v[50:53], v[216:219], v[184:187], v[50:53]
	v_mfma_f32_16x16x32_bf16 v[46:49], v[208:211], v[192:195], v[46:49]
	v_mfma_f32_16x16x32_bf16 v[42:45], v[216:219], v[192:195], v[42:45]
	v_mfma_f32_16x16x32_bf16 v[38:41], v[208:211], v[200:203], v[38:41]
	v_mfma_f32_16x16x32_bf16 v[34:37], v[216:219], v[200:203], v[34:37]
	s_barrier
	s_setprio 0
	ds_read_b128 v[172:175], v141 offset:16384
	ds_read_b128 v[176:179], v141 offset:17408
	ds_read_b128 v[180:183], v141 offset:18432
	ds_read_b128 v[184:187], v141 offset:19456
	ds_read_b128 v[188:191], v141 offset:20480
	ds_read_b128 v[192:195], v141 offset:21504
	ds_read_b128 v[196:199], v141 offset:22528
	ds_read_b128 v[200:203], v141 offset:23552
	s_mov_b32 m0, s33
	v_lshl_add_u64 v[228:229], v[224:225], 0, s[26:27]
	global_load_lds_dwordx4 v[228:229], off
	v_lshl_add_u64 v[228:229], v[226:227], 0, s[26:27]
	s_mov_b32 m0, s34
	s_nop 0
	global_load_lds_dwordx4 v[228:229], off
	s_mov_b32 m0, s14
	v_lshl_add_u64 v[228:229], v[220:221], 0, s[26:27]
	global_load_lds_dwordx4 v[228:229], off
	v_lshl_add_u64 v[228:229], v[222:223], 0, s[26:27]
	s_mov_b32 m0, s35
	s_nop 0
	global_load_lds_dwordx4 v[228:229], off
	s_mov_b32 m0, s58
	v_lshl_add_u64 v[228:229], v[224:225], 0, s[38:39]
	global_load_lds_dwordx4 v[228:229], off
	v_lshl_add_u64 v[228:229], v[226:227], 0, s[38:39]
	s_mov_b32 m0, s59
	s_nop 0
	global_load_lds_dwordx4 v[228:229], off
	s_waitcnt vmcnt(8)
	s_waitcnt lgkmcnt(0)
	s_setprio 1
	s_barrier
; #define LDA(dst, b, h)                                                                                     \
;   _Pragma("unroll") for (int m = 0; m < 4; ++m) _Pragma("unroll") for (int k = 0; k < 2; ++k) dst[m][k] = \
;       *reinterpret_cast<const bf16x8*>(shmc + aL + (((b) * 2 + (h)) * 16384 + (m * 2 + k) * 1024))
; #define LDB(dst, b, h)                                                                                     \
;   _Pragma("unroll") for (int n = 0; n < 2; ++n) _Pragma("unroll") for (int k = 0; k < 2; ++k) dst[n][k] = \
;       *reinterpret_cast<const bf16x8*>(shmc + bL + (((b) * 2 + (h)) * 16384 + (n * 2 + k) * 1024))
; #define OPAQ asm volatile("" : "+v"(aL), "+v"(bL))
; #define WAIT_V(n) asm volatile("s_waitcnt vmcnt(" #n ")" ::: "memory")
; #define WAIT_L(n) asm volatile("s_waitcnt lgkmcnt(" #n ")" ::: "memory")
; #define BAR __builtin_amdgcn_s_barrier()
; #define SCHED __builtin_amdgcn_sched_barrier(0)
; template <int EPI>
; __device__ __forceinline__ void phase_gemm(const Params& p, const GemmDesc& d, char* shmc) {
;     ...
;     for (int t = 0; t < nt - 2; t += 2) {
;       OPAQ;
;       LDB(B0, 0, 0); SCHED; LDA(At, 0, 0); STAGE_A(SA(1, 1), 1, t + 1);
;       WAIT_L(8); BAR; WAIT_L(0); MMA(0, 0, At, B0); BAR; SCHED;
;       LDB(B1, 0, 1); STAGE_B(SB(0, 0), 0, t + 2);
;       BAR; WAIT_L(0); MMA(0, 1, At, B1); BAR;
;       LDA(At, 0, 1); STAGE_A(SA(0, 0), 0, t + 2);
;       BAR; WAIT_L(0); MMA(1, 0, At, B0); BAR; SCHED;
;       STAGE_B(SB(0, 1), 1, t + 2);
;       WAIT_V(6); BAR; MMA(1, 1, At, B1); BAR;
;       LDB(B0, 1, 0); SCHED; LDA(At, 1, 0); STAGE_A(SA(0, 1), 1, t + 2);
;       WAIT_L(8); BAR; WAIT_L(0); MMA(0, 0, At, B0); BAR; SCHED;
;       LDB(B1, 1, 1); STAGE_B(SB(1, 0), 0, t + 3);
;       BAR; WAIT_L(0); MMA(0, 1, At, B1); BAR;
;       LDA(At, 1, 1); STAGE_A(SA(1, 0), 0, t + 3);
;       BAR; WAIT_L(0); MMA(1, 0, At, B0); BAR; SCHED;
;       STAGE_B(SB(1, 1), 1, t + 3);
;       WAIT_V(6); BAR; MMA(1, 1, At, B1); BAR;
;     }
	v_mfma_f32_16x16x32_bf16 v[30:33], v[156:159], v[172:175], v[30:33]
	v_mfma_f32_16x16x32_bf16 v[26:29], v[164:167], v[172:175], v[26:29]
	v_mfma_f32_16x16x32_bf16 v[22:25], v[156:159], v[180:183], v[22:25]
	v_mfma_f32_16x16x32_bf16 v[18:21], v[164:167], v[180:183], v[18:21]
	v_mfma_f32_16x16x32_bf16 v[14:17], v[156:159], v[188:191], v[14:17]
	v_mfma_f32_16x16x32_bf16 v[10:13], v[164:167], v[188:191], v[10:13]
	v_mfma_f32_16x16x32_bf16 v[6:9], v[156:159], v[196:199], v[6:9]
	v_mfma_f32_16x16x32_bf16 v[2:5], v[164:167], v[196:199], v[2:5]
	v_mfma_f32_16x16x32_bf16 v[30:33], v[160:163], v[176:179], v[30:33]
	v_mfma_f32_16x16x32_bf16 v[26:29], v[168:171], v[176:179], v[26:29]
	v_mfma_f32_16x16x32_bf16 v[22:25], v[160:163], v[184:187], v[22:25]
	v_mfma_f32_16x16x32_bf16 v[18:21], v[168:171], v[184:187], v[18:21]
	v_mfma_f32_16x16x32_bf16 v[14:17], v[160:163], v[192:195], v[14:17]
	v_mfma_f32_16x16x32_bf16 v[10:13], v[168:171], v[192:195], v[10:13]
	v_mfma_f32_16x16x32_bf16 v[6:9], v[160:163], v[200:203], v[6:9]
	v_mfma_f32_16x16x32_bf16 v[2:5], v[168:171], v[200:203], v[2:5]
	v_mfma_f32_16x16x32_bf16 v[58:61], v[204:207], v[172:175], v[58:61]
	v_mfma_f32_16x16x32_bf16 v[62:65], v[212:215], v[172:175], v[62:65]
	v_mfma_f32_16x16x32_bf16 v[66:69], v[204:207], v[180:183], v[66:69]
	v_mfma_f32_16x16x32_bf16 v[74:77], v[212:215], v[180:183], v[74:77]
	v_mfma_f32_16x16x32_bf16 v[78:81], v[204:207], v[188:191], v[78:81]
	v_mfma_f32_16x16x32_bf16 v[82:85], v[212:215], v[188:191], v[82:85]
	v_mfma_f32_16x16x32_bf16 v[90:93], v[204:207], v[196:199], v[90:93]
	v_mfma_f32_16x16x32_bf16 v[94:97], v[212:215], v[196:199], v[94:97]
	v_mfma_f32_16x16x32_bf16 v[58:61], v[208:211], v[176:179], v[58:61]
	v_mfma_f32_16x16x32_bf16 v[62:65], v[216:219], v[176:179], v[62:65]
	v_mfma_f32_16x16x32_bf16 v[66:69], v[208:211], v[184:187], v[66:69]
	v_mfma_f32_16x16x32_bf16 v[74:77], v[216:219], v[184:187], v[74:77]
	v_mfma_f32_16x16x32_bf16 v[78:81], v[208:211], v[192:195], v[78:81]
	v_mfma_f32_16x16x32_bf16 v[82:85], v[216:219], v[192:195], v[82:85]
	v_mfma_f32_16x16x32_bf16 v[90:93], v[208:211], v[200:203], v[90:93]
	v_mfma_f32_16x16x32_bf16 v[94:97], v[216:219], v[200:203], v[94:97]
	s_barrier
	s_setprio 0
	ds_read_b128 v[156:159], v130 offset:32768
	ds_read_b128 v[160:163], v130 offset:33792
	ds_read_b128 v[164:167], v130 offset:34816
	ds_read_b128 v[168:171], v130 offset:35840
	ds_read_b128 v[204:207], v130 offset:49152
	ds_read_b128 v[208:211], v130 offset:50176
	ds_read_b128 v[212:215], v130 offset:51200
	ds_read_b128 v[216:219], v130 offset:52224
	ds_read_b128 v[172:175], v141 offset:32768
	ds_read_b128 v[176:179], v141 offset:33792
	ds_read_b128 v[180:183], v141 offset:34816
	ds_read_b128 v[184:187], v141 offset:35840
	ds_read_b128 v[188:191], v141 offset:36864
	ds_read_b128 v[192:195], v141 offset:37888
	ds_read_b128 v[196:199], v141 offset:38912
	ds_read_b128 v[200:203], v141 offset:39936
	s_mov_b32 m0, s60
	v_lshl_add_u64 v[228:229], v[220:221], 0, s[38:39]
	global_load_lds_dwordx4 v[228:229], off
	v_lshl_add_u64 v[228:229], v[222:223], 0, s[38:39]
	s_mov_b32 m0, s61
	s_nop 0
	global_load_lds_dwordx4 v[228:229], off
	s_waitcnt vmcnt(8)
	s_waitcnt lgkmcnt(0)
	s_setprio 1
	s_barrier
	v_mfma_f32_16x16x32_bf16 v[126:129], v[156:159], v[172:175], v[126:129]
	v_mfma_f32_16x16x32_bf16 v[122:125], v[164:167], v[172:175], v[122:125]
	v_mfma_f32_16x16x32_bf16 v[118:121], v[156:159], v[180:183], v[118:121]
	v_mfma_f32_16x16x32_bf16 v[114:117], v[164:167], v[180:183], v[114:117]
	v_mfma_f32_16x16x32_bf16 v[110:113], v[156:159], v[188:191], v[110:113]
	v_mfma_f32_16x16x32_bf16 v[106:109], v[164:167], v[188:191], v[106:109]
	v_mfma_f32_16x16x32_bf16 v[102:105], v[156:159], v[196:199], v[102:105]
	v_mfma_f32_16x16x32_bf16 v[98:101], v[164:167], v[196:199], v[98:101]
	v_mfma_f32_16x16x32_bf16 v[126:129], v[160:163], v[176:179], v[126:129]
	v_mfma_f32_16x16x32_bf16 v[122:125], v[168:171], v[176:179], v[122:125]
	v_mfma_f32_16x16x32_bf16 v[118:121], v[160:163], v[184:187], v[118:121]
	v_mfma_f32_16x16x32_bf16 v[114:117], v[168:171], v[184:187], v[114:117]
	v_mfma_f32_16x16x32_bf16 v[110:113], v[160:163], v[192:195], v[110:113]
	v_mfma_f32_16x16x32_bf16 v[106:109], v[168:171], v[192:195], v[106:109]
	v_mfma_f32_16x16x32_bf16 v[102:105], v[160:163], v[200:203], v[102:105]
	v_mfma_f32_16x16x32_bf16 v[98:101], v[168:171], v[200:203], v[98:101]
	v_mfma_f32_16x16x32_bf16 v[86:89], v[204:207], v[172:175], v[86:89]
	v_mfma_f32_16x16x32_bf16 v[70:73], v[212:215], v[172:175], v[70:73]
	v_mfma_f32_16x16x32_bf16 v[54:57], v[204:207], v[180:183], v[54:57]
	v_mfma_f32_16x16x32_bf16 v[50:53], v[212:215], v[180:183], v[50:53]
	v_mfma_f32_16x16x32_bf16 v[46:49], v[204:207], v[188:191], v[46:49]
	v_mfma_f32_16x16x32_bf16 v[42:45], v[212:215], v[188:191], v[42:45]
	v_mfma_f32_16x16x32_bf16 v[38:41], v[204:207], v[196:199], v[38:41]
	v_mfma_f32_16x16x32_bf16 v[34:37], v[212:215], v[196:199], v[34:37]
	v_mfma_f32_16x16x32_bf16 v[86:89], v[208:211], v[176:179], v[86:89]
	v_mfma_f32_16x16x32_bf16 v[70:73], v[216:219], v[176:179], v[70:73]
	v_mfma_f32_16x16x32_bf16 v[54:57], v[208:211], v[184:187], v[54:57]
	v_mfma_f32_16x16x32_bf16 v[50:53], v[216:219], v[184:187], v[50:53]
	v_mfma_f32_16x16x32_bf16 v[46:49], v[208:211], v[192:195], v[46:49]
	v_mfma_f32_16x16x32_bf16 v[42:45], v[216:219], v[192:195], v[42:45]
	v_mfma_f32_16x16x32_bf16 v[38:41], v[208:211], v[200:203], v[38:41]
	v_mfma_f32_16x16x32_bf16 v[34:37], v[216:219], v[200:203], v[34:37]
	s_barrier
; #define LDA(dst, b, h)                                                                                     \
;   _Pragma("unroll") for (int m = 0; m < 4; ++m) _Pragma("unroll") for (int k = 0; k < 2; ++k) dst[m][k] = \
;       *reinterpret_cast<const bf16x8*>(shmc + aL + (((b) * 2 + (h)) * 16384 + (m * 2 + k) * 1024))
; #define LDB(dst, b, h)                                                                                     \
;   _Pragma("unroll") for (int n = 0; n < 2; ++n) _Pragma("unroll") for (int k = 0; k < 2; ++k) dst[n][k] = \
;       *reinterpret_cast<const bf16x8*>(shmc + bL + (((b) * 2 + (h)) * 16384 + (n * 2 + k) * 1024))
; #define OPAQ asm volatile("" : "+v"(aL), "+v"(bL))
; #define WAIT_V(n) asm volatile("s_waitcnt vmcnt(" #n ")" ::: "memory")
; #define WAIT_L(n) asm volatile("s_waitcnt lgkmcnt(" #n ")" ::: "memory")
; #define BAR __builtin_amdgcn_s_barrier()
; #define SCHED __builtin_amdgcn_sched_barrier(0)
; template <int EPI>
; __device__ __forceinline__ void phase_gemm(const Params& p, const GemmDesc& d, char* shmc) {
;     ...
;     for (int t = 0; t < nt - 2; t += 2) {
;       OPAQ;
;       LDB(B0, 0, 0); SCHED; LDA(At, 0, 0); STAGE_A(SA(1, 1), 1, t + 1);
;       WAIT_L(8); BAR; WAIT_L(0); MMA(0, 0, At, B0); BAR; SCHED;
;       LDB(B1, 0, 1); STAGE_B(SB(0, 0), 0, t + 2);
;       BAR; WAIT_L(0); MMA(0, 1, At, B1); BAR;
;       LDA(At, 0, 1); STAGE_A(SA(0, 0), 0, t + 2);
;       BAR; WAIT_L(0); MMA(1, 0, At, B0); BAR; SCHED;
;       STAGE_B(SB(0, 1), 1, t + 2);
;       WAIT_V(6); BAR; MMA(1, 1, At, B1); BAR;
;       LDB(B0, 1, 0); SCHED; LDA(At, 1, 0); STAGE_A(SA(0, 1), 1, t + 2);
;       WAIT_L(8); BAR; WAIT_L(0); MMA(0, 0, At, B0); BAR; SCHED;
;       LDB(B1, 1, 1); STAGE_B(SB(1, 0), 0, t + 3);
;       BAR; WAIT_L(0); MMA(0, 1, At, B1); BAR;
;       LDA(At, 1, 1); STAGE_A(SA(1, 0), 0, t + 3);
;       BAR; WAIT_L(0); MMA(1, 0, At, B0); BAR; SCHED;
;       STAGE_B(SB(1, 1), 1, t + 3);
;       WAIT_V(6); BAR; MMA(1, 1, At, B1); BAR;
;     }
;     {
;       OPAQ;
;       LDB(B0, 0, 0); LDA(At, 0, 0); STAGE_A(SA(1, 1), 1, nt - 1);
;       BAR; WAIT_L(0); MMA(0, 0, At, B0); BAR;
;       LDB(B1, 0, 1); BAR; WAIT_L(0); MMA(0, 1, At, B1); BAR;
;       LDA(At, 0, 1); WAIT_V(4); BAR; WAIT_L(0); MMA(1, 0, At, B0); MMA(1, 1, At, B1); BAR;
	s_setprio 0
	ds_read_b128 v[172:175], v141 offset:49152
	ds_read_b128 v[176:179], v141 offset:50176
	ds_read_b128 v[180:183], v141 offset:51200
	ds_read_b128 v[184:187], v141 offset:52224
	ds_read_b128 v[188:191], v141 offset:53248
	ds_read_b128 v[192:195], v141 offset:54272
	ds_read_b128 v[196:199], v141 offset:55296
	ds_read_b128 v[200:203], v141 offset:56320
	s_mov_b32 m0, s62
	v_lshl_add_u64 v[228:229], v[224:225], 0, s[40:41]
	global_load_lds_dwordx4 v[228:229], off
	v_lshl_add_u64 v[228:229], v[226:227], 0, s[40:41]
	s_mov_b32 m0, s63
	s_nop 0
	global_load_lds_dwordx4 v[228:229], off
	s_mov_b32 m0, s64
	v_lshl_add_u64 v[228:229], v[220:221], 0, s[40:41]
	global_load_lds_dwordx4 v[228:229], off
	v_lshl_add_u64 v[228:229], v[222:223], 0, s[40:41]
	s_mov_b32 m0, s65
	s_nop 0
	global_load_lds_dwordx4 v[228:229], off
	s_mov_b32 m0, s68
	v_lshl_add_u64 v[228:229], v[224:225], 0, s[42:43]
	global_load_lds_dwordx4 v[228:229], off
	v_lshl_add_u64 v[228:229], v[226:227], 0, s[42:43]
	s_mov_b32 m0, s69
	s_nop 0
	global_load_lds_dwordx4 v[228:229], off
	s_add_i32 s54, s54, 2
	s_add_u32 s52, s52, 0x100
	s_addc_u32 s53, s53, 0
	s_cmpk_gt_u32 s54, 0x53
	s_waitcnt vmcnt(8)
	s_waitcnt lgkmcnt(0)
	s_setprio 1
	s_barrier
	v_mfma_f32_16x16x32_bf16 v[30:33], v[156:159], v[172:175], v[30:33]
	v_mfma_f32_16x16x32_bf16 v[26:29], v[164:167], v[172:175], v[26:29]
	v_mfma_f32_16x16x32_bf16 v[22:25], v[156:159], v[180:183], v[22:25]
	v_mfma_f32_16x16x32_bf16 v[18:21], v[164:167], v[180:183], v[18:21]
	v_mfma_f32_16x16x32_bf16 v[14:17], v[156:159], v[188:191], v[14:17]
	v_mfma_f32_16x16x32_bf16 v[10:13], v[164:167], v[188:191], v[10:13]
	v_mfma_f32_16x16x32_bf16 v[6:9], v[156:159], v[196:199], v[6:9]
	v_mfma_f32_16x16x32_bf16 v[2:5], v[164:167], v[196:199], v[2:5]
	v_mfma_f32_16x16x32_bf16 v[30:33], v[160:163], v[176:179], v[30:33]
	v_mfma_f32_16x16x32_bf16 v[26:29], v[168:171], v[176:179], v[26:29]
	v_mfma_f32_16x16x32_bf16 v[22:25], v[160:163], v[184:187], v[22:25]
	v_mfma_f32_16x16x32_bf16 v[18:21], v[168:171], v[184:187], v[18:21]
	v_mfma_f32_16x16x32_bf16 v[14:17], v[160:163], v[192:195], v[14:17]
	v_mfma_f32_16x16x32_bf16 v[10:13], v[168:171], v[192:195], v[10:13]
	v_mfma_f32_16x16x32_bf16 v[6:9], v[160:163], v[200:203], v[6:9]
	v_mfma_f32_16x16x32_bf16 v[2:5], v[168:171], v[200:203], v[2:5]
	v_mfma_f32_16x16x32_bf16 v[58:61], v[204:207], v[172:175], v[58:61]
	v_mfma_f32_16x16x32_bf16 v[62:65], v[212:215], v[172:175], v[62:65]
	v_mfma_f32_16x16x32_bf16 v[66:69], v[204:207], v[180:183], v[66:69]
	v_mfma_f32_16x16x32_bf16 v[74:77], v[212:215], v[180:183], v[74:77]
	v_mfma_f32_16x16x32_bf16 v[78:81], v[204:207], v[188:191], v[78:81]
	v_mfma_f32_16x16x32_bf16 v[82:85], v[212:215], v[188:191], v[82:85]
	v_mfma_f32_16x16x32_bf16 v[90:93], v[204:207], v[196:199], v[90:93]
	v_mfma_f32_16x16x32_bf16 v[94:97], v[212:215], v[196:199], v[94:97]
	v_mfma_f32_16x16x32_bf16 v[58:61], v[208:211], v[176:179], v[58:61]
	v_mfma_f32_16x16x32_bf16 v[62:65], v[216:219], v[176:179], v[62:65]
	v_mfma_f32_16x16x32_bf16 v[66:69], v[208:211], v[184:187], v[66:69]
	v_mfma_f32_16x16x32_bf16 v[74:77], v[216:219], v[184:187], v[74:77]
	v_mfma_f32_16x16x32_bf16 v[78:81], v[208:211], v[192:195], v[78:81]
	v_mfma_f32_16x16x32_bf16 v[82:85], v[216:219], v[192:195], v[82:85]
	v_mfma_f32_16x16x32_bf16 v[90:93], v[208:211], v[200:203], v[90:93]
	v_mfma_f32_16x16x32_bf16 v[94:97], v[216:219], v[200:203], v[94:97]
	s_barrier
	s_cbranch_scc0 .LBB0_455
	s_setprio 0
	s_add_u32 s48, s48, 0x162b80
	s_addc_u32 s49, s49, 0
	v_add_u32_e32 v130, 0, v153
	v_add_u32_e32 v141, 0, v152
	s_mov_b32 m0, s70
	ds_read_b128 v[144:147], v130
	ds_read_b128 v[148:151], v130 offset:1024
	ds_read_b128 v[156:159], v130 offset:2048
	ds_read_b128 v[160:163], v130 offset:3072
	ds_read_b128 v[164:167], v141
	ds_read_b128 v[168:171], v141 offset:1024
	ds_read_b128 v[172:175], v141 offset:2048
	ds_read_b128 v[176:179], v141 offset:3072
	ds_read_b128 v[180:183], v141 offset:4096
	ds_read_b128 v[184:187], v141 offset:5120
	ds_read_b128 v[188:191], v141 offset:6144
	ds_read_b128 v[192:195], v141 offset:7168
	global_load_lds_dwordx4 v140, s[48:49]
	s_mov_b32 m0, s71
	s_nop 0
	global_load_lds_dwordx4 v142, s[48:49]
	s_waitcnt vmcnt(8)
	s_barrier
	s_waitcnt lgkmcnt(0)
	s_setprio 1
	s_waitcnt lgkmcnt(0)
	v_mfma_f32_16x16x32_bf16 v[126:129], v[144:147], v[164:167], v[126:129]
	v_mfma_f32_16x16x32_bf16 v[122:125], v[156:159], v[164:167], v[122:125]
	v_mfma_f32_16x16x32_bf16 v[114:117], v[156:159], v[172:175], v[114:117]
	v_mfma_f32_16x16x32_bf16 v[110:113], v[144:147], v[180:183], v[110:113]
	v_mfma_f32_16x16x32_bf16 v[102:105], v[144:147], v[188:191], v[102:105]
	v_mfma_f32_16x16x32_bf16 v[126:129], v[148:151], v[168:171], v[126:129]
	v_mfma_f32_16x16x32_bf16 v[122:125], v[160:163], v[168:171], v[122:125]
	v_mfma_f32_16x16x32_bf16 v[118:121], v[144:147], v[172:175], v[118:121]
	v_mfma_f32_16x16x32_bf16 v[114:117], v[160:163], v[176:179], v[114:117]
	v_mfma_f32_16x16x32_bf16 v[110:113], v[148:151], v[184:187], v[110:113]
	v_mfma_f32_16x16x32_bf16 v[106:109], v[156:159], v[180:183], v[106:109]
	v_mfma_f32_16x16x32_bf16 v[102:105], v[148:151], v[192:195], v[102:105]
	v_mfma_f32_16x16x32_bf16 v[98:101], v[156:159], v[188:191], v[98:101]
	v_mfma_f32_16x16x32_bf16 v[196:199], v[148:151], v[176:179], v[118:121]
	v_mfma_f32_16x16x32_bf16 v[200:203], v[160:163], v[184:187], v[106:109]
	v_mfma_f32_16x16x32_bf16 v[204:207], v[160:163], v[192:195], v[98:101]
	s_setprio 0
	s_barrier
	s_nop 2
	ds_read_b128 v[98:101], v130 offset:16384
	ds_read_b128 v[106:109], v130 offset:17408
	ds_read_b128 v[118:121], v130 offset:18432
	ds_read_b128 v[208:211], v130 offset:19456
	s_barrier
; #define LDA(dst, b, h)                                                                                     \
;   _Pragma("unroll") for (int m = 0; m < 4; ++m) _Pragma("unroll") for (int k = 0; k < 2; ++k) dst[m][k] = \
;       *reinterpret_cast<const bf16x8*>(shmc + aL + (((b) * 2 + (h)) * 16384 + (m * 2 + k) * 1024))
; #define LDB(dst, b, h)                                                                                     \
;   _Pragma("unroll") for (int n = 0; n < 2; ++n) _Pragma("unroll") for (int k = 0; k < 2; ++k) dst[n][k] = \
;       *reinterpret_cast<const bf16x8*>(shmc + bL + (((b) * 2 + (h)) * 16384 + (n * 2 + k) * 1024))
; #define WAIT_V(n) asm volatile("s_waitcnt vmcnt(" #n ")" ::: "memory")
; #define WAIT_L(n) asm volatile("s_waitcnt lgkmcnt(" #n ")" ::: "memory")
; #define BAR __builtin_amdgcn_s_barrier()
; template <int EPI>
; __device__ __forceinline__ void phase_gemm(const Params& p, const GemmDesc& d, char* shmc) {
;     ...
;       BAR; WAIT_L(0); MMA(0, 0, At, B0); BAR;
;       LDB(B1, 0, 1); BAR; WAIT_L(0); MMA(0, 1, At, B1); BAR;
;       LDA(At, 0, 1); WAIT_V(4); BAR; WAIT_L(0); MMA(1, 0, At, B0); MMA(1, 1, At, B1); BAR;
;     }
;     {
;       LDB(B0, 1, 0); LDA(At, 1, 0); WAIT_V(2); BAR; WAIT_L(0); MMA(0, 0, At, B0); BAR;
	s_waitcnt lgkmcnt(0)
	s_setprio 1
	s_waitcnt lgkmcnt(0)
	v_mfma_f32_16x16x32_bf16 v[86:89], v[98:101], v[164:167], v[86:89]
	v_mfma_f32_16x16x32_bf16 v[70:73], v[118:121], v[164:167], v[70:73]
	v_mfma_f32_16x16x32_bf16 v[54:57], v[98:101], v[172:175], v[54:57]
	v_mfma_f32_16x16x32_bf16 v[50:53], v[118:121], v[172:175], v[50:53]
	v_mfma_f32_16x16x32_bf16 v[46:49], v[98:101], v[180:183], v[46:49]
	v_mfma_f32_16x16x32_bf16 v[42:45], v[118:121], v[180:183], v[42:45]
	v_mfma_f32_16x16x32_bf16 v[38:41], v[98:101], v[188:191], v[38:41]
	v_mfma_f32_16x16x32_bf16 v[34:37], v[118:121], v[188:191], v[34:37]
	v_mfma_f32_16x16x32_bf16 v[86:89], v[106:109], v[168:171], v[86:89]
	v_mfma_f32_16x16x32_bf16 v[70:73], v[208:211], v[168:171], v[70:73]
	v_mfma_f32_16x16x32_bf16 v[54:57], v[106:109], v[176:179], v[54:57]
	v_mfma_f32_16x16x32_bf16 v[50:53], v[208:211], v[176:179], v[50:53]
	v_mfma_f32_16x16x32_bf16 v[46:49], v[106:109], v[184:187], v[46:49]
	v_mfma_f32_16x16x32_bf16 v[42:45], v[208:211], v[184:187], v[42:45]
	v_mfma_f32_16x16x32_bf16 v[38:41], v[106:109], v[192:195], v[38:41]
	v_mfma_f32_16x16x32_bf16 v[34:37], v[208:211], v[192:195], v[34:37]
	s_setprio 0
	s_barrier
	ds_read_b128 v[164:167], v141 offset:16384
	ds_read_b128 v[168:171], v141 offset:17408
	ds_read_b128 v[172:175], v141 offset:18432
	ds_read_b128 v[176:179], v141 offset:19456
	ds_read_b128 v[180:183], v141 offset:20480
	ds_read_b128 v[184:187], v141 offset:21504
	ds_read_b128 v[188:191], v141 offset:22528
	ds_read_b128 v[192:195], v141 offset:23552
	s_waitcnt vmcnt(4)
	s_barrier
	s_waitcnt lgkmcnt(0)
	s_setprio 1
	s_waitcnt lgkmcnt(0)
	v_mfma_f32_16x16x32_bf16 v[30:33], v[144:147], v[164:167], v[30:33]
	v_mfma_f32_16x16x32_bf16 v[26:29], v[156:159], v[164:167], v[26:29]
	v_mfma_f32_16x16x32_bf16 v[22:25], v[144:147], v[172:175], v[22:25]
	v_mfma_f32_16x16x32_bf16 v[18:21], v[156:159], v[172:175], v[18:21]
	v_mfma_f32_16x16x32_bf16 v[14:17], v[144:147], v[180:183], v[14:17]
	v_mfma_f32_16x16x32_bf16 v[10:13], v[156:159], v[180:183], v[10:13]
	v_mfma_f32_16x16x32_bf16 v[6:9], v[144:147], v[188:191], v[6:9]
	v_mfma_f32_16x16x32_bf16 v[2:5], v[156:159], v[188:191], v[2:5]
	v_mfma_f32_16x16x32_bf16 v[30:33], v[148:151], v[168:171], v[30:33]
	v_mfma_f32_16x16x32_bf16 v[26:29], v[160:163], v[168:171], v[26:29]
	v_mfma_f32_16x16x32_bf16 v[22:25], v[148:151], v[176:179], v[22:25]
	v_mfma_f32_16x16x32_bf16 v[18:21], v[160:163], v[176:179], v[18:21]
	v_mfma_f32_16x16x32_bf16 v[14:17], v[148:151], v[184:187], v[14:17]
	v_mfma_f32_16x16x32_bf16 v[10:13], v[160:163], v[184:187], v[10:13]
	v_mfma_f32_16x16x32_bf16 v[6:9], v[148:151], v[192:195], v[6:9]
	v_mfma_f32_16x16x32_bf16 v[2:5], v[160:163], v[192:195], v[2:5]
	s_setprio 0
	s_setprio 1
	v_mfma_f32_16x16x32_bf16 v[62:65], v[118:121], v[164:167], v[62:65]
	v_mfma_f32_16x16x32_bf16 v[144:147], v[208:211], v[168:171], v[62:65]
	v_mfma_f32_16x16x32_bf16 v[62:65], v[98:101], v[172:175], v[66:69]
	v_mfma_f32_16x16x32_bf16 v[148:151], v[106:109], v[176:179], v[62:65]
	v_mfma_f32_16x16x32_bf16 v[62:65], v[118:121], v[172:175], v[74:77]
	v_mfma_f32_16x16x32_bf16 v[156:159], v[208:211], v[176:179], v[62:65]
	v_mfma_f32_16x16x32_bf16 v[62:65], v[98:101], v[180:183], v[78:81]
	v_mfma_f32_16x16x32_bf16 v[160:163], v[106:109], v[184:187], v[62:65]
	v_mfma_f32_16x16x32_bf16 v[62:65], v[118:121], v[180:183], v[82:85]
	v_mfma_f32_16x16x32_bf16 v[58:61], v[98:101], v[164:167], v[58:61]
	v_mfma_f32_16x16x32_bf16 v[164:167], v[208:211], v[184:187], v[62:65]
	v_mfma_f32_16x16x32_bf16 v[62:65], v[98:101], v[188:191], v[90:93]
	v_mfma_f32_16x16x32_bf16 v[58:61], v[106:109], v[168:171], v[58:61]
	v_mfma_f32_16x16x32_bf16 v[168:171], v[106:109], v[192:195], v[62:65]
	v_mfma_f32_16x16x32_bf16 v[62:65], v[118:121], v[188:191], v[94:97]
	v_mfma_f32_16x16x32_bf16 v[172:175], v[208:211], v[192:195], v[62:65]
	s_setprio 0
	s_barrier
	ds_read_b128 v[176:179], v130 offset:32768
	ds_read_b128 v[180:183], v130 offset:33792
	ds_read_b128 v[184:187], v130 offset:34816
	ds_read_b128 v[188:191], v130 offset:35840
	s_nop 0
	ds_read_b128 v[62:65], v141 offset:32768
	ds_read_b128 v[78:81], v141 offset:33792
	ds_read_b128 v[94:97], v141 offset:34816
	ds_read_b128 v[192:195], v141 offset:35840
	ds_read_b128 v[208:211], v141 offset:36864
	ds_read_b128 v[212:215], v141 offset:37888
	ds_read_b128 v[216:219], v141 offset:38912
	ds_read_b128 v[220:223], v141 offset:39936
	s_waitcnt vmcnt(2)
	s_barrier
; #define LDA(dst, b, h)                                                                                     \
;   _Pragma("unroll") for (int m = 0; m < 4; ++m) _Pragma("unroll") for (int k = 0; k < 2; ++k) dst[m][k] = \
;       *reinterpret_cast<const bf16x8*>(shmc + aL + (((b) * 2 + (h)) * 16384 + (m * 2 + k) * 1024))
; #define LDB(dst, b, h)                                                                                     \
;   _Pragma("unroll") for (int n = 0; n < 2; ++n) _Pragma("unroll") for (int k = 0; k < 2; ++k) dst[n][k] = \
;       *reinterpret_cast<const bf16x8*>(shmc + bL + (((b) * 2 + (h)) * 16384 + (n * 2 + k) * 1024))
; #define WAIT_V(n) asm volatile("s_waitcnt vmcnt(" #n ")" ::: "memory")
; #define WAIT_L(n) asm volatile("s_waitcnt lgkmcnt(" #n ")" ::: "memory")
; #define BAR __builtin_amdgcn_s_barrier()
; template <int EPI>
; __device__ __forceinline__ void phase_gemm(const Params& p, const GemmDesc& d, char* shmc) {
;     ...
;       LDB(B0, 1, 0); LDA(At, 1, 0); WAIT_V(2); BAR; WAIT_L(0); MMA(0, 0, At, B0); BAR;
;       LDB(B1, 1, 1); WAIT_V(0); BAR; WAIT_L(0); MMA(0, 1, At, B1); BAR;
;       LDA(At, 1, 1); BAR; WAIT_L(0); MMA(1, 0, At, B0); MMA(1, 1, At, B1); BAR;
;     }
;     if (wr == 0) BAR;
	s_waitcnt lgkmcnt(0)
	s_setprio 1
	s_waitcnt lgkmcnt(0)
	v_mfma_f32_16x16x32_bf16 v[66:69], v[176:179], v[62:65], v[126:129]
	v_mfma_f32_16x16x32_bf16 v[126:129], v[180:183], v[78:81], v[66:69]
	v_mfma_f32_16x16x32_bf16 v[66:69], v[184:187], v[62:65], v[122:125]
	v_mfma_f32_16x16x32_bf16 v[118:121], v[188:191], v[78:81], v[66:69]
	v_mfma_f32_16x16x32_bf16 v[66:69], v[176:179], v[94:97], v[196:199]
	v_mfma_f32_16x16x32_bf16 v[106:109], v[180:183], v[192:195], v[66:69]
	v_mfma_f32_16x16x32_bf16 v[66:69], v[184:187], v[94:97], v[114:117]
	v_mfma_f32_16x16x32_bf16 v[98:101], v[188:191], v[192:195], v[66:69]
	v_mfma_f32_16x16x32_bf16 v[66:69], v[176:179], v[208:211], v[110:113]
	v_mfma_f32_16x16x32_bf16 v[90:93], v[180:183], v[212:215], v[66:69]
	v_mfma_f32_16x16x32_bf16 v[66:69], v[184:187], v[208:211], v[200:203]
	v_mfma_f32_16x16x32_bf16 v[82:85], v[188:191], v[212:215], v[66:69]
	v_mfma_f32_16x16x32_bf16 v[66:69], v[176:179], v[216:219], v[102:105]
	v_mfma_f32_16x16x32_bf16 v[74:77], v[180:183], v[220:223], v[66:69]
	v_mfma_f32_16x16x32_bf16 v[66:69], v[184:187], v[216:219], v[204:207]
	v_mfma_f32_16x16x32_bf16 v[66:69], v[188:191], v[220:223], v[66:69]
	s_setprio 0
	s_barrier
	ds_read_b128 v[196:199], v130 offset:49152
	ds_read_b128 v[200:203], v130 offset:50176
	ds_read_b128 v[204:207], v130 offset:51200
	ds_read_b128 v[224:227], v130 offset:52224
	s_waitcnt vmcnt(0)
	s_barrier
	s_waitcnt lgkmcnt(0)
	s_setprio 1
	s_waitcnt lgkmcnt(0)
	v_mfma_f32_16x16x32_bf16 v[86:89], v[196:199], v[62:65], v[86:89]
	v_mfma_f32_16x16x32_bf16 v[62:65], v[204:207], v[62:65], v[70:73]
	v_mfma_f32_16x16x32_bf16 v[54:57], v[196:199], v[94:97], v[54:57]
	v_mfma_f32_16x16x32_bf16 v[50:53], v[204:207], v[94:97], v[50:53]
	v_mfma_f32_16x16x32_bf16 v[46:49], v[196:199], v[208:211], v[46:49]
	v_mfma_f32_16x16x32_bf16 v[42:45], v[204:207], v[208:211], v[42:45]
	v_mfma_f32_16x16x32_bf16 v[38:41], v[196:199], v[216:219], v[38:41]
	v_mfma_f32_16x16x32_bf16 v[34:37], v[204:207], v[216:219], v[34:37]
	v_mfma_f32_16x16x32_bf16 v[122:125], v[200:203], v[78:81], v[86:89]
	v_mfma_f32_16x16x32_bf16 v[114:117], v[224:227], v[78:81], v[62:65]
	v_mfma_f32_16x16x32_bf16 v[110:113], v[200:203], v[192:195], v[54:57]
	v_mfma_f32_16x16x32_bf16 v[102:105], v[224:227], v[192:195], v[50:53]
	v_mfma_f32_16x16x32_bf16 v[94:97], v[200:203], v[212:215], v[46:49]
	v_mfma_f32_16x16x32_bf16 v[86:89], v[224:227], v[212:215], v[42:45]
	v_mfma_f32_16x16x32_bf16 v[78:81], v[200:203], v[220:223], v[38:41]
	v_mfma_f32_16x16x32_bf16 v[70:73], v[224:227], v[220:223], v[34:37]
	s_setprio 0
	s_barrier
	s_nop 0
	ds_read_b128 v[34:37], v141 offset:49152
	ds_read_b128 v[42:45], v141 offset:50176
	ds_read_b128 v[192:195], v141 offset:51200
	ds_read_b128 v[208:211], v141 offset:52224
	ds_read_b128 v[212:215], v141 offset:53248
	ds_read_b128 v[216:219], v141 offset:54272
	ds_read_b128 v[220:223], v141 offset:55296
	ds_read_b128 v[228:231], v141 offset:56320
	s_barrier
	s_waitcnt lgkmcnt(0)
	s_setprio 1
	s_waitcnt lgkmcnt(0)
	v_mfma_f32_16x16x32_bf16 v[30:33], v[176:179], v[34:37], v[30:33]
	v_mfma_f32_16x16x32_bf16 v[26:29], v[184:187], v[34:37], v[26:29]
	v_mfma_f32_16x16x32_bf16 v[22:25], v[176:179], v[192:195], v[22:25]
	v_mfma_f32_16x16x32_bf16 v[18:21], v[184:187], v[192:195], v[18:21]
	v_mfma_f32_16x16x32_bf16 v[14:17], v[176:179], v[212:215], v[14:17]
	v_mfma_f32_16x16x32_bf16 v[10:13], v[184:187], v[212:215], v[10:13]
	v_mfma_f32_16x16x32_bf16 v[6:9], v[176:179], v[220:223], v[6:9]
	v_mfma_f32_16x16x32_bf16 v[2:5], v[184:187], v[220:223], v[2:5]
	v_mfma_f32_16x16x32_bf16 v[62:65], v[180:183], v[42:45], v[30:33]
	v_mfma_f32_16x16x32_bf16 v[54:57], v[188:191], v[42:45], v[26:29]
	v_mfma_f32_16x16x32_bf16 v[46:49], v[180:183], v[208:211], v[22:25]
	v_mfma_f32_16x16x32_bf16 v[38:41], v[188:191], v[208:211], v[18:21]
	v_mfma_f32_16x16x32_bf16 v[30:33], v[180:183], v[216:219], v[14:17]
	v_mfma_f32_16x16x32_bf16 v[22:25], v[188:191], v[216:219], v[10:13]
	v_mfma_f32_16x16x32_bf16 v[14:17], v[180:183], v[228:231], v[6:9]
	v_mfma_f32_16x16x32_bf16 v[6:9], v[188:191], v[228:231], v[2:5]
	s_setprio 0
	s_setprio 1
	v_mfma_f32_16x16x32_bf16 v[2:5], v[196:199], v[34:37], v[58:61]
	v_mfma_f32_16x16x32_bf16 v[58:61], v[200:203], v[42:45], v[2:5]
	v_mfma_f32_16x16x32_bf16 v[2:5], v[204:207], v[34:37], v[144:147]
	v_mfma_f32_16x16x32_bf16 v[50:53], v[224:227], v[42:45], v[2:5]
	v_mfma_f32_16x16x32_bf16 v[2:5], v[196:199], v[192:195], v[148:151]
	v_mfma_f32_16x16x32_bf16 v[42:45], v[200:203], v[208:211], v[2:5]
	v_mfma_f32_16x16x32_bf16 v[2:5], v[204:207], v[192:195], v[156:159]
	v_mfma_f32_16x16x32_bf16 v[34:37], v[224:227], v[208:211], v[2:5]
	v_mfma_f32_16x16x32_bf16 v[2:5], v[196:199], v[212:215], v[160:163]
	v_mfma_f32_16x16x32_bf16 v[26:29], v[200:203], v[216:219], v[2:5]
	v_mfma_f32_16x16x32_bf16 v[2:5], v[204:207], v[212:215], v[164:167]
	v_mfma_f32_16x16x32_bf16 v[18:21], v[224:227], v[216:219], v[2:5]
	v_mfma_f32_16x16x32_bf16 v[2:5], v[196:199], v[220:223], v[168:171]
	v_mfma_f32_16x16x32_bf16 v[10:13], v[200:203], v[228:231], v[2:5]
	v_mfma_f32_16x16x32_bf16 v[2:5], v[204:207], v[220:223], v[172:175]
	v_mfma_f32_16x16x32_bf16 v[2:5], v[224:227], v[228:231], v[2:5]
	s_setprio 0
	s_barrier
	s_and_saveexec_b64 s[48:49], s[4:5]
	s_cbranch_execz .LBB0_458
	s_barrier

; #define LDA(dst, b, h)                                                                                     \
;   _Pragma("unroll") for (int m = 0; m < 4; ++m) _Pragma("unroll") for (int k = 0; k < 2; ++k) dst[m][k] = \
;       *reinterpret_cast<const bf16x8*>(shmc + aL + (((b) * 2 + (h)) * 16384 + (m * 2 + k) * 1024))
; #define LDB(dst, b, h)                                                                                     \
;   _Pragma("unroll") for (int n = 0; n < 2; ++n) _Pragma("unroll") for (int k = 0; k < 2; ++k) dst[n][k] = \
;       *reinterpret_cast<const bf16x8*>(shmc + bL + (((b) * 2 + (h)) * 16384 + (n * 2 + k) * 1024))
; #define OPAQ asm volatile("" : "+v"(aL), "+v"(bL))
; #define WAIT_V(n) asm volatile("s_waitcnt vmcnt(" #n ")" ::: "memory")
; #define WAIT_L(n) asm volatile("s_waitcnt lgkmcnt(" #n ")" ::: "memory")
; #define BAR __builtin_amdgcn_s_barrier()
; #define SCHED __builtin_amdgcn_sched_barrier(0)
; template <int EPI>
; __device__ __forceinline__ void phase_gemm(const Params& p, const GemmDesc& d, char* shmc) {
;     ...
;     for (int t = 0; t < nt - 2; t += 2) {
;       OPAQ;
;       LDB(B0, 0, 0); SCHED; LDA(At, 0, 0); STAGE_A(SA(1, 1), 1, t + 1);
;       WAIT_L(8); BAR; WAIT_L(0); MMA(0, 0, At, B0); BAR; SCHED;
;       LDB(B1, 0, 1); STAGE_B(SB(0, 0), 0, t + 2);
;       BAR; WAIT_L(0); MMA(0, 1, At, B1); BAR;
;       LDA(At, 0, 1); STAGE_A(SA(0, 0), 0, t + 2);
;       BAR; WAIT_L(0); MMA(1, 0, At, B0); BAR; SCHED;
;       STAGE_B(SB(0, 1), 1, t + 2);
;       WAIT_V(6); BAR; MMA(1, 1, At, B1); BAR;
;       LDB(B0, 1, 0); SCHED; LDA(At, 1, 0); STAGE_A(SA(0, 1), 1, t + 2);
;       WAIT_L(8); BAR; WAIT_L(0); MMA(0, 0, At, B0); BAR; SCHED;
;       LDB(B1, 1, 1); STAGE_B(SB(1, 0), 0, t + 3);
;       BAR; WAIT_L(0); MMA(0, 1, At, B1); BAR;
;       LDA(At, 1, 1); STAGE_A(SA(1, 0), 0, t + 3);
;       BAR; WAIT_L(0); MMA(1, 0, At, B0); BAR; SCHED;
;       STAGE_B(SB(1, 1), 1, t + 3);
;       WAIT_V(6); BAR; MMA(1, 1, At, B1); BAR;
;     }
.LBB0_598:
	s_nop 0
	v_add_u32_e32 v175, 0, v179
	v_add_u32_e32 v176, 0, v177
	s_setprio 0
	ds_read_b128 v[138:141], v175
	ds_read_b128 v[142:145], v175 offset:1024
	ds_read_b128 v[146:149], v175 offset:2048
	ds_read_b128 v[150:153], v175 offset:3072
	ds_read_b128 v[206:209], v175 offset:16384
	ds_read_b128 v[210:213], v175 offset:17408
	ds_read_b128 v[214:217], v175 offset:18432
	ds_read_b128 v[218:221], v175 offset:19456
	v_lshl_add_u64 v[222:223], v[134:135], 0, s[62:63]
	v_lshl_add_u64 v[224:225], v[136:137], 0, s[62:63]
	v_lshl_add_u64 v[226:227], v[130:131], 0, s[62:63]
	v_lshl_add_u64 v[228:229], v[132:133], 0, s[62:63]
	ds_read_b128 v[154:157], v176
	ds_read_b128 v[158:161], v176 offset:1024
	ds_read_b128 v[182:185], v176 offset:2048
	ds_read_b128 v[186:189], v176 offset:3072
	ds_read_b128 v[190:193], v176 offset:4096
	ds_read_b128 v[194:197], v176 offset:5120
	ds_read_b128 v[198:201], v176 offset:6144
	ds_read_b128 v[202:205], v176 offset:7168
	s_add_i32 s88, s68, 0xc000
	s_mov_b32 m0, s88
	v_lshl_add_u64 v[230:231], v[222:223], 0, s[26:27]
	global_load_lds_dwordx4 v[230:231], off
	s_add_i32 s89, s68, 0xe000
	v_lshl_add_u64 v[230:231], v[224:225], 0, s[26:27]
	s_mov_b32 m0, s89
	s_nop 0
	global_load_lds_dwordx4 v[230:231], off
	s_waitcnt vmcnt(8)
	s_waitcnt lgkmcnt(0)
	s_setprio 1
	s_barrier
	v_mfma_f32_16x16x32_bf16 v[126:129], v[154:157], v[138:141], v[126:129]
	v_mfma_f32_16x16x32_bf16 v[122:125], v[154:157], v[146:149], v[122:125]
	v_mfma_f32_16x16x32_bf16 v[118:121], v[182:185], v[138:141], v[118:121]
	v_mfma_f32_16x16x32_bf16 v[114:117], v[182:185], v[146:149], v[114:117]
	v_mfma_f32_16x16x32_bf16 v[110:113], v[190:193], v[138:141], v[110:113]
	v_mfma_f32_16x16x32_bf16 v[106:109], v[190:193], v[146:149], v[106:109]
	v_mfma_f32_16x16x32_bf16 v[102:105], v[198:201], v[138:141], v[102:105]
	v_mfma_f32_16x16x32_bf16 v[94:97], v[198:201], v[146:149], v[94:97]
	v_mfma_f32_16x16x32_bf16 v[126:129], v[158:161], v[142:145], v[126:129]
	v_mfma_f32_16x16x32_bf16 v[122:125], v[158:161], v[150:153], v[122:125]
	v_mfma_f32_16x16x32_bf16 v[118:121], v[186:189], v[142:145], v[118:121]
	v_mfma_f32_16x16x32_bf16 v[114:117], v[186:189], v[150:153], v[114:117]
	v_mfma_f32_16x16x32_bf16 v[110:113], v[194:197], v[142:145], v[110:113]
	v_mfma_f32_16x16x32_bf16 v[106:109], v[194:197], v[150:153], v[106:109]
	v_mfma_f32_16x16x32_bf16 v[102:105], v[202:205], v[142:145], v[102:105]
	v_mfma_f32_16x16x32_bf16 v[94:97], v[202:205], v[150:153], v[94:97]
	v_mfma_f32_16x16x32_bf16 v[50:53], v[154:157], v[206:209], v[50:53]
	v_mfma_f32_16x16x32_bf16 v[42:45], v[154:157], v[214:217], v[42:45]
	v_mfma_f32_16x16x32_bf16 v[38:41], v[182:185], v[206:209], v[38:41]
	v_mfma_f32_16x16x32_bf16 v[34:37], v[182:185], v[214:217], v[34:37]
	v_mfma_f32_16x16x32_bf16 v[30:33], v[190:193], v[206:209], v[30:33]
	v_mfma_f32_16x16x32_bf16 v[26:29], v[190:193], v[214:217], v[26:29]
	v_mfma_f32_16x16x32_bf16 v[22:25], v[198:201], v[206:209], v[22:25]
	v_mfma_f32_16x16x32_bf16 v[18:21], v[198:201], v[214:217], v[18:21]
	v_mfma_f32_16x16x32_bf16 v[50:53], v[158:161], v[210:213], v[50:53]
	v_mfma_f32_16x16x32_bf16 v[42:45], v[158:161], v[218:221], v[42:45]
	v_mfma_f32_16x16x32_bf16 v[38:41], v[186:189], v[210:213], v[38:41]
	v_mfma_f32_16x16x32_bf16 v[34:37], v[186:189], v[218:221], v[34:37]
	v_mfma_f32_16x16x32_bf16 v[30:33], v[194:197], v[210:213], v[30:33]
	v_mfma_f32_16x16x32_bf16 v[26:29], v[194:197], v[218:221], v[26:29]
	v_mfma_f32_16x16x32_bf16 v[22:25], v[202:205], v[210:213], v[22:25]
	v_mfma_f32_16x16x32_bf16 v[18:21], v[202:205], v[218:221], v[18:21]
	s_barrier
	s_setprio 0
	ds_read_b128 v[154:157], v176 offset:16384
	ds_read_b128 v[158:161], v176 offset:17408
	ds_read_b128 v[182:185], v176 offset:18432
	ds_read_b128 v[186:189], v176 offset:19456
	ds_read_b128 v[190:193], v176 offset:20480
	ds_read_b128 v[194:197], v176 offset:21504
	ds_read_b128 v[198:201], v176 offset:22528
	ds_read_b128 v[202:205], v176 offset:23552
	s_mov_b32 m0, s69
	v_lshl_add_u64 v[230:231], v[226:227], 0, s[38:39]
	global_load_lds_dwordx4 v[230:231], off
	v_lshl_add_u64 v[230:231], v[228:229], 0, s[38:39]
	s_mov_b32 m0, s70
	s_nop 0
	global_load_lds_dwordx4 v[230:231], off
	s_mov_b32 m0, s68
	v_lshl_add_u64 v[230:231], v[222:223], 0, s[40:41]
	global_load_lds_dwordx4 v[230:231], off
	v_lshl_add_u64 v[230:231], v[224:225], 0, s[40:41]
	s_mov_b32 m0, s71
	s_nop 0
	global_load_lds_dwordx4 v[230:231], off
	s_mov_b32 m0, s76
	v_lshl_add_u64 v[230:231], v[226:227], 0, s[42:43]
	global_load_lds_dwordx4 v[230:231], off
	v_lshl_add_u64 v[230:231], v[228:229], 0, s[42:43]
	s_mov_b32 m0, s77
	s_nop 0
	global_load_lds_dwordx4 v[230:231], off
	s_waitcnt vmcnt(8)
	s_waitcnt lgkmcnt(0)
	s_setprio 1
	s_barrier
; #define LDA(dst, b, h)                                                                                     \
;   _Pragma("unroll") for (int m = 0; m < 4; ++m) _Pragma("unroll") for (int k = 0; k < 2; ++k) dst[m][k] = \
;       *reinterpret_cast<const bf16x8*>(shmc + aL + (((b) * 2 + (h)) * 16384 + (m * 2 + k) * 1024))
; #define LDB(dst, b, h)                                                                                     \
;   _Pragma("unroll") for (int n = 0; n < 2; ++n) _Pragma("unroll") for (int k = 0; k < 2; ++k) dst[n][k] = \
;       *reinterpret_cast<const bf16x8*>(shmc + bL + (((b) * 2 + (h)) * 16384 + (n * 2 + k) * 1024))
; #define OPAQ asm volatile("" : "+v"(aL), "+v"(bL))
; #define WAIT_V(n) asm volatile("s_waitcnt vmcnt(" #n ")" ::: "memory")
; #define WAIT_L(n) asm volatile("s_waitcnt lgkmcnt(" #n ")" ::: "memory")
; #define BAR __builtin_amdgcn_s_barrier()
; #define SCHED __builtin_amdgcn_sched_barrier(0)
; template <int EPI>
; __device__ __forceinline__ void phase_gemm(const Params& p, const GemmDesc& d, char* shmc) {
;     ...
;     for (int t = 0; t < nt - 2; t += 2) {
;       OPAQ;
;       LDB(B0, 0, 0); SCHED; LDA(At, 0, 0); STAGE_A(SA(1, 1), 1, t + 1);
;       WAIT_L(8); BAR; WAIT_L(0); MMA(0, 0, At, B0); BAR; SCHED;
;       LDB(B1, 0, 1); STAGE_B(SB(0, 0), 0, t + 2);
;       BAR; WAIT_L(0); MMA(0, 1, At, B1); BAR;
;       LDA(At, 0, 1); STAGE_A(SA(0, 0), 0, t + 2);
;       BAR; WAIT_L(0); MMA(1, 0, At, B0); BAR; SCHED;
;       STAGE_B(SB(0, 1), 1, t + 2);
;       WAIT_V(6); BAR; MMA(1, 1, At, B1); BAR;
;       LDB(B0, 1, 0); SCHED; LDA(At, 1, 0); STAGE_A(SA(0, 1), 1, t + 2);
;       WAIT_L(8); BAR; WAIT_L(0); MMA(0, 0, At, B0); BAR; SCHED;
;       LDB(B1, 1, 1); STAGE_B(SB(1, 0), 0, t + 3);
;       BAR; WAIT_L(0); MMA(0, 1, At, B1); BAR;
;       LDA(At, 1, 1); STAGE_A(SA(1, 0), 0, t + 3);
;       BAR; WAIT_L(0); MMA(1, 0, At, B0); BAR; SCHED;
;       STAGE_B(SB(1, 1), 1, t + 3);
;       WAIT_V(6); BAR; MMA(1, 1, At, B1); BAR;
;     }
	v_mfma_f32_16x16x32_bf16 v[14:17], v[154:157], v[138:141], v[14:17]
	v_mfma_f32_16x16x32_bf16 v[10:13], v[154:157], v[146:149], v[10:13]
	v_mfma_f32_16x16x32_bf16 v[6:9], v[182:185], v[138:141], v[6:9]
	v_mfma_f32_16x16x32_bf16 v[2:5], v[182:185], v[146:149], v[2:5]
	v_mfma_f32_16x16x32_bf16 v[46:49], v[190:193], v[138:141], v[46:49]
	v_mfma_f32_16x16x32_bf16 v[54:57], v[190:193], v[146:149], v[54:57]
	v_mfma_f32_16x16x32_bf16 v[58:61], v[198:201], v[138:141], v[58:61]
	v_mfma_f32_16x16x32_bf16 v[62:65], v[198:201], v[146:149], v[62:65]
	v_mfma_f32_16x16x32_bf16 v[14:17], v[158:161], v[142:145], v[14:17]
	v_mfma_f32_16x16x32_bf16 v[10:13], v[158:161], v[150:153], v[10:13]
	v_mfma_f32_16x16x32_bf16 v[6:9], v[186:189], v[142:145], v[6:9]
	v_mfma_f32_16x16x32_bf16 v[2:5], v[186:189], v[150:153], v[2:5]
	v_mfma_f32_16x16x32_bf16 v[46:49], v[194:197], v[142:145], v[46:49]
	v_mfma_f32_16x16x32_bf16 v[54:57], v[194:197], v[150:153], v[54:57]
	v_mfma_f32_16x16x32_bf16 v[58:61], v[202:205], v[142:145], v[58:61]
	v_mfma_f32_16x16x32_bf16 v[62:65], v[202:205], v[150:153], v[62:65]
	v_mfma_f32_16x16x32_bf16 v[66:69], v[154:157], v[206:209], v[66:69]
	v_mfma_f32_16x16x32_bf16 v[70:73], v[154:157], v[214:217], v[70:73]
	v_mfma_f32_16x16x32_bf16 v[74:77], v[182:185], v[206:209], v[74:77]
	v_mfma_f32_16x16x32_bf16 v[78:81], v[182:185], v[214:217], v[78:81]
	v_mfma_f32_16x16x32_bf16 v[82:85], v[190:193], v[206:209], v[82:85]
	v_mfma_f32_16x16x32_bf16 v[86:89], v[190:193], v[214:217], v[86:89]
	v_mfma_f32_16x16x32_bf16 v[90:93], v[198:201], v[206:209], v[90:93]
	v_mfma_f32_16x16x32_bf16 v[98:101], v[198:201], v[214:217], v[98:101]
	v_mfma_f32_16x16x32_bf16 v[66:69], v[158:161], v[210:213], v[66:69]
	v_mfma_f32_16x16x32_bf16 v[70:73], v[158:161], v[218:221], v[70:73]
	v_mfma_f32_16x16x32_bf16 v[74:77], v[186:189], v[210:213], v[74:77]
	v_mfma_f32_16x16x32_bf16 v[78:81], v[186:189], v[218:221], v[78:81]
	v_mfma_f32_16x16x32_bf16 v[82:85], v[194:197], v[210:213], v[82:85]
	v_mfma_f32_16x16x32_bf16 v[86:89], v[194:197], v[218:221], v[86:89]
	v_mfma_f32_16x16x32_bf16 v[90:93], v[202:205], v[210:213], v[90:93]
	v_mfma_f32_16x16x32_bf16 v[98:101], v[202:205], v[218:221], v[98:101]
	s_barrier
	s_setprio 0
	ds_read_b128 v[138:141], v175 offset:32768
	ds_read_b128 v[142:145], v175 offset:33792
	ds_read_b128 v[146:149], v175 offset:34816
	ds_read_b128 v[150:153], v175 offset:35840
	ds_read_b128 v[206:209], v175 offset:49152
	ds_read_b128 v[210:213], v175 offset:50176
	ds_read_b128 v[214:217], v175 offset:51200
	ds_read_b128 v[218:221], v175 offset:52224
	ds_read_b128 v[154:157], v176 offset:32768
	ds_read_b128 v[158:161], v176 offset:33792
	ds_read_b128 v[182:185], v176 offset:34816
	ds_read_b128 v[186:189], v176 offset:35840
	ds_read_b128 v[190:193], v176 offset:36864
	ds_read_b128 v[194:197], v176 offset:37888
	ds_read_b128 v[198:201], v176 offset:38912
	ds_read_b128 v[202:205], v176 offset:39936
	s_mov_b32 m0, s80
	v_lshl_add_u64 v[230:231], v[222:223], 0, s[48:49]
	global_load_lds_dwordx4 v[230:231], off
	v_lshl_add_u64 v[230:231], v[224:225], 0, s[48:49]
	s_mov_b32 m0, s81
	s_nop 0
	global_load_lds_dwordx4 v[230:231], off
	s_waitcnt vmcnt(8)
	s_waitcnt lgkmcnt(0)
	s_setprio 1
	s_barrier
	v_mfma_f32_16x16x32_bf16 v[126:129], v[154:157], v[138:141], v[126:129]
	v_mfma_f32_16x16x32_bf16 v[122:125], v[154:157], v[146:149], v[122:125]
	v_mfma_f32_16x16x32_bf16 v[118:121], v[182:185], v[138:141], v[118:121]
	v_mfma_f32_16x16x32_bf16 v[114:117], v[182:185], v[146:149], v[114:117]
	v_mfma_f32_16x16x32_bf16 v[110:113], v[190:193], v[138:141], v[110:113]
	v_mfma_f32_16x16x32_bf16 v[106:109], v[190:193], v[146:149], v[106:109]
	v_mfma_f32_16x16x32_bf16 v[102:105], v[198:201], v[138:141], v[102:105]
	v_mfma_f32_16x16x32_bf16 v[94:97], v[198:201], v[146:149], v[94:97]
	v_mfma_f32_16x16x32_bf16 v[126:129], v[158:161], v[142:145], v[126:129]
	v_mfma_f32_16x16x32_bf16 v[122:125], v[158:161], v[150:153], v[122:125]
	v_mfma_f32_16x16x32_bf16 v[118:121], v[186:189], v[142:145], v[118:121]
	v_mfma_f32_16x16x32_bf16 v[114:117], v[186:189], v[150:153], v[114:117]
	v_mfma_f32_16x16x32_bf16 v[110:113], v[194:197], v[142:145], v[110:113]
	v_mfma_f32_16x16x32_bf16 v[106:109], v[194:197], v[150:153], v[106:109]
	v_mfma_f32_16x16x32_bf16 v[102:105], v[202:205], v[142:145], v[102:105]
	v_mfma_f32_16x16x32_bf16 v[94:97], v[202:205], v[150:153], v[94:97]
	v_mfma_f32_16x16x32_bf16 v[50:53], v[154:157], v[206:209], v[50:53]
	v_mfma_f32_16x16x32_bf16 v[42:45], v[154:157], v[214:217], v[42:45]
	v_mfma_f32_16x16x32_bf16 v[38:41], v[182:185], v[206:209], v[38:41]
	v_mfma_f32_16x16x32_bf16 v[34:37], v[182:185], v[214:217], v[34:37]
	v_mfma_f32_16x16x32_bf16 v[30:33], v[190:193], v[206:209], v[30:33]
	v_mfma_f32_16x16x32_bf16 v[26:29], v[190:193], v[214:217], v[26:29]
	v_mfma_f32_16x16x32_bf16 v[22:25], v[198:201], v[206:209], v[22:25]
	v_mfma_f32_16x16x32_bf16 v[18:21], v[198:201], v[214:217], v[18:21]
	v_mfma_f32_16x16x32_bf16 v[50:53], v[158:161], v[210:213], v[50:53]
	v_mfma_f32_16x16x32_bf16 v[42:45], v[158:161], v[218:221], v[42:45]
	v_mfma_f32_16x16x32_bf16 v[38:41], v[186:189], v[210:213], v[38:41]
	v_mfma_f32_16x16x32_bf16 v[34:37], v[186:189], v[218:221], v[34:37]
	v_mfma_f32_16x16x32_bf16 v[30:33], v[194:197], v[210:213], v[30:33]
	v_mfma_f32_16x16x32_bf16 v[26:29], v[194:197], v[218:221], v[26:29]
	v_mfma_f32_16x16x32_bf16 v[22:25], v[202:205], v[210:213], v[22:25]
	v_mfma_f32_16x16x32_bf16 v[18:21], v[202:205], v[218:221], v[18:21]
	s_barrier
; #define LDA(dst, b, h)                                                                                     \
;   _Pragma("unroll") for (int m = 0; m < 4; ++m) _Pragma("unroll") for (int k = 0; k < 2; ++k) dst[m][k] = \
;       *reinterpret_cast<const bf16x8*>(shmc + aL + (((b) * 2 + (h)) * 16384 + (m * 2 + k) * 1024))
; #define LDB(dst, b, h)                                                                                     \
;   _Pragma("unroll") for (int n = 0; n < 2; ++n) _Pragma("unroll") for (int k = 0; k < 2; ++k) dst[n][k] = \
;       *reinterpret_cast<const bf16x8*>(shmc + bL + (((b) * 2 + (h)) * 16384 + (n * 2 + k) * 1024))
; #define OPAQ asm volatile("" : "+v"(aL), "+v"(bL))
; #define WAIT_V(n) asm volatile("s_waitcnt vmcnt(" #n ")" ::: "memory")
; #define WAIT_L(n) asm volatile("s_waitcnt lgkmcnt(" #n ")" ::: "memory")
; #define BAR __builtin_amdgcn_s_barrier()
; #define SCHED __builtin_amdgcn_sched_barrier(0)
; template <int EPI>
; __device__ __forceinline__ void phase_gemm(const Params& p, const GemmDesc& d, char* shmc) {
;     ...
;     for (int t = 0; t < nt - 2; t += 2) {
;       OPAQ;
;       LDB(B0, 0, 0); SCHED; LDA(At, 0, 0); STAGE_A(SA(1, 1), 1, t + 1);
;       WAIT_L(8); BAR; WAIT_L(0); MMA(0, 0, At, B0); BAR; SCHED;
;       LDB(B1, 0, 1); STAGE_B(SB(0, 0), 0, t + 2);
;       BAR; WAIT_L(0); MMA(0, 1, At, B1); BAR;
;       LDA(At, 0, 1); STAGE_A(SA(0, 0), 0, t + 2);
;       BAR; WAIT_L(0); MMA(1, 0, At, B0); BAR; SCHED;
;       STAGE_B(SB(0, 1), 1, t + 2);
;       WAIT_V(6); BAR; MMA(1, 1, At, B1); BAR;
;       LDB(B0, 1, 0); SCHED; LDA(At, 1, 0); STAGE_A(SA(0, 1), 1, t + 2);
;       WAIT_L(8); BAR; WAIT_L(0); MMA(0, 0, At, B0); BAR; SCHED;
;       LDB(B1, 1, 1); STAGE_B(SB(1, 0), 0, t + 3);
;       BAR; WAIT_L(0); MMA(0, 1, At, B1); BAR;
;       LDA(At, 1, 1); STAGE_A(SA(1, 0), 0, t + 3);
;       BAR; WAIT_L(0); MMA(1, 0, At, B0); BAR; SCHED;
;       STAGE_B(SB(1, 1), 1, t + 3);
;       WAIT_V(6); BAR; MMA(1, 1, At, B1); BAR;
;     }
;     {
;       OPAQ;
;       LDB(B0, 0, 0); LDA(At, 0, 0); STAGE_A(SA(1, 1), 1, nt - 1);
;       BAR; WAIT_L(0); MMA(0, 0, At, B0); BAR;
;       LDB(B1, 0, 1); BAR; WAIT_L(0); MMA(0, 1, At, B1); BAR;
;       LDA(At, 0, 1); WAIT_V(4); BAR; WAIT_L(0); MMA(1, 0, At, B0); MMA(1, 1, At, B1); BAR;
	s_setprio 0
	ds_read_b128 v[154:157], v176 offset:49152
	ds_read_b128 v[158:161], v176 offset:50176
	ds_read_b128 v[182:185], v176 offset:51200
	ds_read_b128 v[186:189], v176 offset:52224
	ds_read_b128 v[190:193], v176 offset:53248
	ds_read_b128 v[194:197], v176 offset:54272
	ds_read_b128 v[198:201], v176 offset:55296
	ds_read_b128 v[202:205], v176 offset:56320
	s_mov_b32 m0, s61
	v_lshl_add_u64 v[230:231], v[226:227], 0, s[52:53]
	global_load_lds_dwordx4 v[230:231], off
	v_lshl_add_u64 v[230:231], v[228:229], 0, s[52:53]
	s_mov_b32 m0, s78
	s_nop 0
	global_load_lds_dwordx4 v[230:231], off
	s_mov_b32 m0, s79
	v_lshl_add_u64 v[230:231], v[222:223], 0, s[54:55]
	global_load_lds_dwordx4 v[230:231], off
	v_lshl_add_u64 v[230:231], v[224:225], 0, s[54:55]
	s_mov_b32 m0, s86
	s_nop 0
	global_load_lds_dwordx4 v[230:231], off
	s_mov_b32 m0, s64
	v_lshl_add_u64 v[230:231], v[226:227], 0, s[56:57]
	global_load_lds_dwordx4 v[230:231], off
	v_lshl_add_u64 v[230:231], v[228:229], 0, s[56:57]
	s_mov_b32 m0, s65
	s_nop 0
	global_load_lds_dwordx4 v[230:231], off
	s_add_i32 s87, s87, 2
	s_add_u32 s62, s62, 0x100
	s_addc_u32 s63, s63, 0
	s_cmp_gt_u32 s87, 27
	s_waitcnt vmcnt(8)
	s_waitcnt lgkmcnt(0)
	s_setprio 1
	s_barrier
	v_mfma_f32_16x16x32_bf16 v[14:17], v[154:157], v[138:141], v[14:17]
	v_mfma_f32_16x16x32_bf16 v[10:13], v[154:157], v[146:149], v[10:13]
	v_mfma_f32_16x16x32_bf16 v[6:9], v[182:185], v[138:141], v[6:9]
	v_mfma_f32_16x16x32_bf16 v[2:5], v[182:185], v[146:149], v[2:5]
	v_mfma_f32_16x16x32_bf16 v[46:49], v[190:193], v[138:141], v[46:49]
	v_mfma_f32_16x16x32_bf16 v[54:57], v[190:193], v[146:149], v[54:57]
	v_mfma_f32_16x16x32_bf16 v[58:61], v[198:201], v[138:141], v[58:61]
	v_mfma_f32_16x16x32_bf16 v[62:65], v[198:201], v[146:149], v[62:65]
	v_mfma_f32_16x16x32_bf16 v[14:17], v[158:161], v[142:145], v[14:17]
	v_mfma_f32_16x16x32_bf16 v[10:13], v[158:161], v[150:153], v[10:13]
	v_mfma_f32_16x16x32_bf16 v[6:9], v[186:189], v[142:145], v[6:9]
	v_mfma_f32_16x16x32_bf16 v[2:5], v[186:189], v[150:153], v[2:5]
	v_mfma_f32_16x16x32_bf16 v[46:49], v[194:197], v[142:145], v[46:49]
	v_mfma_f32_16x16x32_bf16 v[54:57], v[194:197], v[150:153], v[54:57]
	v_mfma_f32_16x16x32_bf16 v[58:61], v[202:205], v[142:145], v[58:61]
	v_mfma_f32_16x16x32_bf16 v[62:65], v[202:205], v[150:153], v[62:65]
	v_mfma_f32_16x16x32_bf16 v[66:69], v[154:157], v[206:209], v[66:69]
	v_mfma_f32_16x16x32_bf16 v[70:73], v[154:157], v[214:217], v[70:73]
	v_mfma_f32_16x16x32_bf16 v[74:77], v[182:185], v[206:209], v[74:77]
	v_mfma_f32_16x16x32_bf16 v[78:81], v[182:185], v[214:217], v[78:81]
	v_mfma_f32_16x16x32_bf16 v[82:85], v[190:193], v[206:209], v[82:85]
	v_mfma_f32_16x16x32_bf16 v[86:89], v[190:193], v[214:217], v[86:89]
	v_mfma_f32_16x16x32_bf16 v[90:93], v[198:201], v[206:209], v[90:93]
	v_mfma_f32_16x16x32_bf16 v[98:101], v[198:201], v[214:217], v[98:101]
	v_mfma_f32_16x16x32_bf16 v[66:69], v[158:161], v[210:213], v[66:69]
	v_mfma_f32_16x16x32_bf16 v[70:73], v[158:161], v[218:221], v[70:73]
	v_mfma_f32_16x16x32_bf16 v[74:77], v[186:189], v[210:213], v[74:77]
	v_mfma_f32_16x16x32_bf16 v[78:81], v[186:189], v[218:221], v[78:81]
	v_mfma_f32_16x16x32_bf16 v[82:85], v[194:197], v[210:213], v[82:85]
	v_mfma_f32_16x16x32_bf16 v[86:89], v[194:197], v[218:221], v[86:89]
	v_mfma_f32_16x16x32_bf16 v[90:93], v[202:205], v[210:213], v[90:93]
	v_mfma_f32_16x16x32_bf16 v[98:101], v[202:205], v[218:221], v[98:101]
	s_barrier
	s_cbranch_scc0 .LBB0_598
	s_setprio 0
	s_add_u32 s8, s8, 0x80f80
	s_addc_u32 s9, s9, 0
	v_add_u32_e32 v175, 0, v179
	v_add_u32_e32 v176, 0, v177
	s_mov_b32 m0, s88
	ds_read_b128 v[130:133], v175
	ds_read_b128 v[134:137], v175 offset:1024
	ds_read_b128 v[138:141], v175 offset:2048
	ds_read_b128 v[142:145], v175 offset:3072
	ds_read_b128 v[146:149], v176
	ds_read_b128 v[150:153], v176 offset:1024
	ds_read_b128 v[154:157], v176 offset:2048
	ds_read_b128 v[158:161], v176 offset:3072
	ds_read_b128 v[182:185], v176 offset:4096
	ds_read_b128 v[186:189], v176 offset:5120
	ds_read_b128 v[190:193], v176 offset:6144
	ds_read_b128 v[194:197], v176 offset:7168
	global_load_lds_dwordx4 v162, s[8:9]
	s_mov_b32 m0, s89
	s_nop 0
	global_load_lds_dwordx4 v174, s[8:9]
	s_waitcnt vmcnt(8)
	s_barrier
	s_waitcnt lgkmcnt(0)
	s_setprio 1
	s_waitcnt lgkmcnt(0)
	v_mfma_f32_16x16x32_bf16 v[126:129], v[146:149], v[130:133], v[126:129]
	v_mfma_f32_16x16x32_bf16 v[122:125], v[146:149], v[138:141], v[122:125]
	v_mfma_f32_16x16x32_bf16 v[114:117], v[154:157], v[138:141], v[114:117]
	v_mfma_f32_16x16x32_bf16 v[110:113], v[182:185], v[130:133], v[110:113]
	v_mfma_f32_16x16x32_bf16 v[126:129], v[150:153], v[134:137], v[126:129]
	v_mfma_f32_16x16x32_bf16 v[122:125], v[150:153], v[142:145], v[122:125]
	v_mfma_f32_16x16x32_bf16 v[118:121], v[154:157], v[130:133], v[118:121]
	v_mfma_f32_16x16x32_bf16 v[114:117], v[158:161], v[142:145], v[114:117]
	v_mfma_f32_16x16x32_bf16 v[110:113], v[186:189], v[134:137], v[110:113]
	v_mfma_f32_16x16x32_bf16 v[106:109], v[182:185], v[138:141], v[106:109]
	v_mfma_f32_16x16x32_bf16 v[102:105], v[190:193], v[130:133], v[102:105]
	v_mfma_f32_16x16x32_bf16 v[94:97], v[190:193], v[138:141], v[94:97]
	v_mfma_f32_16x16x32_bf16 v[118:121], v[158:161], v[134:137], v[118:121]
	v_mfma_f32_16x16x32_bf16 v[106:109], v[186:189], v[142:145], v[106:109]
	v_mfma_f32_16x16x32_bf16 v[102:105], v[194:197], v[134:137], v[102:105]
	v_mfma_f32_16x16x32_bf16 v[94:97], v[194:197], v[142:145], v[94:97]
	s_setprio 0
	s_barrier
	ds_read_b128 v[198:201], v175 offset:16384
	ds_read_b128 v[202:205], v175 offset:17408
	ds_read_b128 v[206:209], v175 offset:18432
	ds_read_b128 v[210:213], v175 offset:19456
	s_barrier
; #define LDA(dst, b, h)                                                                                     \
;   _Pragma("unroll") for (int m = 0; m < 4; ++m) _Pragma("unroll") for (int k = 0; k < 2; ++k) dst[m][k] = \
;       *reinterpret_cast<const bf16x8*>(shmc + aL + (((b) * 2 + (h)) * 16384 + (m * 2 + k) * 1024))
; #define LDB(dst, b, h)                                                                                     \
;   _Pragma("unroll") for (int n = 0; n < 2; ++n) _Pragma("unroll") for (int k = 0; k < 2; ++k) dst[n][k] = \
;       *reinterpret_cast<const bf16x8*>(shmc + bL + (((b) * 2 + (h)) * 16384 + (n * 2 + k) * 1024))
; #define WAIT_V(n) asm volatile("s_waitcnt vmcnt(" #n ")" ::: "memory")
; #define WAIT_L(n) asm volatile("s_waitcnt lgkmcnt(" #n ")" ::: "memory")
; #define BAR __builtin_amdgcn_s_barrier()
; template <int EPI>
; __device__ __forceinline__ void phase_gemm(const Params& p, const GemmDesc& d, char* shmc) {
;     ...
;       BAR; WAIT_L(0); MMA(0, 0, At, B0); BAR;
;       LDB(B1, 0, 1); BAR; WAIT_L(0); MMA(0, 1, At, B1); BAR;
;       LDA(At, 0, 1); WAIT_V(4); BAR; WAIT_L(0); MMA(1, 0, At, B0); MMA(1, 1, At, B1); BAR;
;     }
;     {
;       LDB(B0, 1, 0); LDA(At, 1, 0); WAIT_V(2); BAR; WAIT_L(0); MMA(0, 0, At, B0); BAR;
	s_waitcnt lgkmcnt(0)
	s_setprio 1
	s_waitcnt lgkmcnt(0)
	v_mfma_f32_16x16x32_bf16 v[50:53], v[146:149], v[198:201], v[50:53]
	v_mfma_f32_16x16x32_bf16 v[42:45], v[146:149], v[206:209], v[42:45]
	v_mfma_f32_16x16x32_bf16 v[38:41], v[154:157], v[198:201], v[38:41]
	v_mfma_f32_16x16x32_bf16 v[30:33], v[182:185], v[198:201], v[30:33]
	v_mfma_f32_16x16x32_bf16 v[22:25], v[190:193], v[198:201], v[22:25]
	v_mfma_f32_16x16x32_bf16 v[50:53], v[150:153], v[202:205], v[50:53]
	v_mfma_f32_16x16x32_bf16 v[42:45], v[150:153], v[210:213], v[42:45]
	v_mfma_f32_16x16x32_bf16 v[38:41], v[158:161], v[202:205], v[38:41]
	v_mfma_f32_16x16x32_bf16 v[34:37], v[154:157], v[206:209], v[34:37]
	v_mfma_f32_16x16x32_bf16 v[30:33], v[186:189], v[202:205], v[30:33]
	v_mfma_f32_16x16x32_bf16 v[26:29], v[182:185], v[206:209], v[26:29]
	v_mfma_f32_16x16x32_bf16 v[22:25], v[194:197], v[202:205], v[22:25]
	v_mfma_f32_16x16x32_bf16 v[18:21], v[190:193], v[206:209], v[18:21]
	v_mfma_f32_16x16x32_bf16 v[34:37], v[158:161], v[210:213], v[34:37]
	v_mfma_f32_16x16x32_bf16 v[26:29], v[186:189], v[210:213], v[26:29]
	v_mfma_f32_16x16x32_bf16 v[18:21], v[194:197], v[210:213], v[18:21]
	s_setprio 0
	s_barrier
	ds_read_b128 v[146:149], v176 offset:16384
	ds_read_b128 v[150:153], v176 offset:17408
	ds_read_b128 v[154:157], v176 offset:18432
	ds_read_b128 v[158:161], v176 offset:19456
	ds_read_b128 v[182:185], v176 offset:20480
	ds_read_b128 v[186:189], v176 offset:21504
	ds_read_b128 v[190:193], v176 offset:22528
	ds_read_b128 v[194:197], v176 offset:23552
	s_waitcnt vmcnt(4)
	s_barrier
	s_waitcnt lgkmcnt(0)
	s_setprio 1
	s_waitcnt lgkmcnt(0)
	v_mfma_f32_16x16x32_bf16 v[14:17], v[146:149], v[130:133], v[14:17]
	v_mfma_f32_16x16x32_bf16 v[6:9], v[154:157], v[130:133], v[6:9]
	v_mfma_f32_16x16x32_bf16 v[2:5], v[154:157], v[138:141], v[2:5]
	v_mfma_f32_16x16x32_bf16 v[46:49], v[182:185], v[130:133], v[46:49]
	v_mfma_f32_16x16x32_bf16 v[54:57], v[182:185], v[138:141], v[54:57]
	v_mfma_f32_16x16x32_bf16 v[58:61], v[190:193], v[130:133], v[58:61]
	v_mfma_f32_16x16x32_bf16 v[14:17], v[150:153], v[134:137], v[14:17]
	v_mfma_f32_16x16x32_bf16 v[10:13], v[146:149], v[138:141], v[10:13]
	v_mfma_f32_16x16x32_bf16 v[6:9], v[158:161], v[134:137], v[6:9]
	v_mfma_f32_16x16x32_bf16 v[2:5], v[158:161], v[142:145], v[2:5]
	v_mfma_f32_16x16x32_bf16 v[46:49], v[186:189], v[134:137], v[46:49]
	v_mfma_f32_16x16x32_bf16 v[54:57], v[186:189], v[142:145], v[54:57]
	v_mfma_f32_16x16x32_bf16 v[214:217], v[194:197], v[134:137], v[58:61]
	v_mfma_f32_16x16x32_bf16 v[58:61], v[190:193], v[138:141], v[62:65]
	v_mfma_f32_16x16x32_bf16 v[10:13], v[150:153], v[142:145], v[10:13]
	v_mfma_f32_16x16x32_bf16 v[218:221], v[194:197], v[142:145], v[58:61]
	s_setprio 0
	s_setprio 1
	v_mfma_f32_16x16x32_bf16 v[58:61], v[146:149], v[198:201], v[66:69]
	v_mfma_f32_16x16x32_bf16 v[222:225], v[150:153], v[202:205], v[58:61]
	v_mfma_f32_16x16x32_bf16 v[58:61], v[146:149], v[206:209], v[70:73]
	v_mfma_f32_16x16x32_bf16 v[226:229], v[150:153], v[210:213], v[58:61]
	v_mfma_f32_16x16x32_bf16 v[58:61], v[154:157], v[198:201], v[74:77]
	v_mfma_f32_16x16x32_bf16 v[230:233], v[158:161], v[202:205], v[58:61]
	v_mfma_f32_16x16x32_bf16 v[58:61], v[154:157], v[206:209], v[78:81]
	v_mfma_f32_16x16x32_bf16 v[234:237], v[158:161], v[210:213], v[58:61]
	v_mfma_f32_16x16x32_bf16 v[58:61], v[182:185], v[198:201], v[82:85]
	v_mfma_f32_16x16x32_bf16 v[238:241], v[186:189], v[202:205], v[58:61]
	v_mfma_f32_16x16x32_bf16 v[58:61], v[182:185], v[206:209], v[86:89]
	v_mfma_f32_16x16x32_bf16 v[182:185], v[186:189], v[210:213], v[58:61]
	v_mfma_f32_16x16x32_bf16 v[58:61], v[190:193], v[198:201], v[90:93]
	v_mfma_f32_16x16x32_bf16 v[186:189], v[194:197], v[202:205], v[58:61]
	v_mfma_f32_16x16x32_bf16 v[58:61], v[190:193], v[206:209], v[98:101]
	v_mfma_f32_16x16x32_bf16 v[190:193], v[194:197], v[210:213], v[58:61]
	s_setprio 0
	s_barrier
	ds_read_b128 v[66:69], v175 offset:32768
	ds_read_b128 v[194:197], v175 offset:33792
	ds_read_b128 v[198:201], v175 offset:34816
	ds_read_b128 v[202:205], v175 offset:35840
	s_nop 0
	ds_read_b128 v[58:61], v176 offset:32768
	ds_read_b128 v[62:65], v176 offset:33792
	ds_read_b128 v[70:73], v176 offset:34816
	ds_read_b128 v[74:77], v176 offset:35840
	ds_read_b128 v[78:81], v176 offset:36864
	ds_read_b128 v[82:85], v176 offset:37888
	ds_read_b128 v[206:209], v176 offset:38912
	ds_read_b128 v[210:213], v176 offset:39936
	s_waitcnt vmcnt(2)
	s_barrier
; #define LDA(dst, b, h)                                                                                     \
;   _Pragma("unroll") for (int m = 0; m < 4; ++m) _Pragma("unroll") for (int k = 0; k < 2; ++k) dst[m][k] = \
;       *reinterpret_cast<const bf16x8*>(shmc + aL + (((b) * 2 + (h)) * 16384 + (m * 2 + k) * 1024))
; #define LDB(dst, b, h)                                                                                     \
;   _Pragma("unroll") for (int n = 0; n < 2; ++n) _Pragma("unroll") for (int k = 0; k < 2; ++k) dst[n][k] = \
;       *reinterpret_cast<const bf16x8*>(shmc + bL + (((b) * 2 + (h)) * 16384 + (n * 2 + k) * 1024))
; #define WAIT_V(n) asm volatile("s_waitcnt vmcnt(" #n ")" ::: "memory")
; #define WAIT_L(n) asm volatile("s_waitcnt lgkmcnt(" #n ")" ::: "memory")
; #define BAR __builtin_amdgcn_s_barrier()
; template <int EPI>
; __device__ __forceinline__ void phase_gemm(const Params& p, const GemmDesc& d, char* shmc) {
;     ...
;       LDB(B0, 1, 0); LDA(At, 1, 0); WAIT_V(2); BAR; WAIT_L(0); MMA(0, 0, At, B0); BAR;
;       LDB(B1, 1, 1); WAIT_V(0); BAR; WAIT_L(0); MMA(0, 1, At, B1); BAR;
;       LDA(At, 1, 1); BAR; WAIT_L(0); MMA(1, 0, At, B0); MMA(1, 1, At, B1); BAR;
;     }
;     if (wr == 0) BAR;
	s_waitcnt lgkmcnt(0)
	s_setprio 1
	s_waitcnt lgkmcnt(0)
	v_mfma_f32_16x16x32_bf16 v[86:89], v[58:61], v[66:69], v[126:129]
	v_mfma_f32_16x16x32_bf16 v[158:161], v[62:65], v[194:197], v[86:89]
	v_mfma_f32_16x16x32_bf16 v[86:89], v[58:61], v[198:201], v[122:125]
	v_mfma_f32_16x16x32_bf16 v[142:145], v[62:65], v[202:205], v[86:89]
	v_mfma_f32_16x16x32_bf16 v[86:89], v[70:73], v[66:69], v[118:121]
	v_mfma_f32_16x16x32_bf16 v[154:157], v[74:77], v[194:197], v[86:89]
	v_mfma_f32_16x16x32_bf16 v[86:89], v[70:73], v[198:201], v[114:117]
	v_mfma_f32_16x16x32_bf16 v[138:141], v[74:77], v[202:205], v[86:89]
	v_mfma_f32_16x16x32_bf16 v[86:89], v[78:81], v[66:69], v[110:113]
	v_mfma_f32_16x16x32_bf16 v[150:153], v[82:85], v[194:197], v[86:89]
	v_mfma_f32_16x16x32_bf16 v[86:89], v[78:81], v[198:201], v[106:109]
	v_mfma_f32_16x16x32_bf16 v[134:137], v[82:85], v[202:205], v[86:89]
	v_mfma_f32_16x16x32_bf16 v[86:89], v[206:209], v[66:69], v[102:105]
	v_mfma_f32_16x16x32_bf16 v[146:149], v[210:213], v[194:197], v[86:89]
	v_mfma_f32_16x16x32_bf16 v[86:89], v[206:209], v[198:201], v[94:97]
	v_mfma_f32_16x16x32_bf16 v[130:133], v[210:213], v[202:205], v[86:89]
	s_setprio 0
	s_barrier
	ds_read_b128 v[94:97], v175 offset:49152
	ds_read_b128 v[102:105], v175 offset:50176
	ds_read_b128 v[106:109], v175 offset:51200
	ds_read_b128 v[118:121], v175 offset:52224
	s_waitcnt vmcnt(0)
	s_barrier
	s_waitcnt lgkmcnt(0)
	s_setprio 1
	s_waitcnt lgkmcnt(0)
	v_mfma_f32_16x16x32_bf16 v[50:53], v[58:61], v[94:97], v[50:53]
	v_mfma_f32_16x16x32_bf16 v[42:45], v[58:61], v[106:109], v[42:45]
	v_mfma_f32_16x16x32_bf16 v[38:41], v[70:73], v[94:97], v[38:41]
	v_mfma_f32_16x16x32_bf16 v[34:37], v[70:73], v[106:109], v[34:37]
	v_mfma_f32_16x16x32_bf16 v[30:33], v[78:81], v[94:97], v[30:33]
	v_mfma_f32_16x16x32_bf16 v[26:29], v[78:81], v[106:109], v[26:29]
	v_mfma_f32_16x16x32_bf16 v[22:25], v[206:209], v[94:97], v[22:25]
	v_mfma_f32_16x16x32_bf16 v[18:21], v[206:209], v[106:109], v[18:21]
	v_mfma_f32_16x16x32_bf16 v[126:129], v[62:65], v[102:105], v[50:53]
	v_mfma_f32_16x16x32_bf16 v[98:101], v[62:65], v[118:121], v[42:45]
	v_mfma_f32_16x16x32_bf16 v[122:125], v[74:77], v[102:105], v[38:41]
	v_mfma_f32_16x16x32_bf16 v[90:93], v[74:77], v[118:121], v[34:37]
	v_mfma_f32_16x16x32_bf16 v[114:117], v[82:85], v[102:105], v[30:33]
	v_mfma_f32_16x16x32_bf16 v[86:89], v[82:85], v[118:121], v[26:29]
	v_mfma_f32_16x16x32_bf16 v[110:113], v[210:213], v[102:105], v[22:25]
	v_mfma_f32_16x16x32_bf16 v[82:85], v[210:213], v[118:121], v[18:21]
	s_setprio 0
	s_barrier
	s_nop 0
	ds_read_b128 v[18:21], v176 offset:49152
	ds_read_b128 v[22:25], v176 offset:50176
	ds_read_b128 v[26:29], v176 offset:51200
	ds_read_b128 v[30:33], v176 offset:52224
	ds_read_b128 v[34:37], v176 offset:53248
	ds_read_b128 v[206:209], v176 offset:54272
	ds_read_b128 v[210:213], v176 offset:55296
	ds_read_b128 v[242:245], v176 offset:56320
	s_barrier
	s_waitcnt lgkmcnt(0)
	s_setprio 1
	s_waitcnt lgkmcnt(0)
	v_mfma_f32_16x16x32_bf16 v[2:5], v[26:29], v[198:201], v[2:5]
	v_mfma_f32_16x16x32_bf16 v[58:61], v[30:33], v[202:205], v[2:5]
	v_mfma_f32_16x16x32_bf16 v[2:5], v[34:37], v[66:69], v[46:49]
	v_mfma_f32_16x16x32_bf16 v[70:73], v[206:209], v[194:197], v[2:5]
	v_mfma_f32_16x16x32_bf16 v[2:5], v[34:37], v[198:201], v[54:57]
	v_mfma_f32_16x16x32_bf16 v[54:57], v[206:209], v[202:205], v[2:5]
	v_mfma_f32_16x16x32_bf16 v[2:5], v[210:213], v[66:69], v[214:217]
	v_mfma_f32_16x16x32_bf16 v[14:17], v[18:21], v[66:69], v[14:17]
	v_mfma_f32_16x16x32_bf16 v[10:13], v[18:21], v[198:201], v[10:13]
	v_mfma_f32_16x16x32_bf16 v[6:9], v[26:29], v[66:69], v[6:9]
	v_mfma_f32_16x16x32_bf16 v[66:69], v[242:245], v[194:197], v[2:5]
	v_mfma_f32_16x16x32_bf16 v[2:5], v[210:213], v[198:201], v[218:221]
	v_mfma_f32_16x16x32_bf16 v[78:81], v[22:25], v[194:197], v[14:17]
	v_mfma_f32_16x16x32_bf16 v[62:65], v[22:25], v[202:205], v[10:13]
	v_mfma_f32_16x16x32_bf16 v[74:77], v[30:33], v[194:197], v[6:9]
	v_mfma_f32_16x16x32_bf16 v[50:53], v[242:245], v[202:205], v[2:5]
	s_setprio 0
	s_setprio 1
	v_mfma_f32_16x16x32_bf16 v[2:5], v[18:21], v[94:97], v[222:225]
	v_mfma_f32_16x16x32_bf16 v[46:49], v[22:25], v[102:105], v[2:5]
	v_mfma_f32_16x16x32_bf16 v[2:5], v[18:21], v[106:109], v[226:229]
	v_mfma_f32_16x16x32_bf16 v[22:25], v[22:25], v[118:121], v[2:5]
	v_mfma_f32_16x16x32_bf16 v[2:5], v[26:29], v[94:97], v[230:233]
	v_mfma_f32_16x16x32_bf16 v[42:45], v[30:33], v[102:105], v[2:5]
	v_mfma_f32_16x16x32_bf16 v[2:5], v[26:29], v[106:109], v[234:237]
	v_mfma_f32_16x16x32_bf16 v[14:17], v[30:33], v[118:121], v[2:5]
	v_mfma_f32_16x16x32_bf16 v[2:5], v[34:37], v[94:97], v[238:241]
	v_mfma_f32_16x16x32_bf16 v[38:41], v[206:209], v[102:105], v[2:5]
	v_mfma_f32_16x16x32_bf16 v[2:5], v[34:37], v[106:109], v[182:185]
	v_mfma_f32_16x16x32_bf16 v[6:9], v[206:209], v[118:121], v[2:5]
	v_mfma_f32_16x16x32_bf16 v[2:5], v[210:213], v[94:97], v[186:189]
	v_mfma_f32_16x16x32_bf16 v[30:33], v[242:245], v[102:105], v[2:5]
	v_mfma_f32_16x16x32_bf16 v[2:5], v[210:213], v[106:109], v[190:193]
	v_mfma_f32_16x16x32_bf16 v[2:5], v[242:245], v[118:121], v[2:5]
	s_setprio 0
	s_barrier
	s_and_saveexec_b64 s[8:9], s[6:7]
	s_cbranch_execz .LBB0_601
	s_barrier

; #define LDA(dst, b, h)                                                                                     \
;   _Pragma("unroll") for (int m = 0; m < 4; ++m) _Pragma("unroll") for (int k = 0; k < 2; ++k) dst[m][k] = \
;       *reinterpret_cast<const bf16x8*>(shmc + aL + (((b) * 2 + (h)) * 16384 + (m * 2 + k) * 1024))
; #define LDB(dst, b, h)                                                                                     \
;   _Pragma("unroll") for (int n = 0; n < 2; ++n) _Pragma("unroll") for (int k = 0; k < 2; ++k) dst[n][k] = \
;       *reinterpret_cast<const bf16x8*>(shmc + bL + (((b) * 2 + (h)) * 16384 + (n * 2 + k) * 1024))
; #define OPAQ asm volatile("" : "+v"(aL), "+v"(bL))
; #define WAIT_V(n) asm volatile("s_waitcnt vmcnt(" #n ")" ::: "memory")
; #define WAIT_L(n) asm volatile("s_waitcnt lgkmcnt(" #n ")" ::: "memory")
; #define BAR __builtin_amdgcn_s_barrier()
; #define SCHED __builtin_amdgcn_sched_barrier(0)
; template <int EPI>
; __device__ __forceinline__ void phase_gemm(const Params& p, const GemmDesc& d, char* shmc) {
;     ...
;     for (int t = 0; t < nt - 2; t += 2) {
;       OPAQ;
;       LDB(B0, 0, 0); SCHED; LDA(At, 0, 0); STAGE_A(SA(1, 1), 1, t + 1);
;       WAIT_L(8); BAR; WAIT_L(0); MMA(0, 0, At, B0); BAR; SCHED;
;       LDB(B1, 0, 1); STAGE_B(SB(0, 0), 0, t + 2);
;       BAR; WAIT_L(0); MMA(0, 1, At, B1); BAR;
;       LDA(At, 0, 1); STAGE_A(SA(0, 0), 0, t + 2);
;       BAR; WAIT_L(0); MMA(1, 0, At, B0); BAR; SCHED;
;       STAGE_B(SB(0, 1), 1, t + 2);
;       WAIT_V(6); BAR; MMA(1, 1, At, B1); BAR;
;       LDB(B0, 1, 0); SCHED; LDA(At, 1, 0); STAGE_A(SA(0, 1), 1, t + 2);
;       WAIT_L(8); BAR; WAIT_L(0); MMA(0, 0, At, B0); BAR; SCHED;
;       LDB(B1, 1, 1); STAGE_B(SB(1, 0), 0, t + 3);
;       BAR; WAIT_L(0); MMA(0, 1, At, B1); BAR;
;       LDA(At, 1, 1); STAGE_A(SA(1, 0), 0, t + 3);
;       BAR; WAIT_L(0); MMA(1, 0, At, B0); BAR; SCHED;
;       STAGE_B(SB(1, 1), 1, t + 3);
;       WAIT_V(6); BAR; MMA(1, 1, At, B1); BAR;
;     }
.LBB0_1010:
	s_nop 0
	v_add_u32_e32 v130, 0, v153
	v_add_u32_e32 v141, 0, v152
	s_setprio 0
	ds_read_b128 v[156:159], v130
	ds_read_b128 v[160:163], v130 offset:1024
	ds_read_b128 v[164:167], v130 offset:2048
	ds_read_b128 v[168:171], v130 offset:3072
	ds_read_b128 v[204:207], v130 offset:16384
	ds_read_b128 v[208:211], v130 offset:17408
	ds_read_b128 v[212:215], v130 offset:18432
	ds_read_b128 v[216:219], v130 offset:19456
	v_lshl_add_u64 v[220:221], v[148:149], 0, s[58:59]
	v_lshl_add_u64 v[222:223], v[150:151], 0, s[58:59]
	v_lshl_add_u64 v[224:225], v[144:145], 0, s[58:59]
	v_lshl_add_u64 v[226:227], v[146:147], 0, s[58:59]
	ds_read_b128 v[172:175], v141
	ds_read_b128 v[176:179], v141 offset:1024
	ds_read_b128 v[180:183], v141 offset:2048
	ds_read_b128 v[184:187], v141 offset:3072
	ds_read_b128 v[188:191], v141 offset:4096
	ds_read_b128 v[192:195], v141 offset:5120
	ds_read_b128 v[196:199], v141 offset:6144
	ds_read_b128 v[200:203], v141 offset:7168
	s_mov_b32 m0, s80
	v_lshl_add_u64 v[228:229], v[220:221], 0, s[10:11]
	global_load_lds_dwordx4 v[228:229], off
	v_lshl_add_u64 v[228:229], v[222:223], 0, s[10:11]
	s_mov_b32 m0, s81
	s_nop 0
	global_load_lds_dwordx4 v[228:229], off
	s_waitcnt vmcnt(8)
	s_waitcnt lgkmcnt(0)
	s_setprio 1
	s_barrier
	v_mfma_f32_16x16x32_bf16 v[126:129], v[156:159], v[172:175], v[126:129]
	v_mfma_f32_16x16x32_bf16 v[122:125], v[164:167], v[172:175], v[122:125]
	v_mfma_f32_16x16x32_bf16 v[118:121], v[156:159], v[180:183], v[118:121]
	v_mfma_f32_16x16x32_bf16 v[114:117], v[164:167], v[180:183], v[114:117]
	v_mfma_f32_16x16x32_bf16 v[110:113], v[156:159], v[188:191], v[110:113]
	v_mfma_f32_16x16x32_bf16 v[106:109], v[164:167], v[188:191], v[106:109]
	v_mfma_f32_16x16x32_bf16 v[102:105], v[156:159], v[196:199], v[102:105]
	v_mfma_f32_16x16x32_bf16 v[98:101], v[164:167], v[196:199], v[98:101]
	v_mfma_f32_16x16x32_bf16 v[126:129], v[160:163], v[176:179], v[126:129]
	v_mfma_f32_16x16x32_bf16 v[122:125], v[168:171], v[176:179], v[122:125]
	v_mfma_f32_16x16x32_bf16 v[118:121], v[160:163], v[184:187], v[118:121]
	v_mfma_f32_16x16x32_bf16 v[114:117], v[168:171], v[184:187], v[114:117]
	v_mfma_f32_16x16x32_bf16 v[110:113], v[160:163], v[192:195], v[110:113]
	v_mfma_f32_16x16x32_bf16 v[106:109], v[168:171], v[192:195], v[106:109]
	v_mfma_f32_16x16x32_bf16 v[102:105], v[160:163], v[200:203], v[102:105]
	v_mfma_f32_16x16x32_bf16 v[98:101], v[168:171], v[200:203], v[98:101]
	v_mfma_f32_16x16x32_bf16 v[86:89], v[204:207], v[172:175], v[86:89]
	v_mfma_f32_16x16x32_bf16 v[70:73], v[212:215], v[172:175], v[70:73]
	v_mfma_f32_16x16x32_bf16 v[54:57], v[204:207], v[180:183], v[54:57]
	v_mfma_f32_16x16x32_bf16 v[50:53], v[212:215], v[180:183], v[50:53]
	v_mfma_f32_16x16x32_bf16 v[46:49], v[204:207], v[188:191], v[46:49]
	v_mfma_f32_16x16x32_bf16 v[42:45], v[212:215], v[188:191], v[42:45]
	v_mfma_f32_16x16x32_bf16 v[38:41], v[204:207], v[196:199], v[38:41]
	v_mfma_f32_16x16x32_bf16 v[34:37], v[212:215], v[196:199], v[34:37]
	v_mfma_f32_16x16x32_bf16 v[86:89], v[208:211], v[176:179], v[86:89]
	v_mfma_f32_16x16x32_bf16 v[70:73], v[216:219], v[176:179], v[70:73]
	v_mfma_f32_16x16x32_bf16 v[54:57], v[208:211], v[184:187], v[54:57]
	v_mfma_f32_16x16x32_bf16 v[50:53], v[216:219], v[184:187], v[50:53]
	v_mfma_f32_16x16x32_bf16 v[46:49], v[208:211], v[192:195], v[46:49]
	v_mfma_f32_16x16x32_bf16 v[42:45], v[216:219], v[192:195], v[42:45]
	v_mfma_f32_16x16x32_bf16 v[38:41], v[208:211], v[200:203], v[38:41]
	v_mfma_f32_16x16x32_bf16 v[34:37], v[216:219], v[200:203], v[34:37]
	s_barrier
	s_setprio 0
	ds_read_b128 v[172:175], v141 offset:16384
	ds_read_b128 v[176:179], v141 offset:17408
	ds_read_b128 v[180:183], v141 offset:18432
	ds_read_b128 v[184:187], v141 offset:19456
	ds_read_b128 v[188:191], v141 offset:20480
	ds_read_b128 v[192:195], v141 offset:21504
	ds_read_b128 v[196:199], v141 offset:22528
	ds_read_b128 v[200:203], v141 offset:23552
	s_mov_b32 m0, s35
	v_lshl_add_u64 v[228:229], v[224:225], 0, s[22:23]
	global_load_lds_dwordx4 v[228:229], off
	v_lshl_add_u64 v[228:229], v[226:227], 0, s[22:23]
	s_mov_b32 m0, s64
	s_nop 0
	global_load_lds_dwordx4 v[228:229], off
	s_mov_b32 m0, s34
	v_lshl_add_u64 v[228:229], v[220:221], 0, s[26:27]
	global_load_lds_dwordx4 v[228:229], off
	v_lshl_add_u64 v[228:229], v[222:223], 0, s[26:27]
	s_mov_b32 m0, s65
	s_nop 0
	global_load_lds_dwordx4 v[228:229], off
	s_mov_b32 m0, s66
	v_lshl_add_u64 v[228:229], v[224:225], 0, s[36:37]
	global_load_lds_dwordx4 v[228:229], off
	v_lshl_add_u64 v[228:229], v[226:227], 0, s[36:37]
	s_mov_b32 m0, s67
	s_nop 0
	global_load_lds_dwordx4 v[228:229], off
	s_waitcnt vmcnt(8)
	s_waitcnt lgkmcnt(0)
	s_setprio 1
	s_barrier
; #define LDA(dst, b, h)                                                                                     \
;   _Pragma("unroll") for (int m = 0; m < 4; ++m) _Pragma("unroll") for (int k = 0; k < 2; ++k) dst[m][k] = \
;       *reinterpret_cast<const bf16x8*>(shmc + aL + (((b) * 2 + (h)) * 16384 + (m * 2 + k) * 1024))
; #define LDB(dst, b, h)                                                                                     \
;   _Pragma("unroll") for (int n = 0; n < 2; ++n) _Pragma("unroll") for (int k = 0; k < 2; ++k) dst[n][k] = \
;       *reinterpret_cast<const bf16x8*>(shmc + bL + (((b) * 2 + (h)) * 16384 + (n * 2 + k) * 1024))
; #define OPAQ asm volatile("" : "+v"(aL), "+v"(bL))
; #define WAIT_V(n) asm volatile("s_waitcnt vmcnt(" #n ")" ::: "memory")
; #define WAIT_L(n) asm volatile("s_waitcnt lgkmcnt(" #n ")" ::: "memory")
; #define BAR __builtin_amdgcn_s_barrier()
; #define SCHED __builtin_amdgcn_sched_barrier(0)
; template <int EPI>
; __device__ __forceinline__ void phase_gemm(const Params& p, const GemmDesc& d, char* shmc) {
;     ...
;     for (int t = 0; t < nt - 2; t += 2) {
;       OPAQ;
;       LDB(B0, 0, 0); SCHED; LDA(At, 0, 0); STAGE_A(SA(1, 1), 1, t + 1);
;       WAIT_L(8); BAR; WAIT_L(0); MMA(0, 0, At, B0); BAR; SCHED;
;       LDB(B1, 0, 1); STAGE_B(SB(0, 0), 0, t + 2);
;       BAR; WAIT_L(0); MMA(0, 1, At, B1); BAR;
;       LDA(At, 0, 1); STAGE_A(SA(0, 0), 0, t + 2);
;       BAR; WAIT_L(0); MMA(1, 0, At, B0); BAR; SCHED;
;       STAGE_B(SB(0, 1), 1, t + 2);
;       WAIT_V(6); BAR; MMA(1, 1, At, B1); BAR;
;       LDB(B0, 1, 0); SCHED; LDA(At, 1, 0); STAGE_A(SA(0, 1), 1, t + 2);
;       WAIT_L(8); BAR; WAIT_L(0); MMA(0, 0, At, B0); BAR; SCHED;
;       LDB(B1, 1, 1); STAGE_B(SB(1, 0), 0, t + 3);
;       BAR; WAIT_L(0); MMA(0, 1, At, B1); BAR;
;       LDA(At, 1, 1); STAGE_A(SA(1, 0), 0, t + 3);
;       BAR; WAIT_L(0); MMA(1, 0, At, B0); BAR; SCHED;
;       STAGE_B(SB(1, 1), 1, t + 3);
;       WAIT_V(6); BAR; MMA(1, 1, At, B1); BAR;
;     }
	v_mfma_f32_16x16x32_bf16 v[30:33], v[156:159], v[172:175], v[30:33]
	v_mfma_f32_16x16x32_bf16 v[26:29], v[164:167], v[172:175], v[26:29]
	v_mfma_f32_16x16x32_bf16 v[22:25], v[156:159], v[180:183], v[22:25]
	v_mfma_f32_16x16x32_bf16 v[18:21], v[164:167], v[180:183], v[18:21]
	v_mfma_f32_16x16x32_bf16 v[14:17], v[156:159], v[188:191], v[14:17]
	v_mfma_f32_16x16x32_bf16 v[10:13], v[164:167], v[188:191], v[10:13]
	v_mfma_f32_16x16x32_bf16 v[6:9], v[156:159], v[196:199], v[6:9]
	v_mfma_f32_16x16x32_bf16 v[2:5], v[164:167], v[196:199], v[2:5]
	v_mfma_f32_16x16x32_bf16 v[30:33], v[160:163], v[176:179], v[30:33]
	v_mfma_f32_16x16x32_bf16 v[26:29], v[168:171], v[176:179], v[26:29]
	v_mfma_f32_16x16x32_bf16 v[22:25], v[160:163], v[184:187], v[22:25]
	v_mfma_f32_16x16x32_bf16 v[18:21], v[168:171], v[184:187], v[18:21]
	v_mfma_f32_16x16x32_bf16 v[14:17], v[160:163], v[192:195], v[14:17]
	v_mfma_f32_16x16x32_bf16 v[10:13], v[168:171], v[192:195], v[10:13]
	v_mfma_f32_16x16x32_bf16 v[6:9], v[160:163], v[200:203], v[6:9]
	v_mfma_f32_16x16x32_bf16 v[2:5], v[168:171], v[200:203], v[2:5]
	v_mfma_f32_16x16x32_bf16 v[58:61], v[204:207], v[172:175], v[58:61]
	v_mfma_f32_16x16x32_bf16 v[62:65], v[212:215], v[172:175], v[62:65]
	v_mfma_f32_16x16x32_bf16 v[66:69], v[204:207], v[180:183], v[66:69]
	v_mfma_f32_16x16x32_bf16 v[74:77], v[212:215], v[180:183], v[74:77]
	v_mfma_f32_16x16x32_bf16 v[78:81], v[204:207], v[188:191], v[78:81]
	v_mfma_f32_16x16x32_bf16 v[82:85], v[212:215], v[188:191], v[82:85]
	v_mfma_f32_16x16x32_bf16 v[90:93], v[204:207], v[196:199], v[90:93]
	v_mfma_f32_16x16x32_bf16 v[94:97], v[212:215], v[196:199], v[94:97]
	v_mfma_f32_16x16x32_bf16 v[58:61], v[208:211], v[176:179], v[58:61]
	v_mfma_f32_16x16x32_bf16 v[62:65], v[216:219], v[176:179], v[62:65]
	v_mfma_f32_16x16x32_bf16 v[66:69], v[208:211], v[184:187], v[66:69]
	v_mfma_f32_16x16x32_bf16 v[74:77], v[216:219], v[184:187], v[74:77]
	v_mfma_f32_16x16x32_bf16 v[78:81], v[208:211], v[192:195], v[78:81]
	v_mfma_f32_16x16x32_bf16 v[82:85], v[216:219], v[192:195], v[82:85]
	v_mfma_f32_16x16x32_bf16 v[90:93], v[208:211], v[200:203], v[90:93]
	v_mfma_f32_16x16x32_bf16 v[94:97], v[216:219], v[200:203], v[94:97]
	s_barrier
	s_setprio 0
	ds_read_b128 v[156:159], v130 offset:32768
	ds_read_b128 v[160:163], v130 offset:33792
	ds_read_b128 v[164:167], v130 offset:34816
	ds_read_b128 v[168:171], v130 offset:35840
	ds_read_b128 v[204:207], v130 offset:49152
	ds_read_b128 v[208:211], v130 offset:50176
	ds_read_b128 v[212:215], v130 offset:51200
	ds_read_b128 v[216:219], v130 offset:52224
	ds_read_b128 v[172:175], v141 offset:32768
	ds_read_b128 v[176:179], v141 offset:33792
	ds_read_b128 v[180:183], v141 offset:34816
	ds_read_b128 v[184:187], v141 offset:35840
	ds_read_b128 v[188:191], v141 offset:36864
	ds_read_b128 v[192:195], v141 offset:37888
	ds_read_b128 v[196:199], v141 offset:38912
	ds_read_b128 v[200:203], v141 offset:39936
	s_mov_b32 m0, s68
	v_lshl_add_u64 v[228:229], v[220:221], 0, s[38:39]
	global_load_lds_dwordx4 v[228:229], off
	v_lshl_add_u64 v[228:229], v[222:223], 0, s[38:39]
	s_mov_b32 m0, s69
	s_nop 0
	global_load_lds_dwordx4 v[228:229], off
	s_waitcnt vmcnt(8)
	s_waitcnt lgkmcnt(0)
	s_setprio 1
	s_barrier
	v_mfma_f32_16x16x32_bf16 v[126:129], v[156:159], v[172:175], v[126:129]
	v_mfma_f32_16x16x32_bf16 v[122:125], v[164:167], v[172:175], v[122:125]
	v_mfma_f32_16x16x32_bf16 v[118:121], v[156:159], v[180:183], v[118:121]
	v_mfma_f32_16x16x32_bf16 v[114:117], v[164:167], v[180:183], v[114:117]
	v_mfma_f32_16x16x32_bf16 v[110:113], v[156:159], v[188:191], v[110:113]
	v_mfma_f32_16x16x32_bf16 v[106:109], v[164:167], v[188:191], v[106:109]
	v_mfma_f32_16x16x32_bf16 v[102:105], v[156:159], v[196:199], v[102:105]
	v_mfma_f32_16x16x32_bf16 v[98:101], v[164:167], v[196:199], v[98:101]
	v_mfma_f32_16x16x32_bf16 v[126:129], v[160:163], v[176:179], v[126:129]
	v_mfma_f32_16x16x32_bf16 v[122:125], v[168:171], v[176:179], v[122:125]
	v_mfma_f32_16x16x32_bf16 v[118:121], v[160:163], v[184:187], v[118:121]
	v_mfma_f32_16x16x32_bf16 v[114:117], v[168:171], v[184:187], v[114:117]
	v_mfma_f32_16x16x32_bf16 v[110:113], v[160:163], v[192:195], v[110:113]
	v_mfma_f32_16x16x32_bf16 v[106:109], v[168:171], v[192:195], v[106:109]
	v_mfma_f32_16x16x32_bf16 v[102:105], v[160:163], v[200:203], v[102:105]
	v_mfma_f32_16x16x32_bf16 v[98:101], v[168:171], v[200:203], v[98:101]
	v_mfma_f32_16x16x32_bf16 v[86:89], v[204:207], v[172:175], v[86:89]
	v_mfma_f32_16x16x32_bf16 v[70:73], v[212:215], v[172:175], v[70:73]
	v_mfma_f32_16x16x32_bf16 v[54:57], v[204:207], v[180:183], v[54:57]
	v_mfma_f32_16x16x32_bf16 v[50:53], v[212:215], v[180:183], v[50:53]
	v_mfma_f32_16x16x32_bf16 v[46:49], v[204:207], v[188:191], v[46:49]
	v_mfma_f32_16x16x32_bf16 v[42:45], v[212:215], v[188:191], v[42:45]
	v_mfma_f32_16x16x32_bf16 v[38:41], v[204:207], v[196:199], v[38:41]
	v_mfma_f32_16x16x32_bf16 v[34:37], v[212:215], v[196:199], v[34:37]
	v_mfma_f32_16x16x32_bf16 v[86:89], v[208:211], v[176:179], v[86:89]
	v_mfma_f32_16x16x32_bf16 v[70:73], v[216:219], v[176:179], v[70:73]
	v_mfma_f32_16x16x32_bf16 v[54:57], v[208:211], v[184:187], v[54:57]
	v_mfma_f32_16x16x32_bf16 v[50:53], v[216:219], v[184:187], v[50:53]
	v_mfma_f32_16x16x32_bf16 v[46:49], v[208:211], v[192:195], v[46:49]
	v_mfma_f32_16x16x32_bf16 v[42:45], v[216:219], v[192:195], v[42:45]
	v_mfma_f32_16x16x32_bf16 v[38:41], v[208:211], v[200:203], v[38:41]
	v_mfma_f32_16x16x32_bf16 v[34:37], v[216:219], v[200:203], v[34:37]
	s_barrier
; #define LDA(dst, b, h)                                                                                     \
;   _Pragma("unroll") for (int m = 0; m < 4; ++m) _Pragma("unroll") for (int k = 0; k < 2; ++k) dst[m][k] = \
;       *reinterpret_cast<const bf16x8*>(shmc + aL + (((b) * 2 + (h)) * 16384 + (m * 2 + k) * 1024))
; #define LDB(dst, b, h)                                                                                     \
;   _Pragma("unroll") for (int n = 0; n < 2; ++n) _Pragma("unroll") for (int k = 0; k < 2; ++k) dst[n][k] = \
;       *reinterpret_cast<const bf16x8*>(shmc + bL + (((b) * 2 + (h)) * 16384 + (n * 2 + k) * 1024))
; #define OPAQ asm volatile("" : "+v"(aL), "+v"(bL))
; #define WAIT_V(n) asm volatile("s_waitcnt vmcnt(" #n ")" ::: "memory")
; #define WAIT_L(n) asm volatile("s_waitcnt lgkmcnt(" #n ")" ::: "memory")
; #define BAR __builtin_amdgcn_s_barrier()
; #define SCHED __builtin_amdgcn_sched_barrier(0)
; template <int EPI>
; __device__ __forceinline__ void phase_gemm(const Params& p, const GemmDesc& d, char* shmc) {
;     ...
;     for (int t = 0; t < nt - 2; t += 2) {
;       OPAQ;
;       LDB(B0, 0, 0); SCHED; LDA(At, 0, 0); STAGE_A(SA(1, 1), 1, t + 1);
;       WAIT_L(8); BAR; WAIT_L(0); MMA(0, 0, At, B0); BAR; SCHED;
;       LDB(B1, 0, 1); STAGE_B(SB(0, 0), 0, t + 2);
;       BAR; WAIT_L(0); MMA(0, 1, At, B1); BAR;
;       LDA(At, 0, 1); STAGE_A(SA(0, 0), 0, t + 2);
;       BAR; WAIT_L(0); MMA(1, 0, At, B0); BAR; SCHED;
;       STAGE_B(SB(0, 1), 1, t + 2);
;       WAIT_V(6); BAR; MMA(1, 1, At, B1); BAR;
;       LDB(B0, 1, 0); SCHED; LDA(At, 1, 0); STAGE_A(SA(0, 1), 1, t + 2);
;       WAIT_L(8); BAR; WAIT_L(0); MMA(0, 0, At, B0); BAR; SCHED;
;       LDB(B1, 1, 1); STAGE_B(SB(1, 0), 0, t + 3);
;       BAR; WAIT_L(0); MMA(0, 1, At, B1); BAR;
;       LDA(At, 1, 1); STAGE_A(SA(1, 0), 0, t + 3);
;       BAR; WAIT_L(0); MMA(1, 0, At, B0); BAR; SCHED;
;       STAGE_B(SB(1, 1), 1, t + 3);
;       WAIT_V(6); BAR; MMA(1, 1, At, B1); BAR;
;     }
;     {
;       OPAQ;
;       LDB(B0, 0, 0); LDA(At, 0, 0); STAGE_A(SA(1, 1), 1, nt - 1);
;       BAR; WAIT_L(0); MMA(0, 0, At, B0); BAR;
;       LDB(B1, 0, 1); BAR; WAIT_L(0); MMA(0, 1, At, B1); BAR;
;       LDA(At, 0, 1); WAIT_V(4); BAR; WAIT_L(0); MMA(1, 0, At, B0); MMA(1, 1, At, B1); BAR;
	s_setprio 0
	ds_read_b128 v[172:175], v141 offset:49152
	ds_read_b128 v[176:179], v141 offset:50176
	ds_read_b128 v[180:183], v141 offset:51200
	ds_read_b128 v[184:187], v141 offset:52224
	ds_read_b128 v[188:191], v141 offset:53248
	ds_read_b128 v[192:195], v141 offset:54272
	ds_read_b128 v[196:199], v141 offset:55296
	ds_read_b128 v[200:203], v141 offset:56320
	s_mov_b32 m0, s70
	v_lshl_add_u64 v[228:229], v[224:225], 0, s[40:41]
	global_load_lds_dwordx4 v[228:229], off
	v_lshl_add_u64 v[228:229], v[226:227], 0, s[40:41]
	s_mov_b32 m0, s71
	s_nop 0
	global_load_lds_dwordx4 v[228:229], off
	s_mov_b32 m0, s76
	v_lshl_add_u64 v[228:229], v[220:221], 0, s[42:43]
	global_load_lds_dwordx4 v[228:229], off
	v_lshl_add_u64 v[228:229], v[222:223], 0, s[42:43]
	s_mov_b32 m0, s77
	s_nop 0
	global_load_lds_dwordx4 v[228:229], off
	s_mov_b32 m0, s78
	v_lshl_add_u64 v[228:229], v[224:225], 0, s[48:49]
	global_load_lds_dwordx4 v[228:229], off
	v_lshl_add_u64 v[228:229], v[226:227], 0, s[48:49]
	s_mov_b32 m0, s79
	s_nop 0
	global_load_lds_dwordx4 v[228:229], off
	s_add_i32 s53, s53, 2
	s_add_u32 s58, s58, 0x100
	s_addc_u32 s59, s59, 0
	s_cmp_gt_u32 s53, 27
	s_waitcnt vmcnt(8)
	s_waitcnt lgkmcnt(0)
	s_setprio 1
	s_barrier
	v_mfma_f32_16x16x32_bf16 v[30:33], v[156:159], v[172:175], v[30:33]
	v_mfma_f32_16x16x32_bf16 v[26:29], v[164:167], v[172:175], v[26:29]
	v_mfma_f32_16x16x32_bf16 v[22:25], v[156:159], v[180:183], v[22:25]
	v_mfma_f32_16x16x32_bf16 v[18:21], v[164:167], v[180:183], v[18:21]
	v_mfma_f32_16x16x32_bf16 v[14:17], v[156:159], v[188:191], v[14:17]
	v_mfma_f32_16x16x32_bf16 v[10:13], v[164:167], v[188:191], v[10:13]
	v_mfma_f32_16x16x32_bf16 v[6:9], v[156:159], v[196:199], v[6:9]
	v_mfma_f32_16x16x32_bf16 v[2:5], v[164:167], v[196:199], v[2:5]
	v_mfma_f32_16x16x32_bf16 v[30:33], v[160:163], v[176:179], v[30:33]
	v_mfma_f32_16x16x32_bf16 v[26:29], v[168:171], v[176:179], v[26:29]
	v_mfma_f32_16x16x32_bf16 v[22:25], v[160:163], v[184:187], v[22:25]
	v_mfma_f32_16x16x32_bf16 v[18:21], v[168:171], v[184:187], v[18:21]
	v_mfma_f32_16x16x32_bf16 v[14:17], v[160:163], v[192:195], v[14:17]
	v_mfma_f32_16x16x32_bf16 v[10:13], v[168:171], v[192:195], v[10:13]
	v_mfma_f32_16x16x32_bf16 v[6:9], v[160:163], v[200:203], v[6:9]
	v_mfma_f32_16x16x32_bf16 v[2:5], v[168:171], v[200:203], v[2:5]
	v_mfma_f32_16x16x32_bf16 v[58:61], v[204:207], v[172:175], v[58:61]
	v_mfma_f32_16x16x32_bf16 v[62:65], v[212:215], v[172:175], v[62:65]
	v_mfma_f32_16x16x32_bf16 v[66:69], v[204:207], v[180:183], v[66:69]
	v_mfma_f32_16x16x32_bf16 v[74:77], v[212:215], v[180:183], v[74:77]
	v_mfma_f32_16x16x32_bf16 v[78:81], v[204:207], v[188:191], v[78:81]
	v_mfma_f32_16x16x32_bf16 v[82:85], v[212:215], v[188:191], v[82:85]
	v_mfma_f32_16x16x32_bf16 v[90:93], v[204:207], v[196:199], v[90:93]
	v_mfma_f32_16x16x32_bf16 v[94:97], v[212:215], v[196:199], v[94:97]
	v_mfma_f32_16x16x32_bf16 v[58:61], v[208:211], v[176:179], v[58:61]
	v_mfma_f32_16x16x32_bf16 v[62:65], v[216:219], v[176:179], v[62:65]
	v_mfma_f32_16x16x32_bf16 v[66:69], v[208:211], v[184:187], v[66:69]
	v_mfma_f32_16x16x32_bf16 v[74:77], v[216:219], v[184:187], v[74:77]
	v_mfma_f32_16x16x32_bf16 v[78:81], v[208:211], v[192:195], v[78:81]
	v_mfma_f32_16x16x32_bf16 v[82:85], v[216:219], v[192:195], v[82:85]
	v_mfma_f32_16x16x32_bf16 v[90:93], v[208:211], v[200:203], v[90:93]
	v_mfma_f32_16x16x32_bf16 v[94:97], v[216:219], v[200:203], v[94:97]
	s_barrier
	s_cbranch_scc0 .LBB0_1010
	s_setprio 0
	s_add_u32 s56, s56, 0x80f80
	s_addc_u32 s57, s57, 0
	v_add_u32_e32 v130, 0, v153
	v_add_u32_e32 v141, 0, v152
	s_mov_b32 m0, s80
	ds_read_b128 v[144:147], v130
	ds_read_b128 v[148:151], v130 offset:1024
	ds_read_b128 v[156:159], v130 offset:2048
	ds_read_b128 v[160:163], v130 offset:3072
	ds_read_b128 v[164:167], v141
	ds_read_b128 v[168:171], v141 offset:1024
	ds_read_b128 v[172:175], v141 offset:2048
	ds_read_b128 v[176:179], v141 offset:3072
	ds_read_b128 v[180:183], v141 offset:4096
	ds_read_b128 v[184:187], v141 offset:5120
	ds_read_b128 v[188:191], v141 offset:6144
	ds_read_b128 v[192:195], v141 offset:7168
	global_load_lds_dwordx4 v140, s[56:57]
	s_mov_b32 m0, s81
	s_nop 0
	global_load_lds_dwordx4 v142, s[56:57]
	s_waitcnt vmcnt(8)
	s_barrier
	s_waitcnt lgkmcnt(0)
	s_setprio 1
	s_waitcnt lgkmcnt(0)
	v_mfma_f32_16x16x32_bf16 v[126:129], v[144:147], v[164:167], v[126:129]
	v_mfma_f32_16x16x32_bf16 v[122:125], v[156:159], v[164:167], v[122:125]
	v_mfma_f32_16x16x32_bf16 v[114:117], v[156:159], v[172:175], v[114:117]
	v_mfma_f32_16x16x32_bf16 v[110:113], v[144:147], v[180:183], v[110:113]
	v_mfma_f32_16x16x32_bf16 v[102:105], v[144:147], v[188:191], v[102:105]
	v_mfma_f32_16x16x32_bf16 v[126:129], v[148:151], v[168:171], v[126:129]
	v_mfma_f32_16x16x32_bf16 v[122:125], v[160:163], v[168:171], v[122:125]
	v_mfma_f32_16x16x32_bf16 v[118:121], v[144:147], v[172:175], v[118:121]
	v_mfma_f32_16x16x32_bf16 v[114:117], v[160:163], v[176:179], v[114:117]
	v_mfma_f32_16x16x32_bf16 v[110:113], v[148:151], v[184:187], v[110:113]
	v_mfma_f32_16x16x32_bf16 v[106:109], v[156:159], v[180:183], v[106:109]
	v_mfma_f32_16x16x32_bf16 v[102:105], v[148:151], v[192:195], v[102:105]
	v_mfma_f32_16x16x32_bf16 v[98:101], v[156:159], v[188:191], v[98:101]
	v_mfma_f32_16x16x32_bf16 v[196:199], v[148:151], v[176:179], v[118:121]
	v_mfma_f32_16x16x32_bf16 v[200:203], v[160:163], v[184:187], v[106:109]
	v_mfma_f32_16x16x32_bf16 v[204:207], v[160:163], v[192:195], v[98:101]
	s_setprio 0
	s_barrier
	s_nop 2
	ds_read_b128 v[98:101], v130 offset:16384
	ds_read_b128 v[106:109], v130 offset:17408
	ds_read_b128 v[118:121], v130 offset:18432
	ds_read_b128 v[208:211], v130 offset:19456
	s_barrier
; #define LDA(dst, b, h)                                                                                     \
;   _Pragma("unroll") for (int m = 0; m < 4; ++m) _Pragma("unroll") for (int k = 0; k < 2; ++k) dst[m][k] = \
;       *reinterpret_cast<const bf16x8*>(shmc + aL + (((b) * 2 + (h)) * 16384 + (m * 2 + k) * 1024))
; #define LDB(dst, b, h)                                                                                     \
;   _Pragma("unroll") for (int n = 0; n < 2; ++n) _Pragma("unroll") for (int k = 0; k < 2; ++k) dst[n][k] = \
;       *reinterpret_cast<const bf16x8*>(shmc + bL + (((b) * 2 + (h)) * 16384 + (n * 2 + k) * 1024))
; #define WAIT_V(n) asm volatile("s_waitcnt vmcnt(" #n ")" ::: "memory")
; #define WAIT_L(n) asm volatile("s_waitcnt lgkmcnt(" #n ")" ::: "memory")
; #define BAR __builtin_amdgcn_s_barrier()
; template <int EPI>
; __device__ __forceinline__ void phase_gemm(const Params& p, const GemmDesc& d, char* shmc) {
;     ...
;       BAR; WAIT_L(0); MMA(0, 0, At, B0); BAR;
;       LDB(B1, 0, 1); BAR; WAIT_L(0); MMA(0, 1, At, B1); BAR;
;       LDA(At, 0, 1); WAIT_V(4); BAR; WAIT_L(0); MMA(1, 0, At, B0); MMA(1, 1, At, B1); BAR;
;     }
;     {
;       LDB(B0, 1, 0); LDA(At, 1, 0); WAIT_V(2); BAR; WAIT_L(0); MMA(0, 0, At, B0); BAR;
	s_waitcnt lgkmcnt(0)
	s_setprio 1
	s_waitcnt lgkmcnt(0)
	v_mfma_f32_16x16x32_bf16 v[86:89], v[98:101], v[164:167], v[86:89]
	v_mfma_f32_16x16x32_bf16 v[70:73], v[118:121], v[164:167], v[70:73]
	v_mfma_f32_16x16x32_bf16 v[54:57], v[98:101], v[172:175], v[54:57]
	v_mfma_f32_16x16x32_bf16 v[50:53], v[118:121], v[172:175], v[50:53]
	v_mfma_f32_16x16x32_bf16 v[46:49], v[98:101], v[180:183], v[46:49]
	v_mfma_f32_16x16x32_bf16 v[42:45], v[118:121], v[180:183], v[42:45]
	v_mfma_f32_16x16x32_bf16 v[38:41], v[98:101], v[188:191], v[38:41]
	v_mfma_f32_16x16x32_bf16 v[34:37], v[118:121], v[188:191], v[34:37]
	v_mfma_f32_16x16x32_bf16 v[86:89], v[106:109], v[168:171], v[86:89]
	v_mfma_f32_16x16x32_bf16 v[70:73], v[208:211], v[168:171], v[70:73]
	v_mfma_f32_16x16x32_bf16 v[54:57], v[106:109], v[176:179], v[54:57]
	v_mfma_f32_16x16x32_bf16 v[50:53], v[208:211], v[176:179], v[50:53]
	v_mfma_f32_16x16x32_bf16 v[46:49], v[106:109], v[184:187], v[46:49]
	v_mfma_f32_16x16x32_bf16 v[42:45], v[208:211], v[184:187], v[42:45]
	v_mfma_f32_16x16x32_bf16 v[38:41], v[106:109], v[192:195], v[38:41]
	v_mfma_f32_16x16x32_bf16 v[34:37], v[208:211], v[192:195], v[34:37]
	s_setprio 0
	s_barrier
	ds_read_b128 v[164:167], v141 offset:16384
	ds_read_b128 v[168:171], v141 offset:17408
	ds_read_b128 v[172:175], v141 offset:18432
	ds_read_b128 v[176:179], v141 offset:19456
	ds_read_b128 v[180:183], v141 offset:20480
	ds_read_b128 v[184:187], v141 offset:21504
	ds_read_b128 v[188:191], v141 offset:22528
	ds_read_b128 v[192:195], v141 offset:23552
	s_waitcnt vmcnt(4)
	s_barrier
	s_waitcnt lgkmcnt(0)
	s_setprio 1
	s_waitcnt lgkmcnt(0)
	v_mfma_f32_16x16x32_bf16 v[30:33], v[144:147], v[164:167], v[30:33]
	v_mfma_f32_16x16x32_bf16 v[26:29], v[156:159], v[164:167], v[26:29]
	v_mfma_f32_16x16x32_bf16 v[22:25], v[144:147], v[172:175], v[22:25]
	v_mfma_f32_16x16x32_bf16 v[18:21], v[156:159], v[172:175], v[18:21]
	v_mfma_f32_16x16x32_bf16 v[14:17], v[144:147], v[180:183], v[14:17]
	v_mfma_f32_16x16x32_bf16 v[10:13], v[156:159], v[180:183], v[10:13]
	v_mfma_f32_16x16x32_bf16 v[6:9], v[144:147], v[188:191], v[6:9]
	v_mfma_f32_16x16x32_bf16 v[2:5], v[156:159], v[188:191], v[2:5]
	v_mfma_f32_16x16x32_bf16 v[30:33], v[148:151], v[168:171], v[30:33]
	v_mfma_f32_16x16x32_bf16 v[26:29], v[160:163], v[168:171], v[26:29]
	v_mfma_f32_16x16x32_bf16 v[22:25], v[148:151], v[176:179], v[22:25]
	v_mfma_f32_16x16x32_bf16 v[18:21], v[160:163], v[176:179], v[18:21]
	v_mfma_f32_16x16x32_bf16 v[14:17], v[148:151], v[184:187], v[14:17]
	v_mfma_f32_16x16x32_bf16 v[10:13], v[160:163], v[184:187], v[10:13]
	v_mfma_f32_16x16x32_bf16 v[6:9], v[148:151], v[192:195], v[6:9]
	v_mfma_f32_16x16x32_bf16 v[2:5], v[160:163], v[192:195], v[2:5]
	s_setprio 0
	s_setprio 1
	v_mfma_f32_16x16x32_bf16 v[62:65], v[118:121], v[164:167], v[62:65]
	v_mfma_f32_16x16x32_bf16 v[144:147], v[208:211], v[168:171], v[62:65]
	v_mfma_f32_16x16x32_bf16 v[62:65], v[98:101], v[172:175], v[66:69]
	v_mfma_f32_16x16x32_bf16 v[148:151], v[106:109], v[176:179], v[62:65]
	v_mfma_f32_16x16x32_bf16 v[62:65], v[118:121], v[172:175], v[74:77]
	v_mfma_f32_16x16x32_bf16 v[156:159], v[208:211], v[176:179], v[62:65]
	v_mfma_f32_16x16x32_bf16 v[62:65], v[98:101], v[180:183], v[78:81]
	v_mfma_f32_16x16x32_bf16 v[160:163], v[106:109], v[184:187], v[62:65]
	v_mfma_f32_16x16x32_bf16 v[62:65], v[118:121], v[180:183], v[82:85]
	v_mfma_f32_16x16x32_bf16 v[58:61], v[98:101], v[164:167], v[58:61]
	v_mfma_f32_16x16x32_bf16 v[164:167], v[208:211], v[184:187], v[62:65]
	v_mfma_f32_16x16x32_bf16 v[62:65], v[98:101], v[188:191], v[90:93]
	v_mfma_f32_16x16x32_bf16 v[58:61], v[106:109], v[168:171], v[58:61]
	v_mfma_f32_16x16x32_bf16 v[168:171], v[106:109], v[192:195], v[62:65]
	v_mfma_f32_16x16x32_bf16 v[62:65], v[118:121], v[188:191], v[94:97]
	v_mfma_f32_16x16x32_bf16 v[172:175], v[208:211], v[192:195], v[62:65]
	s_setprio 0
	s_barrier
	ds_read_b128 v[176:179], v130 offset:32768
	ds_read_b128 v[180:183], v130 offset:33792
	ds_read_b128 v[184:187], v130 offset:34816
	ds_read_b128 v[188:191], v130 offset:35840
	s_nop 0
	ds_read_b128 v[62:65], v141 offset:32768
	ds_read_b128 v[78:81], v141 offset:33792
	ds_read_b128 v[94:97], v141 offset:34816
	ds_read_b128 v[192:195], v141 offset:35840
	ds_read_b128 v[208:211], v141 offset:36864
	ds_read_b128 v[212:215], v141 offset:37888
	ds_read_b128 v[216:219], v141 offset:38912
	ds_read_b128 v[220:223], v141 offset:39936
	s_waitcnt vmcnt(2)
	s_barrier
; #define LDA(dst, b, h)                                                                                     \
;   _Pragma("unroll") for (int m = 0; m < 4; ++m) _Pragma("unroll") for (int k = 0; k < 2; ++k) dst[m][k] = \
;       *reinterpret_cast<const bf16x8*>(shmc + aL + (((b) * 2 + (h)) * 16384 + (m * 2 + k) * 1024))
; #define LDB(dst, b, h)                                                                                     \
;   _Pragma("unroll") for (int n = 0; n < 2; ++n) _Pragma("unroll") for (int k = 0; k < 2; ++k) dst[n][k] = \
;       *reinterpret_cast<const bf16x8*>(shmc + bL + (((b) * 2 + (h)) * 16384 + (n * 2 + k) * 1024))
; #define WAIT_V(n) asm volatile("s_waitcnt vmcnt(" #n ")" ::: "memory")
; #define WAIT_L(n) asm volatile("s_waitcnt lgkmcnt(" #n ")" ::: "memory")
; #define BAR __builtin_amdgcn_s_barrier()
; template <int EPI>
; __device__ __forceinline__ void phase_gemm(const Params& p, const GemmDesc& d, char* shmc) {
;     ...
;       LDB(B0, 1, 0); LDA(At, 1, 0); WAIT_V(2); BAR; WAIT_L(0); MMA(0, 0, At, B0); BAR;
;       LDB(B1, 1, 1); WAIT_V(0); BAR; WAIT_L(0); MMA(0, 1, At, B1); BAR;
;       LDA(At, 1, 1); BAR; WAIT_L(0); MMA(1, 0, At, B0); MMA(1, 1, At, B1); BAR;
;     }
;     if (wr == 0) BAR;
	s_waitcnt lgkmcnt(0)
	s_setprio 1
	s_waitcnt lgkmcnt(0)
	v_mfma_f32_16x16x32_bf16 v[66:69], v[176:179], v[62:65], v[126:129]
	v_mfma_f32_16x16x32_bf16 v[126:129], v[180:183], v[78:81], v[66:69]
	v_mfma_f32_16x16x32_bf16 v[66:69], v[184:187], v[62:65], v[122:125]
	v_mfma_f32_16x16x32_bf16 v[118:121], v[188:191], v[78:81], v[66:69]
	v_mfma_f32_16x16x32_bf16 v[66:69], v[176:179], v[94:97], v[196:199]
	v_mfma_f32_16x16x32_bf16 v[106:109], v[180:183], v[192:195], v[66:69]
	v_mfma_f32_16x16x32_bf16 v[66:69], v[184:187], v[94:97], v[114:117]
	v_mfma_f32_16x16x32_bf16 v[98:101], v[188:191], v[192:195], v[66:69]
	v_mfma_f32_16x16x32_bf16 v[66:69], v[176:179], v[208:211], v[110:113]
	v_mfma_f32_16x16x32_bf16 v[90:93], v[180:183], v[212:215], v[66:69]
	v_mfma_f32_16x16x32_bf16 v[66:69], v[184:187], v[208:211], v[200:203]
	v_mfma_f32_16x16x32_bf16 v[82:85], v[188:191], v[212:215], v[66:69]
	v_mfma_f32_16x16x32_bf16 v[66:69], v[176:179], v[216:219], v[102:105]
	v_mfma_f32_16x16x32_bf16 v[74:77], v[180:183], v[220:223], v[66:69]
	v_mfma_f32_16x16x32_bf16 v[66:69], v[184:187], v[216:219], v[204:207]
	v_mfma_f32_16x16x32_bf16 v[66:69], v[188:191], v[220:223], v[66:69]
	s_setprio 0
	s_barrier
	ds_read_b128 v[196:199], v130 offset:49152
	ds_read_b128 v[200:203], v130 offset:50176
	ds_read_b128 v[204:207], v130 offset:51200
	ds_read_b128 v[224:227], v130 offset:52224
	s_waitcnt vmcnt(0)
	s_barrier
	s_waitcnt lgkmcnt(0)
	s_setprio 1
	s_waitcnt lgkmcnt(0)
	v_mfma_f32_16x16x32_bf16 v[86:89], v[196:199], v[62:65], v[86:89]
	v_mfma_f32_16x16x32_bf16 v[62:65], v[204:207], v[62:65], v[70:73]
	v_mfma_f32_16x16x32_bf16 v[54:57], v[196:199], v[94:97], v[54:57]
	v_mfma_f32_16x16x32_bf16 v[50:53], v[204:207], v[94:97], v[50:53]
	v_mfma_f32_16x16x32_bf16 v[46:49], v[196:199], v[208:211], v[46:49]
	v_mfma_f32_16x16x32_bf16 v[42:45], v[204:207], v[208:211], v[42:45]
	v_mfma_f32_16x16x32_bf16 v[38:41], v[196:199], v[216:219], v[38:41]
	v_mfma_f32_16x16x32_bf16 v[34:37], v[204:207], v[216:219], v[34:37]
	v_mfma_f32_16x16x32_bf16 v[122:125], v[200:203], v[78:81], v[86:89]
	v_mfma_f32_16x16x32_bf16 v[114:117], v[224:227], v[78:81], v[62:65]
	v_mfma_f32_16x16x32_bf16 v[110:113], v[200:203], v[192:195], v[54:57]
	v_mfma_f32_16x16x32_bf16 v[102:105], v[224:227], v[192:195], v[50:53]
	v_mfma_f32_16x16x32_bf16 v[94:97], v[200:203], v[212:215], v[46:49]
	v_mfma_f32_16x16x32_bf16 v[86:89], v[224:227], v[212:215], v[42:45]
	v_mfma_f32_16x16x32_bf16 v[78:81], v[200:203], v[220:223], v[38:41]
	v_mfma_f32_16x16x32_bf16 v[70:73], v[224:227], v[220:223], v[34:37]
	s_setprio 0
	s_barrier
	s_nop 0
	ds_read_b128 v[34:37], v141 offset:49152
	ds_read_b128 v[42:45], v141 offset:50176
	ds_read_b128 v[192:195], v141 offset:51200
	ds_read_b128 v[208:211], v141 offset:52224
	ds_read_b128 v[212:215], v141 offset:53248
	ds_read_b128 v[216:219], v141 offset:54272
	ds_read_b128 v[220:223], v141 offset:55296
	ds_read_b128 v[228:231], v141 offset:56320
	s_barrier
	s_waitcnt lgkmcnt(0)
	s_setprio 1
	s_waitcnt lgkmcnt(0)
	v_mfma_f32_16x16x32_bf16 v[30:33], v[176:179], v[34:37], v[30:33]
	v_mfma_f32_16x16x32_bf16 v[26:29], v[184:187], v[34:37], v[26:29]
	v_mfma_f32_16x16x32_bf16 v[22:25], v[176:179], v[192:195], v[22:25]
	v_mfma_f32_16x16x32_bf16 v[18:21], v[184:187], v[192:195], v[18:21]
	v_mfma_f32_16x16x32_bf16 v[14:17], v[176:179], v[212:215], v[14:17]
	v_mfma_f32_16x16x32_bf16 v[10:13], v[184:187], v[212:215], v[10:13]
	v_mfma_f32_16x16x32_bf16 v[6:9], v[176:179], v[220:223], v[6:9]
	v_mfma_f32_16x16x32_bf16 v[2:5], v[184:187], v[220:223], v[2:5]
	v_mfma_f32_16x16x32_bf16 v[62:65], v[180:183], v[42:45], v[30:33]
	v_mfma_f32_16x16x32_bf16 v[54:57], v[188:191], v[42:45], v[26:29]
	v_mfma_f32_16x16x32_bf16 v[46:49], v[180:183], v[208:211], v[22:25]
	v_mfma_f32_16x16x32_bf16 v[38:41], v[188:191], v[208:211], v[18:21]
	v_mfma_f32_16x16x32_bf16 v[30:33], v[180:183], v[216:219], v[14:17]
	v_mfma_f32_16x16x32_bf16 v[22:25], v[188:191], v[216:219], v[10:13]
	v_mfma_f32_16x16x32_bf16 v[14:17], v[180:183], v[228:231], v[6:9]
	v_mfma_f32_16x16x32_bf16 v[6:9], v[188:191], v[228:231], v[2:5]
	s_setprio 0
	s_setprio 1
	v_mfma_f32_16x16x32_bf16 v[2:5], v[196:199], v[34:37], v[58:61]
	v_mfma_f32_16x16x32_bf16 v[58:61], v[200:203], v[42:45], v[2:5]
	v_mfma_f32_16x16x32_bf16 v[2:5], v[204:207], v[34:37], v[144:147]
	v_mfma_f32_16x16x32_bf16 v[50:53], v[224:227], v[42:45], v[2:5]
	v_mfma_f32_16x16x32_bf16 v[2:5], v[196:199], v[192:195], v[148:151]
	v_mfma_f32_16x16x32_bf16 v[42:45], v[200:203], v[208:211], v[2:5]
	v_mfma_f32_16x16x32_bf16 v[2:5], v[204:207], v[192:195], v[156:159]
	v_mfma_f32_16x16x32_bf16 v[34:37], v[224:227], v[208:211], v[2:5]
	v_mfma_f32_16x16x32_bf16 v[2:5], v[196:199], v[212:215], v[160:163]
	v_mfma_f32_16x16x32_bf16 v[26:29], v[200:203], v[216:219], v[2:5]
	v_mfma_f32_16x16x32_bf16 v[2:5], v[204:207], v[212:215], v[164:167]
	v_mfma_f32_16x16x32_bf16 v[18:21], v[224:227], v[216:219], v[2:5]
	v_mfma_f32_16x16x32_bf16 v[2:5], v[196:199], v[220:223], v[168:171]
	v_mfma_f32_16x16x32_bf16 v[10:13], v[200:203], v[228:231], v[2:5]
	v_mfma_f32_16x16x32_bf16 v[2:5], v[204:207], v[220:223], v[172:175]
	v_mfma_f32_16x16x32_bf16 v[2:5], v[224:227], v[228:231], v[2:5]
	s_setprio 0
	s_barrier
	s_and_saveexec_b64 s[56:57], s[4:5]
	s_cbranch_execz .LBB0_1013
	s_barrier

; #define LDA(dst, b, h)                                                                                     \
;   _Pragma("unroll") for (int m = 0; m < 4; ++m) _Pragma("unroll") for (int k = 0; k < 2; ++k) dst[m][k] = \
;       *reinterpret_cast<const bf16x8*>(shmc + aL + (((b) * 2 + (h)) * 16384 + (m * 2 + k) * 1024))
; #define LDB(dst, b, h)                                                                                     \
;   _Pragma("unroll") for (int n = 0; n < 2; ++n) _Pragma("unroll") for (int k = 0; k < 2; ++k) dst[n][k] = \
;       *reinterpret_cast<const bf16x8*>(shmc + bL + (((b) * 2 + (h)) * 16384 + (n * 2 + k) * 1024))
; #define OPAQ asm volatile("" : "+v"(aL), "+v"(bL))
; #define WAIT_V(n) asm volatile("s_waitcnt vmcnt(" #n ")" ::: "memory")
; #define WAIT_L(n) asm volatile("s_waitcnt lgkmcnt(" #n ")" ::: "memory")
; #define BAR __builtin_amdgcn_s_barrier()
; #define SCHED __builtin_amdgcn_sched_barrier(0)
; template <int EPI>
; __device__ __forceinline__ void phase_gemm(const Params& p, const GemmDesc& d, char* shmc) {
;     ...
;     for (int t = 0; t < nt - 2; t += 2) {
;       OPAQ;
;       LDB(B0, 0, 0); SCHED; LDA(At, 0, 0); STAGE_A(SA(1, 1), 1, t + 1);
;       WAIT_L(8); BAR; WAIT_L(0); MMA(0, 0, At, B0); BAR; SCHED;
;       LDB(B1, 0, 1); STAGE_B(SB(0, 0), 0, t + 2);
;       BAR; WAIT_L(0); MMA(0, 1, At, B1); BAR;
;       LDA(At, 0, 1); STAGE_A(SA(0, 0), 0, t + 2);
;       BAR; WAIT_L(0); MMA(1, 0, At, B0); BAR; SCHED;
;       STAGE_B(SB(0, 1), 1, t + 2);
;       WAIT_V(6); BAR; MMA(1, 1, At, B1); BAR;
;       LDB(B0, 1, 0); SCHED; LDA(At, 1, 0); STAGE_A(SA(0, 1), 1, t + 2);
;       WAIT_L(8); BAR; WAIT_L(0); MMA(0, 0, At, B0); BAR; SCHED;
.LBB0_1153:
	s_nop 0
	v_add_u32_e32 v162, 0, v205
	v_add_u32_e32 v175, 0, v204
	s_setprio 0
	ds_read_b128 v[138:141], v162
	ds_read_b128 v[142:145], v162 offset:1024
	ds_read_b128 v[146:149], v162 offset:2048
	ds_read_b128 v[150:153], v162 offset:3072
	ds_read_b128 v[208:211], v162 offset:16384
	ds_read_b128 v[212:215], v162 offset:17408
	ds_read_b128 v[216:219], v162 offset:18432
	ds_read_b128 v[220:223], v162 offset:19456
	v_lshl_add_u64 v[202:203], v[134:135], 0, s[10:11]
	v_lshl_add_u64 v[224:225], v[136:137], 0, s[10:11]
	v_lshl_add_u64 v[226:227], v[130:131], 0, s[10:11]
	v_lshl_add_u64 v[228:229], v[132:133], 0, s[10:11]
	ds_read_b128 v[154:157], v175
	ds_read_b128 v[158:161], v175 offset:1024
	ds_read_b128 v[178:181], v175 offset:2048
	ds_read_b128 v[182:185], v175 offset:3072
	ds_read_b128 v[186:189], v175 offset:4096
	ds_read_b128 v[190:193], v175 offset:5120
	ds_read_b128 v[194:197], v175 offset:6144
	ds_read_b128 v[198:201], v175 offset:7168
	s_add_i32 s59, s64, 0xc000
	s_mov_b32 m0, s59
	v_lshl_add_u64 v[230:231], v[202:203], 0, s[26:27]
	global_load_lds_dwordx4 v[230:231], off
	s_add_i32 s68, s64, 0xe000
	v_lshl_add_u64 v[230:231], v[224:225], 0, s[26:27]
	s_mov_b32 m0, s68
	s_nop 0
	global_load_lds_dwordx4 v[230:231], off
	s_waitcnt vmcnt(8)
	s_waitcnt lgkmcnt(0)
	s_setprio 1
	s_barrier
	v_mfma_f32_16x16x32_bf16 v[2:5], v[154:157], v[138:141], v[2:5]
	v_mfma_f32_16x16x32_bf16 v[6:9], v[154:157], v[146:149], v[6:9]
	v_mfma_f32_16x16x32_bf16 v[10:13], v[178:181], v[138:141], v[10:13]
	v_mfma_f32_16x16x32_bf16 v[18:21], v[178:181], v[146:149], v[18:21]
	v_mfma_f32_16x16x32_bf16 v[30:33], v[186:189], v[138:141], v[30:33]
	v_mfma_f32_16x16x32_bf16 v[42:45], v[186:189], v[146:149], v[42:45]
	v_mfma_f32_16x16x32_bf16 v[54:57], v[194:197], v[138:141], v[54:57]
	v_mfma_f32_16x16x32_bf16 v[66:69], v[194:197], v[146:149], v[66:69]
	v_mfma_f32_16x16x32_bf16 v[2:5], v[158:161], v[142:145], v[2:5]
	v_mfma_f32_16x16x32_bf16 v[6:9], v[158:161], v[150:153], v[6:9]
	v_mfma_f32_16x16x32_bf16 v[10:13], v[182:185], v[142:145], v[10:13]
	v_mfma_f32_16x16x32_bf16 v[18:21], v[182:185], v[150:153], v[18:21]
	v_mfma_f32_16x16x32_bf16 v[30:33], v[190:193], v[142:145], v[30:33]
	v_mfma_f32_16x16x32_bf16 v[42:45], v[190:193], v[150:153], v[42:45]
	v_mfma_f32_16x16x32_bf16 v[54:57], v[198:201], v[142:145], v[54:57]
	v_mfma_f32_16x16x32_bf16 v[66:69], v[198:201], v[150:153], v[66:69]
	v_mfma_f32_16x16x32_bf16 v[14:17], v[154:157], v[208:211], v[14:17]
	v_mfma_f32_16x16x32_bf16 v[22:25], v[154:157], v[216:219], v[22:25]
	v_mfma_f32_16x16x32_bf16 v[34:37], v[178:181], v[208:211], v[34:37]
	v_mfma_f32_16x16x32_bf16 v[46:49], v[178:181], v[216:219], v[46:49]
	v_mfma_f32_16x16x32_bf16 v[58:61], v[186:189], v[208:211], v[58:61]
	v_mfma_f32_16x16x32_bf16 v[70:73], v[186:189], v[216:219], v[70:73]
	v_mfma_f32_16x16x32_bf16 v[78:81], v[194:197], v[208:211], v[78:81]
	v_mfma_f32_16x16x32_bf16 v[86:89], v[194:197], v[216:219], v[86:89]
	v_mfma_f32_16x16x32_bf16 v[14:17], v[158:161], v[212:215], v[14:17]
	v_mfma_f32_16x16x32_bf16 v[22:25], v[158:161], v[220:223], v[22:25]
	v_mfma_f32_16x16x32_bf16 v[34:37], v[182:185], v[212:215], v[34:37]
	v_mfma_f32_16x16x32_bf16 v[46:49], v[182:185], v[220:223], v[46:49]
	v_mfma_f32_16x16x32_bf16 v[58:61], v[190:193], v[212:215], v[58:61]
	v_mfma_f32_16x16x32_bf16 v[70:73], v[190:193], v[220:223], v[70:73]
	v_mfma_f32_16x16x32_bf16 v[78:81], v[198:201], v[212:215], v[78:81]
	v_mfma_f32_16x16x32_bf16 v[86:89], v[198:201], v[220:223], v[86:89]
	s_barrier
	s_setprio 0
	ds_read_b128 v[154:157], v175 offset:16384
	ds_read_b128 v[158:161], v175 offset:17408
	ds_read_b128 v[178:181], v175 offset:18432
	ds_read_b128 v[182:185], v175 offset:19456
	ds_read_b128 v[186:189], v175 offset:20480
	ds_read_b128 v[190:193], v175 offset:21504
	ds_read_b128 v[194:197], v175 offset:22528
	ds_read_b128 v[198:201], v175 offset:23552
	s_mov_b32 m0, s65
	v_lshl_add_u64 v[230:231], v[226:227], 0, s[30:31]
	global_load_lds_dwordx4 v[230:231], off
	v_lshl_add_u64 v[230:231], v[228:229], 0, s[30:31]
	s_mov_b32 m0, s66
	s_nop 0
	global_load_lds_dwordx4 v[230:231], off
	s_mov_b32 m0, s64
	v_lshl_add_u64 v[230:231], v[202:203], 0, s[36:37]
	global_load_lds_dwordx4 v[230:231], off
	v_lshl_add_u64 v[230:231], v[224:225], 0, s[36:37]
	s_mov_b32 m0, s67
	s_nop 0
	global_load_lds_dwordx4 v[230:231], off
	s_mov_b32 m0, s71
	v_lshl_add_u64 v[230:231], v[226:227], 0, s[38:39]
	global_load_lds_dwordx4 v[230:231], off
	v_lshl_add_u64 v[230:231], v[228:229], 0, s[38:39]
	s_mov_b32 m0, s76
	s_nop 0
	global_load_lds_dwordx4 v[230:231], off
	s_waitcnt vmcnt(8)
	s_waitcnt lgkmcnt(0)
	s_setprio 1
	s_barrier
; #define LDA(dst, b, h)                                                                                     \
;   _Pragma("unroll") for (int m = 0; m < 4; ++m) _Pragma("unroll") for (int k = 0; k < 2; ++k) dst[m][k] = \
;       *reinterpret_cast<const bf16x8*>(shmc + aL + (((b) * 2 + (h)) * 16384 + (m * 2 + k) * 1024))
; #define LDB(dst, b, h)                                                                                     \
;   _Pragma("unroll") for (int n = 0; n < 2; ++n) _Pragma("unroll") for (int k = 0; k < 2; ++k) dst[n][k] = \
;       *reinterpret_cast<const bf16x8*>(shmc + bL + (((b) * 2 + (h)) * 16384 + (n * 2 + k) * 1024))
; #define WAIT_V(n) asm volatile("s_waitcnt vmcnt(" #n ")" ::: "memory")
; #define WAIT_L(n) asm volatile("s_waitcnt lgkmcnt(" #n ")" ::: "memory")
; #define BAR __builtin_amdgcn_s_barrier()
; #define SCHED __builtin_amdgcn_sched_barrier(0)
; template <int EPI>
; __device__ __forceinline__ void phase_gemm(const Params& p, const GemmDesc& d, char* shmc) {
;     ...
;       LDB(B0, 0, 0); SCHED; LDA(At, 0, 0); STAGE_A(SA(1, 1), 1, t + 1);
;       WAIT_L(8); BAR; WAIT_L(0); MMA(0, 0, At, B0); BAR; SCHED;
;       LDB(B1, 0, 1); STAGE_B(SB(0, 0), 0, t + 2);
;       BAR; WAIT_L(0); MMA(0, 1, At, B1); BAR;
;       LDA(At, 0, 1); STAGE_A(SA(0, 0), 0, t + 2);
;       BAR; WAIT_L(0); MMA(1, 0, At, B0); BAR; SCHED;
;       STAGE_B(SB(0, 1), 1, t + 2);
;       WAIT_V(6); BAR; MMA(1, 1, At, B1); BAR;
;       LDB(B0, 1, 0); SCHED; LDA(At, 1, 0); STAGE_A(SA(0, 1), 1, t + 2);
;       WAIT_L(8); BAR; WAIT_L(0); MMA(0, 0, At, B0); BAR; SCHED;
	v_mfma_f32_16x16x32_bf16 v[26:29], v[154:157], v[138:141], v[26:29]
	v_mfma_f32_16x16x32_bf16 v[38:41], v[154:157], v[146:149], v[38:41]
	v_mfma_f32_16x16x32_bf16 v[50:53], v[178:181], v[138:141], v[50:53]
	v_mfma_f32_16x16x32_bf16 v[62:65], v[178:181], v[146:149], v[62:65]
	v_mfma_f32_16x16x32_bf16 v[74:77], v[186:189], v[138:141], v[74:77]
	v_mfma_f32_16x16x32_bf16 v[82:85], v[186:189], v[146:149], v[82:85]
	v_mfma_f32_16x16x32_bf16 v[90:93], v[194:197], v[138:141], v[90:93]
	v_mfma_f32_16x16x32_bf16 v[94:97], v[194:197], v[146:149], v[94:97]
	v_mfma_f32_16x16x32_bf16 v[26:29], v[158:161], v[142:145], v[26:29]
	v_mfma_f32_16x16x32_bf16 v[38:41], v[158:161], v[150:153], v[38:41]
	v_mfma_f32_16x16x32_bf16 v[50:53], v[182:185], v[142:145], v[50:53]
	v_mfma_f32_16x16x32_bf16 v[62:65], v[182:185], v[150:153], v[62:65]
	v_mfma_f32_16x16x32_bf16 v[74:77], v[190:193], v[142:145], v[74:77]
	v_mfma_f32_16x16x32_bf16 v[82:85], v[190:193], v[150:153], v[82:85]
	v_mfma_f32_16x16x32_bf16 v[90:93], v[198:201], v[142:145], v[90:93]
	v_mfma_f32_16x16x32_bf16 v[94:97], v[198:201], v[150:153], v[94:97]
	v_mfma_f32_16x16x32_bf16 v[98:101], v[154:157], v[208:211], v[98:101]
	v_mfma_f32_16x16x32_bf16 v[102:105], v[154:157], v[216:219], v[102:105]
	v_mfma_f32_16x16x32_bf16 v[106:109], v[178:181], v[208:211], v[106:109]
	v_mfma_f32_16x16x32_bf16 v[110:113], v[178:181], v[216:219], v[110:113]
	v_mfma_f32_16x16x32_bf16 v[114:117], v[186:189], v[208:211], v[114:117]
	v_mfma_f32_16x16x32_bf16 v[118:121], v[186:189], v[216:219], v[118:121]
	v_mfma_f32_16x16x32_bf16 v[122:125], v[194:197], v[208:211], v[122:125]
	v_mfma_f32_16x16x32_bf16 v[126:129], v[194:197], v[216:219], v[126:129]
	v_mfma_f32_16x16x32_bf16 v[98:101], v[158:161], v[212:215], v[98:101]
	v_mfma_f32_16x16x32_bf16 v[102:105], v[158:161], v[220:223], v[102:105]
	v_mfma_f32_16x16x32_bf16 v[106:109], v[182:185], v[212:215], v[106:109]
	v_mfma_f32_16x16x32_bf16 v[110:113], v[182:185], v[220:223], v[110:113]
	v_mfma_f32_16x16x32_bf16 v[114:117], v[190:193], v[212:215], v[114:117]
	v_mfma_f32_16x16x32_bf16 v[118:121], v[190:193], v[220:223], v[118:121]
	v_mfma_f32_16x16x32_bf16 v[122:125], v[198:201], v[212:215], v[122:125]
	v_mfma_f32_16x16x32_bf16 v[126:129], v[198:201], v[220:223], v[126:129]
	s_barrier
	s_setprio 0
	ds_read_b128 v[138:141], v162 offset:32768
	ds_read_b128 v[142:145], v162 offset:33792
	ds_read_b128 v[146:149], v162 offset:34816
	ds_read_b128 v[150:153], v162 offset:35840
	ds_read_b128 v[208:211], v162 offset:49152
	ds_read_b128 v[212:215], v162 offset:50176
	ds_read_b128 v[216:219], v162 offset:51200
	ds_read_b128 v[220:223], v162 offset:52224
	ds_read_b128 v[154:157], v175 offset:32768
	ds_read_b128 v[158:161], v175 offset:33792
	ds_read_b128 v[178:181], v175 offset:34816
	ds_read_b128 v[182:185], v175 offset:35840
	ds_read_b128 v[186:189], v175 offset:36864
	ds_read_b128 v[190:193], v175 offset:37888
	ds_read_b128 v[194:197], v175 offset:38912
	ds_read_b128 v[198:201], v175 offset:39936
	s_mov_b32 m0, s77
	v_lshl_add_u64 v[230:231], v[202:203], 0, s[40:41]
	global_load_lds_dwordx4 v[230:231], off
	v_lshl_add_u64 v[230:231], v[224:225], 0, s[40:41]
	s_mov_b32 m0, s78
	s_nop 0
	global_load_lds_dwordx4 v[230:231], off
	s_waitcnt vmcnt(8)
	s_waitcnt lgkmcnt(0)
	s_setprio 1
	s_barrier
	v_mfma_f32_16x16x32_bf16 v[2:5], v[154:157], v[138:141], v[2:5]
	v_mfma_f32_16x16x32_bf16 v[6:9], v[154:157], v[146:149], v[6:9]
	v_mfma_f32_16x16x32_bf16 v[10:13], v[178:181], v[138:141], v[10:13]
	v_mfma_f32_16x16x32_bf16 v[18:21], v[178:181], v[146:149], v[18:21]
	v_mfma_f32_16x16x32_bf16 v[30:33], v[186:189], v[138:141], v[30:33]
	v_mfma_f32_16x16x32_bf16 v[42:45], v[186:189], v[146:149], v[42:45]
	v_mfma_f32_16x16x32_bf16 v[54:57], v[194:197], v[138:141], v[54:57]
	v_mfma_f32_16x16x32_bf16 v[66:69], v[194:197], v[146:149], v[66:69]
	v_mfma_f32_16x16x32_bf16 v[2:5], v[158:161], v[142:145], v[2:5]
	v_mfma_f32_16x16x32_bf16 v[6:9], v[158:161], v[150:153], v[6:9]
	v_mfma_f32_16x16x32_bf16 v[10:13], v[182:185], v[142:145], v[10:13]
	v_mfma_f32_16x16x32_bf16 v[18:21], v[182:185], v[150:153], v[18:21]
	v_mfma_f32_16x16x32_bf16 v[30:33], v[190:193], v[142:145], v[30:33]
	v_mfma_f32_16x16x32_bf16 v[42:45], v[190:193], v[150:153], v[42:45]
	v_mfma_f32_16x16x32_bf16 v[54:57], v[198:201], v[142:145], v[54:57]
	v_mfma_f32_16x16x32_bf16 v[66:69], v[198:201], v[150:153], v[66:69]
	v_mfma_f32_16x16x32_bf16 v[14:17], v[154:157], v[208:211], v[14:17]
	v_mfma_f32_16x16x32_bf16 v[22:25], v[154:157], v[216:219], v[22:25]
	v_mfma_f32_16x16x32_bf16 v[34:37], v[178:181], v[208:211], v[34:37]
	v_mfma_f32_16x16x32_bf16 v[46:49], v[178:181], v[216:219], v[46:49]
	v_mfma_f32_16x16x32_bf16 v[58:61], v[186:189], v[208:211], v[58:61]
	v_mfma_f32_16x16x32_bf16 v[70:73], v[186:189], v[216:219], v[70:73]
	v_mfma_f32_16x16x32_bf16 v[78:81], v[194:197], v[208:211], v[78:81]
	v_mfma_f32_16x16x32_bf16 v[86:89], v[194:197], v[216:219], v[86:89]
	v_mfma_f32_16x16x32_bf16 v[14:17], v[158:161], v[212:215], v[14:17]
	v_mfma_f32_16x16x32_bf16 v[22:25], v[158:161], v[220:223], v[22:25]
	v_mfma_f32_16x16x32_bf16 v[34:37], v[182:185], v[212:215], v[34:37]
	v_mfma_f32_16x16x32_bf16 v[46:49], v[182:185], v[220:223], v[46:49]
	v_mfma_f32_16x16x32_bf16 v[58:61], v[190:193], v[212:215], v[58:61]
	v_mfma_f32_16x16x32_bf16 v[70:73], v[190:193], v[220:223], v[70:73]
	v_mfma_f32_16x16x32_bf16 v[78:81], v[198:201], v[212:215], v[78:81]
	v_mfma_f32_16x16x32_bf16 v[86:89], v[198:201], v[220:223], v[86:89]
	s_barrier
; #define LDA(dst, b, h)                                                                                     \
;   _Pragma("unroll") for (int m = 0; m < 4; ++m) _Pragma("unroll") for (int k = 0; k < 2; ++k) dst[m][k] = \
;       *reinterpret_cast<const bf16x8*>(shmc + aL + (((b) * 2 + (h)) * 16384 + (m * 2 + k) * 1024))
; #define LDB(dst, b, h)                                                                                     \
;   _Pragma("unroll") for (int n = 0; n < 2; ++n) _Pragma("unroll") for (int k = 0; k < 2; ++k) dst[n][k] = \
;       *reinterpret_cast<const bf16x8*>(shmc + bL + (((b) * 2 + (h)) * 16384 + (n * 2 + k) * 1024))
; #define OPAQ asm volatile("" : "+v"(aL), "+v"(bL))
; #define WAIT_V(n) asm volatile("s_waitcnt vmcnt(" #n ")" ::: "memory")
; #define WAIT_L(n) asm volatile("s_waitcnt lgkmcnt(" #n ")" ::: "memory")
; #define BAR __builtin_amdgcn_s_barrier()
; #define SCHED __builtin_amdgcn_sched_barrier(0)
; template <int EPI>
; __device__ __forceinline__ void phase_gemm(const Params& p, const GemmDesc& d, char* shmc) {
;     ...
;       LDB(B1, 1, 1); STAGE_B(SB(1, 0), 0, t + 3);
;       BAR; WAIT_L(0); MMA(0, 1, At, B1); BAR;
;       LDA(At, 1, 1); STAGE_A(SA(1, 0), 0, t + 3);
;       BAR; WAIT_L(0); MMA(1, 0, At, B0); BAR; SCHED;
;       STAGE_B(SB(1, 1), 1, t + 3);
;       WAIT_V(6); BAR; MMA(1, 1, At, B1); BAR;
;     }
;     {
;       OPAQ;
;       LDB(B0, 0, 0); LDA(At, 0, 0); STAGE_A(SA(1, 1), 1, nt - 1);
;       BAR; WAIT_L(0); MMA(0, 0, At, B0); BAR;
;       LDB(B1, 0, 1); BAR; WAIT_L(0); MMA(0, 1, At, B1); BAR;
;       LDA(At, 0, 1); WAIT_V(4); BAR; WAIT_L(0); MMA(1, 0, At, B0); MMA(1, 1, At, B1); BAR;
	s_setprio 0
	ds_read_b128 v[154:157], v175 offset:49152
	ds_read_b128 v[158:161], v175 offset:50176
	ds_read_b128 v[178:181], v175 offset:51200
	ds_read_b128 v[182:185], v175 offset:52224
	ds_read_b128 v[186:189], v175 offset:53248
	ds_read_b128 v[190:193], v175 offset:54272
	ds_read_b128 v[194:197], v175 offset:55296
	ds_read_b128 v[198:201], v175 offset:56320
	s_mov_b32 m0, s35
	v_lshl_add_u64 v[230:231], v[226:227], 0, s[42:43]
	global_load_lds_dwordx4 v[230:231], off
	v_lshl_add_u64 v[230:231], v[228:229], 0, s[42:43]
	s_mov_b32 m0, s53
	s_nop 0
	global_load_lds_dwordx4 v[230:231], off
	s_mov_b32 m0, s56
	v_lshl_add_u64 v[230:231], v[202:203], 0, s[46:47]
	global_load_lds_dwordx4 v[230:231], off
	v_lshl_add_u64 v[230:231], v[224:225], 0, s[46:47]
	s_mov_b32 m0, s57
	s_nop 0
	global_load_lds_dwordx4 v[230:231], off
	s_mov_b32 m0, s54
	v_lshl_add_u64 v[230:231], v[226:227], 0, s[48:49]
	global_load_lds_dwordx4 v[230:231], off
	v_lshl_add_u64 v[230:231], v[228:229], 0, s[48:49]
	s_mov_b32 m0, s55
	s_nop 0
	global_load_lds_dwordx4 v[230:231], off
	s_add_i32 s58, s58, 2
	s_add_u32 s10, s10, 0x100
	s_addc_u32 s11, s11, 0
	s_cmp_gt_u32 s58, 27
	s_waitcnt vmcnt(8)
	s_waitcnt lgkmcnt(0)
	s_setprio 1
	s_barrier
	v_mfma_f32_16x16x32_bf16 v[26:29], v[154:157], v[138:141], v[26:29]
	v_mfma_f32_16x16x32_bf16 v[38:41], v[154:157], v[146:149], v[38:41]
	v_mfma_f32_16x16x32_bf16 v[50:53], v[178:181], v[138:141], v[50:53]
	v_mfma_f32_16x16x32_bf16 v[62:65], v[178:181], v[146:149], v[62:65]
	v_mfma_f32_16x16x32_bf16 v[74:77], v[186:189], v[138:141], v[74:77]
	v_mfma_f32_16x16x32_bf16 v[82:85], v[186:189], v[146:149], v[82:85]
	v_mfma_f32_16x16x32_bf16 v[90:93], v[194:197], v[138:141], v[90:93]
	v_mfma_f32_16x16x32_bf16 v[94:97], v[194:197], v[146:149], v[94:97]
	v_mfma_f32_16x16x32_bf16 v[26:29], v[158:161], v[142:145], v[26:29]
	v_mfma_f32_16x16x32_bf16 v[38:41], v[158:161], v[150:153], v[38:41]
	v_mfma_f32_16x16x32_bf16 v[50:53], v[182:185], v[142:145], v[50:53]
	v_mfma_f32_16x16x32_bf16 v[62:65], v[182:185], v[150:153], v[62:65]
	v_mfma_f32_16x16x32_bf16 v[74:77], v[190:193], v[142:145], v[74:77]
	v_mfma_f32_16x16x32_bf16 v[82:85], v[190:193], v[150:153], v[82:85]
	v_mfma_f32_16x16x32_bf16 v[90:93], v[198:201], v[142:145], v[90:93]
	v_mfma_f32_16x16x32_bf16 v[94:97], v[198:201], v[150:153], v[94:97]
	v_mfma_f32_16x16x32_bf16 v[98:101], v[154:157], v[208:211], v[98:101]
	v_mfma_f32_16x16x32_bf16 v[102:105], v[154:157], v[216:219], v[102:105]
	v_mfma_f32_16x16x32_bf16 v[106:109], v[178:181], v[208:211], v[106:109]
	v_mfma_f32_16x16x32_bf16 v[110:113], v[178:181], v[216:219], v[110:113]
	v_mfma_f32_16x16x32_bf16 v[114:117], v[186:189], v[208:211], v[114:117]
	v_mfma_f32_16x16x32_bf16 v[118:121], v[186:189], v[216:219], v[118:121]
	v_mfma_f32_16x16x32_bf16 v[122:125], v[194:197], v[208:211], v[122:125]
	v_mfma_f32_16x16x32_bf16 v[126:129], v[194:197], v[216:219], v[126:129]
	v_mfma_f32_16x16x32_bf16 v[98:101], v[158:161], v[212:215], v[98:101]
	v_mfma_f32_16x16x32_bf16 v[102:105], v[158:161], v[220:223], v[102:105]
	v_mfma_f32_16x16x32_bf16 v[106:109], v[182:185], v[212:215], v[106:109]
	v_mfma_f32_16x16x32_bf16 v[110:113], v[182:185], v[220:223], v[110:113]
	v_mfma_f32_16x16x32_bf16 v[114:117], v[190:193], v[212:215], v[114:117]
	v_mfma_f32_16x16x32_bf16 v[118:121], v[190:193], v[220:223], v[118:121]
	v_mfma_f32_16x16x32_bf16 v[122:125], v[198:201], v[212:215], v[122:125]
	v_mfma_f32_16x16x32_bf16 v[126:129], v[198:201], v[220:223], v[126:129]
	s_barrier
	s_cbranch_scc0 .LBB0_1153
	s_setprio 0
	s_add_u32 s8, s8, 0x80f80
	s_addc_u32 s9, s9, 0
	v_add_u32_e32 v162, 0, v205
	v_add_u32_e32 v175, 0, v204
	s_mov_b32 m0, s59
	ds_read_b128 v[130:133], v162
	ds_read_b128 v[134:137], v162 offset:1024
	ds_read_b128 v[138:141], v162 offset:2048
	ds_read_b128 v[142:145], v162 offset:3072
	ds_read_b128 v[146:149], v175
	ds_read_b128 v[150:153], v175 offset:1024
	ds_read_b128 v[154:157], v175 offset:2048
	ds_read_b128 v[158:161], v175 offset:3072
	ds_read_b128 v[178:181], v175 offset:4096
	ds_read_b128 v[182:185], v175 offset:5120
	ds_read_b128 v[186:189], v175 offset:6144
	ds_read_b128 v[190:193], v175 offset:7168
	global_load_lds_dwordx4 v174, s[8:9]
	s_mov_b32 m0, s68
	s_nop 0
	global_load_lds_dwordx4 v176, s[8:9]
	s_waitcnt vmcnt(8)
	s_barrier
	s_waitcnt lgkmcnt(0)
	s_setprio 1
	s_waitcnt lgkmcnt(0)
	v_mfma_f32_16x16x32_bf16 v[2:5], v[146:149], v[130:133], v[2:5]
	v_mfma_f32_16x16x32_bf16 v[6:9], v[146:149], v[138:141], v[6:9]
	v_mfma_f32_16x16x32_bf16 v[10:13], v[154:157], v[130:133], v[10:13]
	v_mfma_f32_16x16x32_bf16 v[18:21], v[154:157], v[138:141], v[18:21]
	v_mfma_f32_16x16x32_bf16 v[66:69], v[186:189], v[138:141], v[66:69]
	v_mfma_f32_16x16x32_bf16 v[2:5], v[150:153], v[134:137], v[2:5]
	v_mfma_f32_16x16x32_bf16 v[6:9], v[150:153], v[142:145], v[6:9]
	v_mfma_f32_16x16x32_bf16 v[10:13], v[158:161], v[134:137], v[10:13]
	v_mfma_f32_16x16x32_bf16 v[18:21], v[158:161], v[142:145], v[18:21]
	v_mfma_f32_16x16x32_bf16 v[30:33], v[178:181], v[130:133], v[30:33]
	v_mfma_f32_16x16x32_bf16 v[42:45], v[178:181], v[138:141], v[42:45]
	v_mfma_f32_16x16x32_bf16 v[54:57], v[186:189], v[130:133], v[54:57]
	v_mfma_f32_16x16x32_bf16 v[66:69], v[190:193], v[142:145], v[66:69]
	v_mfma_f32_16x16x32_bf16 v[30:33], v[182:185], v[134:137], v[30:33]
	v_mfma_f32_16x16x32_bf16 v[42:45], v[182:185], v[142:145], v[42:45]
	v_mfma_f32_16x16x32_bf16 v[54:57], v[190:193], v[134:137], v[54:57]
	s_setprio 0
	s_barrier
	ds_read_b128 v[194:197], v162 offset:16384
	ds_read_b128 v[198:201], v162 offset:17408
	ds_read_b128 v[208:211], v162 offset:18432
	ds_read_b128 v[212:215], v162 offset:19456
	s_barrier
; #define LDA(dst, b, h)                                                                                     \
;   _Pragma("unroll") for (int m = 0; m < 4; ++m) _Pragma("unroll") for (int k = 0; k < 2; ++k) dst[m][k] = \
;       *reinterpret_cast<const bf16x8*>(shmc + aL + (((b) * 2 + (h)) * 16384 + (m * 2 + k) * 1024))
; #define LDB(dst, b, h)                                                                                     \
;   _Pragma("unroll") for (int n = 0; n < 2; ++n) _Pragma("unroll") for (int k = 0; k < 2; ++k) dst[n][k] = \
;       *reinterpret_cast<const bf16x8*>(shmc + bL + (((b) * 2 + (h)) * 16384 + (n * 2 + k) * 1024))
; #define WAIT_V(n) asm volatile("s_waitcnt vmcnt(" #n ")" ::: "memory")
; #define WAIT_L(n) asm volatile("s_waitcnt lgkmcnt(" #n ")" ::: "memory")
; #define BAR __builtin_amdgcn_s_barrier()
; template <int EPI>
; __device__ __forceinline__ void phase_gemm(const Params& p, const GemmDesc& d, char* shmc) {
;     ...
;       BAR; WAIT_L(0); MMA(0, 0, At, B0); BAR;
;       LDB(B1, 0, 1); BAR; WAIT_L(0); MMA(0, 1, At, B1); BAR;
;       LDA(At, 0, 1); WAIT_V(4); BAR; WAIT_L(0); MMA(1, 0, At, B0); MMA(1, 1, At, B1); BAR;
;     }
;     {
;       LDB(B0, 1, 0); LDA(At, 1, 0); WAIT_V(2); BAR; WAIT_L(0); MMA(0, 0, At, B0); BAR;
	s_waitcnt lgkmcnt(0)
	s_setprio 1
	s_waitcnt lgkmcnt(0)
	v_mfma_f32_16x16x32_bf16 v[14:17], v[146:149], v[194:197], v[14:17]
	v_mfma_f32_16x16x32_bf16 v[22:25], v[146:149], v[208:211], v[22:25]
	v_mfma_f32_16x16x32_bf16 v[58:61], v[178:181], v[194:197], v[58:61]
	v_mfma_f32_16x16x32_bf16 v[14:17], v[150:153], v[198:201], v[14:17]
	v_mfma_f32_16x16x32_bf16 v[22:25], v[150:153], v[212:215], v[22:25]
	v_mfma_f32_16x16x32_bf16 v[150:153], v[182:185], v[198:201], v[58:61]
	v_mfma_f32_16x16x32_bf16 v[58:61], v[178:181], v[208:211], v[70:73]
	v_mfma_f32_16x16x32_bf16 v[34:37], v[154:157], v[194:197], v[34:37]
	v_mfma_f32_16x16x32_bf16 v[46:49], v[154:157], v[208:211], v[46:49]
	v_mfma_f32_16x16x32_bf16 v[154:157], v[182:185], v[212:215], v[58:61]
	v_mfma_f32_16x16x32_bf16 v[58:61], v[186:189], v[194:197], v[78:81]
	v_mfma_f32_16x16x32_bf16 v[78:81], v[190:193], v[198:201], v[58:61]
	v_mfma_f32_16x16x32_bf16 v[58:61], v[186:189], v[208:211], v[86:89]
	v_mfma_f32_16x16x32_bf16 v[86:89], v[190:193], v[212:215], v[58:61]
	v_mfma_f32_16x16x32_bf16 v[34:37], v[158:161], v[198:201], v[34:37]
	v_mfma_f32_16x16x32_bf16 v[46:49], v[158:161], v[212:215], v[46:49]
	s_setprio 0
	s_barrier
	s_nop 2
	ds_read_b128 v[58:61], v175 offset:16384
	ds_read_b128 v[70:73], v175 offset:17408
	ds_read_b128 v[146:149], v175 offset:18432
	ds_read_b128 v[158:161], v175 offset:19456
	ds_read_b128 v[178:181], v175 offset:20480
	ds_read_b128 v[182:185], v175 offset:21504
	ds_read_b128 v[186:189], v175 offset:22528
	ds_read_b128 v[190:193], v175 offset:23552
	s_waitcnt vmcnt(4)
	s_barrier
	s_waitcnt lgkmcnt(0)
	s_setprio 1
	s_waitcnt lgkmcnt(0)
	v_mfma_f32_16x16x32_bf16 v[74:77], v[178:181], v[130:133], v[74:77]
	v_mfma_f32_16x16x32_bf16 v[216:219], v[182:185], v[134:137], v[74:77]
	v_mfma_f32_16x16x32_bf16 v[74:77], v[178:181], v[138:141], v[82:85]
	v_mfma_f32_16x16x32_bf16 v[26:29], v[58:61], v[130:133], v[26:29]
	v_mfma_f32_16x16x32_bf16 v[82:85], v[182:185], v[142:145], v[74:77]
	v_mfma_f32_16x16x32_bf16 v[74:77], v[186:189], v[130:133], v[90:93]
	v_mfma_f32_16x16x32_bf16 v[26:29], v[70:73], v[134:137], v[26:29]
	v_mfma_f32_16x16x32_bf16 v[38:41], v[58:61], v[138:141], v[38:41]
	v_mfma_f32_16x16x32_bf16 v[50:53], v[146:149], v[130:133], v[50:53]
	v_mfma_f32_16x16x32_bf16 v[62:65], v[146:149], v[138:141], v[62:65]
	v_mfma_f32_16x16x32_bf16 v[90:93], v[190:193], v[134:137], v[74:77]
	v_mfma_f32_16x16x32_bf16 v[74:77], v[186:189], v[138:141], v[94:97]
	v_mfma_f32_16x16x32_bf16 v[38:41], v[70:73], v[142:145], v[38:41]
	v_mfma_f32_16x16x32_bf16 v[50:53], v[158:161], v[134:137], v[50:53]
	v_mfma_f32_16x16x32_bf16 v[62:65], v[158:161], v[142:145], v[62:65]
	v_mfma_f32_16x16x32_bf16 v[220:223], v[190:193], v[142:145], v[74:77]
	s_setprio 0
	s_setprio 1
	v_mfma_f32_16x16x32_bf16 v[74:77], v[58:61], v[194:197], v[98:101]
	v_mfma_f32_16x16x32_bf16 v[58:61], v[58:61], v[208:211], v[102:105]
	v_mfma_f32_16x16x32_bf16 v[228:231], v[70:73], v[212:215], v[58:61]
	v_mfma_f32_16x16x32_bf16 v[58:61], v[146:149], v[194:197], v[106:109]
	v_mfma_f32_16x16x32_bf16 v[232:235], v[158:161], v[198:201], v[58:61]
	v_mfma_f32_16x16x32_bf16 v[58:61], v[146:149], v[208:211], v[110:113]
	v_mfma_f32_16x16x32_bf16 v[236:239], v[158:161], v[212:215], v[58:61]
	v_mfma_f32_16x16x32_bf16 v[58:61], v[178:181], v[194:197], v[114:117]
	v_mfma_f32_16x16x32_bf16 v[240:243], v[182:185], v[198:201], v[58:61]
	v_mfma_f32_16x16x32_bf16 v[58:61], v[178:181], v[208:211], v[118:121]
	v_mfma_f32_16x16x32_bf16 v[178:181], v[182:185], v[212:215], v[58:61]
	v_mfma_f32_16x16x32_bf16 v[58:61], v[186:189], v[194:197], v[122:125]
	v_mfma_f32_16x16x32_bf16 v[182:185], v[190:193], v[198:201], v[58:61]
	v_mfma_f32_16x16x32_bf16 v[58:61], v[186:189], v[208:211], v[126:129]
	v_mfma_f32_16x16x32_bf16 v[224:227], v[70:73], v[198:201], v[74:77]
	v_mfma_f32_16x16x32_bf16 v[186:189], v[190:193], v[212:215], v[58:61]
	s_setprio 0
	s_barrier
	ds_read_b128 v[98:101], v162 offset:32768
	ds_read_b128 v[106:109], v162 offset:33792
	ds_read_b128 v[190:193], v162 offset:34816
	ds_read_b128 v[194:197], v162 offset:35840
	ds_read_b128 v[58:61], v175 offset:32768
	ds_read_b128 v[70:73], v175 offset:33792
	ds_read_b128 v[114:117], v175 offset:34816
	ds_read_b128 v[122:125], v175 offset:35840
	ds_read_b128 v[130:133], v175 offset:36864
	ds_read_b128 v[138:141], v175 offset:37888
	ds_read_b128 v[198:201], v175 offset:38912
	ds_read_b128 v[208:211], v175 offset:39936
	s_waitcnt vmcnt(2)
	s_barrier
; #define LDA(dst, b, h)                                                                                     \
;   _Pragma("unroll") for (int m = 0; m < 4; ++m) _Pragma("unroll") for (int k = 0; k < 2; ++k) dst[m][k] = \
;       *reinterpret_cast<const bf16x8*>(shmc + aL + (((b) * 2 + (h)) * 16384 + (m * 2 + k) * 1024))
; #define LDB(dst, b, h)                                                                                     \
;   _Pragma("unroll") for (int n = 0; n < 2; ++n) _Pragma("unroll") for (int k = 0; k < 2; ++k) dst[n][k] = \
;       *reinterpret_cast<const bf16x8*>(shmc + bL + (((b) * 2 + (h)) * 16384 + (n * 2 + k) * 1024))
; #define WAIT_V(n) asm volatile("s_waitcnt vmcnt(" #n ")" ::: "memory")
; #define WAIT_L(n) asm volatile("s_waitcnt lgkmcnt(" #n ")" ::: "memory")
; #define BAR __builtin_amdgcn_s_barrier()
; template <int EPI>
; __device__ __forceinline__ void phase_gemm(const Params& p, const GemmDesc& d, char* shmc) {
;     ...
;       LDB(B0, 1, 0); LDA(At, 1, 0); WAIT_V(2); BAR; WAIT_L(0); MMA(0, 0, At, B0); BAR;
;       LDB(B1, 1, 1); WAIT_V(0); BAR; WAIT_L(0); MMA(0, 1, At, B1); BAR;
;       LDA(At, 1, 1); BAR; WAIT_L(0); MMA(1, 0, At, B0); MMA(1, 1, At, B1); BAR;
;     }
;     if (wr == 0) BAR;
	s_waitcnt lgkmcnt(0)
	s_setprio 1
	s_waitcnt lgkmcnt(0)
	v_mfma_f32_16x16x32_bf16 v[2:5], v[58:61], v[98:101], v[2:5]
	v_mfma_f32_16x16x32_bf16 v[158:161], v[70:73], v[106:109], v[2:5]
	v_mfma_f32_16x16x32_bf16 v[2:5], v[58:61], v[190:193], v[6:9]
	v_mfma_f32_16x16x32_bf16 v[146:149], v[70:73], v[194:197], v[2:5]
	v_mfma_f32_16x16x32_bf16 v[2:5], v[114:117], v[98:101], v[10:13]
	v_mfma_f32_16x16x32_bf16 v[142:145], v[122:125], v[106:109], v[2:5]
	v_mfma_f32_16x16x32_bf16 v[2:5], v[114:117], v[190:193], v[18:21]
	v_mfma_f32_16x16x32_bf16 v[134:137], v[122:125], v[194:197], v[2:5]
	v_mfma_f32_16x16x32_bf16 v[2:5], v[130:133], v[98:101], v[30:33]
	v_mfma_f32_16x16x32_bf16 v[126:129], v[138:141], v[106:109], v[2:5]
	v_mfma_f32_16x16x32_bf16 v[2:5], v[130:133], v[190:193], v[42:45]
	v_mfma_f32_16x16x32_bf16 v[118:121], v[138:141], v[194:197], v[2:5]
	v_mfma_f32_16x16x32_bf16 v[2:5], v[198:201], v[98:101], v[54:57]
	v_mfma_f32_16x16x32_bf16 v[110:113], v[208:211], v[106:109], v[2:5]
	v_mfma_f32_16x16x32_bf16 v[2:5], v[198:201], v[190:193], v[66:69]
	v_mfma_f32_16x16x32_bf16 v[102:105], v[208:211], v[194:197], v[2:5]
	s_setprio 0
	s_barrier
	ds_read_b128 v[30:33], v162 offset:49152
	ds_read_b128 v[42:45], v162 offset:50176
	ds_read_b128 v[54:57], v162 offset:51200
	ds_read_b128 v[212:215], v162 offset:52224
	s_waitcnt vmcnt(0)
	s_barrier
	s_waitcnt lgkmcnt(0)
	s_setprio 1
	s_waitcnt lgkmcnt(0)
	v_mfma_f32_16x16x32_bf16 v[2:5], v[58:61], v[30:33], v[14:17]
	v_mfma_f32_16x16x32_bf16 v[94:97], v[70:73], v[42:45], v[2:5]
	v_mfma_f32_16x16x32_bf16 v[2:5], v[58:61], v[54:57], v[22:25]
	v_mfma_f32_16x16x32_bf16 v[58:61], v[70:73], v[212:215], v[2:5]
	v_mfma_f32_16x16x32_bf16 v[2:5], v[114:117], v[30:33], v[34:37]
	v_mfma_f32_16x16x32_bf16 v[74:77], v[122:125], v[42:45], v[2:5]
	v_mfma_f32_16x16x32_bf16 v[2:5], v[114:117], v[54:57], v[46:49]
	v_mfma_f32_16x16x32_bf16 v[10:13], v[122:125], v[212:215], v[2:5]
	v_mfma_f32_16x16x32_bf16 v[2:5], v[130:133], v[30:33], v[150:153]
	v_mfma_f32_16x16x32_bf16 v[70:73], v[138:141], v[42:45], v[2:5]
	v_mfma_f32_16x16x32_bf16 v[2:5], v[130:133], v[54:57], v[154:157]
	v_mfma_f32_16x16x32_bf16 v[6:9], v[138:141], v[212:215], v[2:5]
	v_mfma_f32_16x16x32_bf16 v[2:5], v[198:201], v[30:33], v[78:81]
	v_mfma_f32_16x16x32_bf16 v[66:69], v[208:211], v[42:45], v[2:5]
	v_mfma_f32_16x16x32_bf16 v[2:5], v[198:201], v[54:57], v[86:89]
	v_mfma_f32_16x16x32_bf16 v[2:5], v[208:211], v[212:215], v[2:5]
	s_setprio 0
	s_barrier
	ds_read_b128 v[14:17], v175 offset:49152
	ds_read_b128 v[18:21], v175 offset:50176
	ds_read_b128 v[22:25], v175 offset:51200
	ds_read_b128 v[34:37], v175 offset:52224
	ds_read_b128 v[46:49], v175 offset:53248
	ds_read_b128 v[78:81], v175 offset:54272
	ds_read_b128 v[198:201], v175 offset:55296
	ds_read_b128 v[208:211], v175 offset:56320
	s_barrier
	s_waitcnt lgkmcnt(0)
	s_setprio 1
	s_waitcnt lgkmcnt(0)
	v_mfma_f32_16x16x32_bf16 v[26:29], v[14:17], v[98:101], v[26:29]
	v_mfma_f32_16x16x32_bf16 v[154:157], v[18:21], v[106:109], v[26:29]
	v_mfma_f32_16x16x32_bf16 v[26:29], v[14:17], v[190:193], v[38:41]
	v_mfma_f32_16x16x32_bf16 v[150:153], v[18:21], v[194:197], v[26:29]
	v_mfma_f32_16x16x32_bf16 v[26:29], v[22:25], v[98:101], v[50:53]
	v_mfma_f32_16x16x32_bf16 v[138:141], v[34:37], v[106:109], v[26:29]
	v_mfma_f32_16x16x32_bf16 v[26:29], v[22:25], v[190:193], v[62:65]
	v_mfma_f32_16x16x32_bf16 v[130:133], v[34:37], v[194:197], v[26:29]
	v_mfma_f32_16x16x32_bf16 v[26:29], v[46:49], v[98:101], v[216:219]
	v_mfma_f32_16x16x32_bf16 v[122:125], v[78:81], v[106:109], v[26:29]
	v_mfma_f32_16x16x32_bf16 v[26:29], v[46:49], v[190:193], v[82:85]
	v_mfma_f32_16x16x32_bf16 v[114:117], v[78:81], v[194:197], v[26:29]
	v_mfma_f32_16x16x32_bf16 v[26:29], v[198:201], v[98:101], v[90:93]
	v_mfma_f32_16x16x32_bf16 v[106:109], v[208:211], v[106:109], v[26:29]
	v_mfma_f32_16x16x32_bf16 v[26:29], v[198:201], v[190:193], v[220:223]
	v_mfma_f32_16x16x32_bf16 v[98:101], v[208:211], v[194:197], v[26:29]
	s_setprio 0
	s_setprio 1
	v_mfma_f32_16x16x32_bf16 v[26:29], v[14:17], v[30:33], v[224:227]
	v_mfma_f32_16x16x32_bf16 v[14:17], v[14:17], v[54:57], v[228:231]
	v_mfma_f32_16x16x32_bf16 v[90:93], v[18:21], v[42:45], v[26:29]
	v_mfma_f32_16x16x32_bf16 v[26:29], v[18:21], v[212:215], v[14:17]
	v_mfma_f32_16x16x32_bf16 v[14:17], v[22:25], v[30:33], v[232:235]
	v_mfma_f32_16x16x32_bf16 v[86:89], v[34:37], v[42:45], v[14:17]
	v_mfma_f32_16x16x32_bf16 v[14:17], v[22:25], v[54:57], v[236:239]
	v_mfma_f32_16x16x32_bf16 v[22:25], v[34:37], v[212:215], v[14:17]
	v_mfma_f32_16x16x32_bf16 v[14:17], v[46:49], v[30:33], v[240:243]
	v_mfma_f32_16x16x32_bf16 v[82:85], v[78:81], v[42:45], v[14:17]
	v_mfma_f32_16x16x32_bf16 v[14:17], v[46:49], v[54:57], v[178:181]
	v_mfma_f32_16x16x32_bf16 v[18:21], v[78:81], v[212:215], v[14:17]
	v_mfma_f32_16x16x32_bf16 v[14:17], v[198:201], v[30:33], v[182:185]
	v_mfma_f32_16x16x32_bf16 v[78:81], v[208:211], v[42:45], v[14:17]
	v_mfma_f32_16x16x32_bf16 v[14:17], v[198:201], v[54:57], v[186:189]
	v_mfma_f32_16x16x32_bf16 v[14:17], v[208:211], v[212:215], v[14:17]
	s_setprio 0
	s_barrier
	s_and_saveexec_b64 s[8:9], s[6:7]
	s_cbranch_execz .LBB0_1156
	s_barrier

; #define LDA(dst, b, h)                                                                                     \
;   _Pragma("unroll") for (int m = 0; m < 4; ++m) _Pragma("unroll") for (int k = 0; k < 2; ++k) dst[m][k] = \
;       *reinterpret_cast<const bf16x8*>(shmc + aL + (((b) * 2 + (h)) * 16384 + (m * 2 + k) * 1024))
; #define LDB(dst, b, h)                                                                                     \
;   _Pragma("unroll") for (int n = 0; n < 2; ++n) _Pragma("unroll") for (int k = 0; k < 2; ++k) dst[n][k] = \
;       *reinterpret_cast<const bf16x8*>(shmc + bL + (((b) * 2 + (h)) * 16384 + (n * 2 + k) * 1024))
; #define OPAQ asm volatile("" : "+v"(aL), "+v"(bL))
; #define WAIT_V(n) asm volatile("s_waitcnt vmcnt(" #n ")" ::: "memory")
; #define WAIT_L(n) asm volatile("s_waitcnt lgkmcnt(" #n ")" ::: "memory")
; #define BAR __builtin_amdgcn_s_barrier()
; #define SCHED __builtin_amdgcn_sched_barrier(0)
; template <int EPI>
; __device__ __forceinline__ void phase_gemm(const Params& p, const GemmDesc& d, char* shmc) {
;     ...
;     for (int t = 0; t < nt - 2; t += 2) {
;       OPAQ;
;       LDB(B0, 0, 0); SCHED; LDA(At, 0, 0); STAGE_A(SA(1, 1), 1, t + 1);
;       WAIT_L(8); BAR; WAIT_L(0); MMA(0, 0, At, B0); BAR; SCHED;
;       LDB(B1, 0, 1); STAGE_B(SB(0, 0), 0, t + 2);
;       BAR; WAIT_L(0); MMA(0, 1, At, B1); BAR;
;       LDA(At, 0, 1); STAGE_A(SA(0, 0), 0, t + 2);
;       BAR; WAIT_L(0); MMA(1, 0, At, B0); BAR; SCHED;
;       STAGE_B(SB(0, 1), 1, t + 2);
;       WAIT_V(6); BAR; MMA(1, 1, At, B1); BAR;
;       LDB(B0, 1, 0); SCHED; LDA(At, 1, 0); STAGE_A(SA(0, 1), 1, t + 2);
;       WAIT_L(8); BAR; WAIT_L(0); MMA(0, 0, At, B0); BAR; SCHED;
.LBB0_1312:
	s_nop 0
	v_add_u32_e32 v130, 0, v153
	v_add_u32_e32 v141, 0, v152
	s_setprio 0
	ds_read_b128 v[156:159], v130
	ds_read_b128 v[160:163], v130 offset:1024
	ds_read_b128 v[164:167], v130 offset:2048
	ds_read_b128 v[168:171], v130 offset:3072
	ds_read_b128 v[204:207], v130 offset:16384
	ds_read_b128 v[208:211], v130 offset:17408
	ds_read_b128 v[212:215], v130 offset:18432
	ds_read_b128 v[216:219], v130 offset:19456
	v_lshl_add_u64 v[220:221], v[148:149], 0, s[40:41]
	v_lshl_add_u64 v[222:223], v[150:151], 0, s[40:41]
	v_lshl_add_u64 v[224:225], v[144:145], 0, s[40:41]
	v_lshl_add_u64 v[226:227], v[146:147], 0, s[40:41]
	ds_read_b128 v[172:175], v141
	ds_read_b128 v[176:179], v141 offset:1024
	ds_read_b128 v[180:183], v141 offset:2048
	ds_read_b128 v[184:187], v141 offset:3072
	ds_read_b128 v[188:191], v141 offset:4096
	ds_read_b128 v[192:195], v141 offset:5120
	ds_read_b128 v[196:199], v141 offset:6144
	ds_read_b128 v[200:203], v141 offset:7168
	s_mov_b32 m0, s59
	v_lshl_add_u64 v[228:229], v[220:221], 0, s[10:11]
	global_load_lds_dwordx4 v[228:229], off
	v_lshl_add_u64 v[228:229], v[222:223], 0, s[10:11]
	s_mov_b32 m0, s60
	s_nop 0
	global_load_lds_dwordx4 v[228:229], off
	s_waitcnt vmcnt(8)
	s_waitcnt lgkmcnt(0)
	s_setprio 1
	s_barrier
	v_mfma_f32_16x16x32_bf16 v[126:129], v[156:159], v[172:175], v[126:129]
	v_mfma_f32_16x16x32_bf16 v[122:125], v[164:167], v[172:175], v[122:125]
	v_mfma_f32_16x16x32_bf16 v[118:121], v[156:159], v[180:183], v[118:121]
	v_mfma_f32_16x16x32_bf16 v[114:117], v[164:167], v[180:183], v[114:117]
	v_mfma_f32_16x16x32_bf16 v[110:113], v[156:159], v[188:191], v[110:113]
	v_mfma_f32_16x16x32_bf16 v[106:109], v[164:167], v[188:191], v[106:109]
	v_mfma_f32_16x16x32_bf16 v[102:105], v[156:159], v[196:199], v[102:105]
	v_mfma_f32_16x16x32_bf16 v[98:101], v[164:167], v[196:199], v[98:101]
	v_mfma_f32_16x16x32_bf16 v[126:129], v[160:163], v[176:179], v[126:129]
	v_mfma_f32_16x16x32_bf16 v[122:125], v[168:171], v[176:179], v[122:125]
	v_mfma_f32_16x16x32_bf16 v[118:121], v[160:163], v[184:187], v[118:121]
	v_mfma_f32_16x16x32_bf16 v[114:117], v[168:171], v[184:187], v[114:117]
	v_mfma_f32_16x16x32_bf16 v[110:113], v[160:163], v[192:195], v[110:113]
	v_mfma_f32_16x16x32_bf16 v[106:109], v[168:171], v[192:195], v[106:109]
	v_mfma_f32_16x16x32_bf16 v[102:105], v[160:163], v[200:203], v[102:105]
	v_mfma_f32_16x16x32_bf16 v[98:101], v[168:171], v[200:203], v[98:101]
	v_mfma_f32_16x16x32_bf16 v[86:89], v[204:207], v[172:175], v[86:89]
	v_mfma_f32_16x16x32_bf16 v[70:73], v[212:215], v[172:175], v[70:73]
	v_mfma_f32_16x16x32_bf16 v[54:57], v[204:207], v[180:183], v[54:57]
	v_mfma_f32_16x16x32_bf16 v[50:53], v[212:215], v[180:183], v[50:53]
	v_mfma_f32_16x16x32_bf16 v[46:49], v[204:207], v[188:191], v[46:49]
	v_mfma_f32_16x16x32_bf16 v[42:45], v[212:215], v[188:191], v[42:45]
	v_mfma_f32_16x16x32_bf16 v[38:41], v[204:207], v[196:199], v[38:41]
	v_mfma_f32_16x16x32_bf16 v[34:37], v[212:215], v[196:199], v[34:37]
	v_mfma_f32_16x16x32_bf16 v[86:89], v[208:211], v[176:179], v[86:89]
	v_mfma_f32_16x16x32_bf16 v[70:73], v[216:219], v[176:179], v[70:73]
	v_mfma_f32_16x16x32_bf16 v[54:57], v[208:211], v[184:187], v[54:57]
	v_mfma_f32_16x16x32_bf16 v[50:53], v[216:219], v[184:187], v[50:53]
	v_mfma_f32_16x16x32_bf16 v[46:49], v[208:211], v[192:195], v[46:49]
	v_mfma_f32_16x16x32_bf16 v[42:45], v[216:219], v[192:195], v[42:45]
	v_mfma_f32_16x16x32_bf16 v[38:41], v[208:211], v[200:203], v[38:41]
	v_mfma_f32_16x16x32_bf16 v[34:37], v[216:219], v[200:203], v[34:37]
	s_barrier
	s_setprio 0
	ds_read_b128 v[172:175], v141 offset:16384
	ds_read_b128 v[176:179], v141 offset:17408
	ds_read_b128 v[180:183], v141 offset:18432
	ds_read_b128 v[184:187], v141 offset:19456
	ds_read_b128 v[188:191], v141 offset:20480
	ds_read_b128 v[192:195], v141 offset:21504
	ds_read_b128 v[196:199], v141 offset:22528
	ds_read_b128 v[200:203], v141 offset:23552
	s_mov_b32 m0, s34
	v_lshl_add_u64 v[228:229], v[224:225], 0, s[18:19]
	global_load_lds_dwordx4 v[228:229], off
	v_lshl_add_u64 v[228:229], v[226:227], 0, s[18:19]
	s_mov_b32 m0, s35
	s_nop 0
	global_load_lds_dwordx4 v[228:229], off
	s_mov_b32 m0, s33
	v_lshl_add_u64 v[228:229], v[220:221], 0, s[20:21]
	global_load_lds_dwordx4 v[228:229], off
	v_lshl_add_u64 v[228:229], v[222:223], 0, s[20:21]
	s_mov_b32 m0, s46
	s_nop 0
	global_load_lds_dwordx4 v[228:229], off
	s_mov_b32 m0, s47
	v_lshl_add_u64 v[228:229], v[224:225], 0, s[22:23]
	global_load_lds_dwordx4 v[228:229], off
	v_lshl_add_u64 v[228:229], v[226:227], 0, s[22:23]
	s_mov_b32 m0, s48
	s_nop 0
	global_load_lds_dwordx4 v[228:229], off
	s_waitcnt vmcnt(8)
	s_waitcnt lgkmcnt(0)
	s_setprio 1
	s_barrier
; #define LDA(dst, b, h)                                                                                     \
;   _Pragma("unroll") for (int m = 0; m < 4; ++m) _Pragma("unroll") for (int k = 0; k < 2; ++k) dst[m][k] = \
;       *reinterpret_cast<const bf16x8*>(shmc + aL + (((b) * 2 + (h)) * 16384 + (m * 2 + k) * 1024))
; #define LDB(dst, b, h)                                                                                     \
;   _Pragma("unroll") for (int n = 0; n < 2; ++n) _Pragma("unroll") for (int k = 0; k < 2; ++k) dst[n][k] = \
;       *reinterpret_cast<const bf16x8*>(shmc + bL + (((b) * 2 + (h)) * 16384 + (n * 2 + k) * 1024))
; #define WAIT_V(n) asm volatile("s_waitcnt vmcnt(" #n ")" ::: "memory")
; #define WAIT_L(n) asm volatile("s_waitcnt lgkmcnt(" #n ")" ::: "memory")
; #define BAR __builtin_amdgcn_s_barrier()
; #define SCHED __builtin_amdgcn_sched_barrier(0)
; template <int EPI>
; __device__ __forceinline__ void phase_gemm(const Params& p, const GemmDesc& d, char* shmc) {
;     ...
;       LDB(B0, 0, 0); SCHED; LDA(At, 0, 0); STAGE_A(SA(1, 1), 1, t + 1);
;       WAIT_L(8); BAR; WAIT_L(0); MMA(0, 0, At, B0); BAR; SCHED;
;       LDB(B1, 0, 1); STAGE_B(SB(0, 0), 0, t + 2);
;       BAR; WAIT_L(0); MMA(0, 1, At, B1); BAR;
;       LDA(At, 0, 1); STAGE_A(SA(0, 0), 0, t + 2);
;       BAR; WAIT_L(0); MMA(1, 0, At, B0); BAR; SCHED;
;       STAGE_B(SB(0, 1), 1, t + 2);
;       WAIT_V(6); BAR; MMA(1, 1, At, B1); BAR;
;       LDB(B0, 1, 0); SCHED; LDA(At, 1, 0); STAGE_A(SA(0, 1), 1, t + 2);
;       WAIT_L(8); BAR; WAIT_L(0); MMA(0, 0, At, B0); BAR; SCHED;
	v_mfma_f32_16x16x32_bf16 v[30:33], v[156:159], v[172:175], v[30:33]
	v_mfma_f32_16x16x32_bf16 v[26:29], v[164:167], v[172:175], v[26:29]
	v_mfma_f32_16x16x32_bf16 v[22:25], v[156:159], v[180:183], v[22:25]
	v_mfma_f32_16x16x32_bf16 v[18:21], v[164:167], v[180:183], v[18:21]
	v_mfma_f32_16x16x32_bf16 v[14:17], v[156:159], v[188:191], v[14:17]
	v_mfma_f32_16x16x32_bf16 v[10:13], v[164:167], v[188:191], v[10:13]
	v_mfma_f32_16x16x32_bf16 v[6:9], v[156:159], v[196:199], v[6:9]
	v_mfma_f32_16x16x32_bf16 v[2:5], v[164:167], v[196:199], v[2:5]
	v_mfma_f32_16x16x32_bf16 v[30:33], v[160:163], v[176:179], v[30:33]
	v_mfma_f32_16x16x32_bf16 v[26:29], v[168:171], v[176:179], v[26:29]
	v_mfma_f32_16x16x32_bf16 v[22:25], v[160:163], v[184:187], v[22:25]
	v_mfma_f32_16x16x32_bf16 v[18:21], v[168:171], v[184:187], v[18:21]
	v_mfma_f32_16x16x32_bf16 v[14:17], v[160:163], v[192:195], v[14:17]
	v_mfma_f32_16x16x32_bf16 v[10:13], v[168:171], v[192:195], v[10:13]
	v_mfma_f32_16x16x32_bf16 v[6:9], v[160:163], v[200:203], v[6:9]
	v_mfma_f32_16x16x32_bf16 v[2:5], v[168:171], v[200:203], v[2:5]
	v_mfma_f32_16x16x32_bf16 v[58:61], v[204:207], v[172:175], v[58:61]
	v_mfma_f32_16x16x32_bf16 v[62:65], v[212:215], v[172:175], v[62:65]
	v_mfma_f32_16x16x32_bf16 v[66:69], v[204:207], v[180:183], v[66:69]
	v_mfma_f32_16x16x32_bf16 v[74:77], v[212:215], v[180:183], v[74:77]
	v_mfma_f32_16x16x32_bf16 v[78:81], v[204:207], v[188:191], v[78:81]
	v_mfma_f32_16x16x32_bf16 v[82:85], v[212:215], v[188:191], v[82:85]
	v_mfma_f32_16x16x32_bf16 v[90:93], v[204:207], v[196:199], v[90:93]
	v_mfma_f32_16x16x32_bf16 v[94:97], v[212:215], v[196:199], v[94:97]
	v_mfma_f32_16x16x32_bf16 v[58:61], v[208:211], v[176:179], v[58:61]
	v_mfma_f32_16x16x32_bf16 v[62:65], v[216:219], v[176:179], v[62:65]
	v_mfma_f32_16x16x32_bf16 v[66:69], v[208:211], v[184:187], v[66:69]
	v_mfma_f32_16x16x32_bf16 v[74:77], v[216:219], v[184:187], v[74:77]
	v_mfma_f32_16x16x32_bf16 v[78:81], v[208:211], v[192:195], v[78:81]
	v_mfma_f32_16x16x32_bf16 v[82:85], v[216:219], v[192:195], v[82:85]
	v_mfma_f32_16x16x32_bf16 v[90:93], v[208:211], v[200:203], v[90:93]
	v_mfma_f32_16x16x32_bf16 v[94:97], v[216:219], v[200:203], v[94:97]
	s_barrier
	s_setprio 0
	ds_read_b128 v[156:159], v130 offset:32768
	ds_read_b128 v[160:163], v130 offset:33792
	ds_read_b128 v[164:167], v130 offset:34816
	ds_read_b128 v[168:171], v130 offset:35840
	ds_read_b128 v[204:207], v130 offset:49152
	ds_read_b128 v[208:211], v130 offset:50176
	ds_read_b128 v[212:215], v130 offset:51200
	ds_read_b128 v[216:219], v130 offset:52224
	ds_read_b128 v[172:175], v141 offset:32768
	ds_read_b128 v[176:179], v141 offset:33792
	ds_read_b128 v[180:183], v141 offset:34816
	ds_read_b128 v[184:187], v141 offset:35840
	ds_read_b128 v[188:191], v141 offset:36864
	ds_read_b128 v[192:195], v141 offset:37888
	ds_read_b128 v[196:199], v141 offset:38912
	ds_read_b128 v[200:203], v141 offset:39936
	s_mov_b32 m0, s49
	v_lshl_add_u64 v[228:229], v[220:221], 0, s[24:25]
	global_load_lds_dwordx4 v[228:229], off
	v_lshl_add_u64 v[228:229], v[222:223], 0, s[24:25]
	s_mov_b32 m0, s52
	s_nop 0
	global_load_lds_dwordx4 v[228:229], off
	s_waitcnt vmcnt(8)
	s_waitcnt lgkmcnt(0)
	s_setprio 1
	s_barrier
	v_mfma_f32_16x16x32_bf16 v[126:129], v[156:159], v[172:175], v[126:129]
	v_mfma_f32_16x16x32_bf16 v[122:125], v[164:167], v[172:175], v[122:125]
	v_mfma_f32_16x16x32_bf16 v[118:121], v[156:159], v[180:183], v[118:121]
	v_mfma_f32_16x16x32_bf16 v[114:117], v[164:167], v[180:183], v[114:117]
	v_mfma_f32_16x16x32_bf16 v[110:113], v[156:159], v[188:191], v[110:113]
	v_mfma_f32_16x16x32_bf16 v[106:109], v[164:167], v[188:191], v[106:109]
	v_mfma_f32_16x16x32_bf16 v[102:105], v[156:159], v[196:199], v[102:105]
	v_mfma_f32_16x16x32_bf16 v[98:101], v[164:167], v[196:199], v[98:101]
	v_mfma_f32_16x16x32_bf16 v[126:129], v[160:163], v[176:179], v[126:129]
	v_mfma_f32_16x16x32_bf16 v[122:125], v[168:171], v[176:179], v[122:125]
	v_mfma_f32_16x16x32_bf16 v[118:121], v[160:163], v[184:187], v[118:121]
	v_mfma_f32_16x16x32_bf16 v[114:117], v[168:171], v[184:187], v[114:117]
	v_mfma_f32_16x16x32_bf16 v[110:113], v[160:163], v[192:195], v[110:113]
	v_mfma_f32_16x16x32_bf16 v[106:109], v[168:171], v[192:195], v[106:109]
	v_mfma_f32_16x16x32_bf16 v[102:105], v[160:163], v[200:203], v[102:105]
	v_mfma_f32_16x16x32_bf16 v[98:101], v[168:171], v[200:203], v[98:101]
	v_mfma_f32_16x16x32_bf16 v[86:89], v[204:207], v[172:175], v[86:89]
	v_mfma_f32_16x16x32_bf16 v[70:73], v[212:215], v[172:175], v[70:73]
	v_mfma_f32_16x16x32_bf16 v[54:57], v[204:207], v[180:183], v[54:57]
	v_mfma_f32_16x16x32_bf16 v[50:53], v[212:215], v[180:183], v[50:53]
	v_mfma_f32_16x16x32_bf16 v[46:49], v[204:207], v[188:191], v[46:49]
	v_mfma_f32_16x16x32_bf16 v[42:45], v[212:215], v[188:191], v[42:45]
	v_mfma_f32_16x16x32_bf16 v[38:41], v[204:207], v[196:199], v[38:41]
	v_mfma_f32_16x16x32_bf16 v[34:37], v[212:215], v[196:199], v[34:37]
	v_mfma_f32_16x16x32_bf16 v[86:89], v[208:211], v[176:179], v[86:89]
	v_mfma_f32_16x16x32_bf16 v[70:73], v[216:219], v[176:179], v[70:73]
	v_mfma_f32_16x16x32_bf16 v[54:57], v[208:211], v[184:187], v[54:57]
	v_mfma_f32_16x16x32_bf16 v[50:53], v[216:219], v[184:187], v[50:53]
	v_mfma_f32_16x16x32_bf16 v[46:49], v[208:211], v[192:195], v[46:49]
	v_mfma_f32_16x16x32_bf16 v[42:45], v[216:219], v[192:195], v[42:45]
	v_mfma_f32_16x16x32_bf16 v[38:41], v[208:211], v[200:203], v[38:41]
	v_mfma_f32_16x16x32_bf16 v[34:37], v[216:219], v[200:203], v[34:37]
	s_barrier
; #define LDA(dst, b, h)                                                                                     \
;   _Pragma("unroll") for (int m = 0; m < 4; ++m) _Pragma("unroll") for (int k = 0; k < 2; ++k) dst[m][k] = \
;       *reinterpret_cast<const bf16x8*>(shmc + aL + (((b) * 2 + (h)) * 16384 + (m * 2 + k) * 1024))
; #define LDB(dst, b, h)                                                                                     \
;   _Pragma("unroll") for (int n = 0; n < 2; ++n) _Pragma("unroll") for (int k = 0; k < 2; ++k) dst[n][k] = \
;       *reinterpret_cast<const bf16x8*>(shmc + bL + (((b) * 2 + (h)) * 16384 + (n * 2 + k) * 1024))
; #define OPAQ asm volatile("" : "+v"(aL), "+v"(bL))
; #define WAIT_V(n) asm volatile("s_waitcnt vmcnt(" #n ")" ::: "memory")
; #define WAIT_L(n) asm volatile("s_waitcnt lgkmcnt(" #n ")" ::: "memory")
; #define BAR __builtin_amdgcn_s_barrier()
; #define SCHED __builtin_amdgcn_sched_barrier(0)
; template <int EPI>
; __device__ __forceinline__ void phase_gemm(const Params& p, const GemmDesc& d, char* shmc) {
;     ...
;       LDB(B1, 1, 1); STAGE_B(SB(1, 0), 0, t + 3);
;       BAR; WAIT_L(0); MMA(0, 1, At, B1); BAR;
;       LDA(At, 1, 1); STAGE_A(SA(1, 0), 0, t + 3);
;       BAR; WAIT_L(0); MMA(1, 0, At, B0); BAR; SCHED;
;       STAGE_B(SB(1, 1), 1, t + 3);
;       WAIT_V(6); BAR; MMA(1, 1, At, B1); BAR;
;     }
;     {
;       OPAQ;
;       LDB(B0, 0, 0); LDA(At, 0, 0); STAGE_A(SA(1, 1), 1, nt - 1);
;       BAR; WAIT_L(0); MMA(0, 0, At, B0); BAR;
;       LDB(B1, 0, 1); BAR; WAIT_L(0); MMA(0, 1, At, B1); BAR;
;       LDA(At, 0, 1); WAIT_V(4); BAR; WAIT_L(0); MMA(1, 0, At, B0); MMA(1, 1, At, B1); BAR;
	s_setprio 0
	ds_read_b128 v[172:175], v141 offset:49152
	ds_read_b128 v[176:179], v141 offset:50176
	ds_read_b128 v[180:183], v141 offset:51200
	ds_read_b128 v[184:187], v141 offset:52224
	ds_read_b128 v[188:191], v141 offset:53248
	ds_read_b128 v[192:195], v141 offset:54272
	ds_read_b128 v[196:199], v141 offset:55296
	ds_read_b128 v[200:203], v141 offset:56320
	s_mov_b32 m0, s53
	v_lshl_add_u64 v[228:229], v[224:225], 0, s[26:27]
	global_load_lds_dwordx4 v[228:229], off
	v_lshl_add_u64 v[228:229], v[226:227], 0, s[26:27]
	s_mov_b32 m0, s54
	s_nop 0
	global_load_lds_dwordx4 v[228:229], off
	s_mov_b32 m0, s55
	v_lshl_add_u64 v[228:229], v[220:221], 0, s[30:31]
	global_load_lds_dwordx4 v[228:229], off
	v_lshl_add_u64 v[228:229], v[222:223], 0, s[30:31]
	s_mov_b32 m0, s56
	s_nop 0
	global_load_lds_dwordx4 v[228:229], off
	s_mov_b32 m0, s57
	v_lshl_add_u64 v[228:229], v[224:225], 0, s[36:37]
	global_load_lds_dwordx4 v[228:229], off
	v_lshl_add_u64 v[228:229], v[226:227], 0, s[36:37]
	s_mov_b32 m0, s58
	s_nop 0
	global_load_lds_dwordx4 v[228:229], off
	s_add_i32 s42, s42, 2
	s_add_u32 s40, s40, 0x100
	s_addc_u32 s41, s41, 0
	s_cmpk_gt_u32 s42, 0x53
	s_waitcnt vmcnt(8)
	s_waitcnt lgkmcnt(0)
	s_setprio 1
	s_barrier
	v_mfma_f32_16x16x32_bf16 v[30:33], v[156:159], v[172:175], v[30:33]
	v_mfma_f32_16x16x32_bf16 v[26:29], v[164:167], v[172:175], v[26:29]
	v_mfma_f32_16x16x32_bf16 v[22:25], v[156:159], v[180:183], v[22:25]
	v_mfma_f32_16x16x32_bf16 v[18:21], v[164:167], v[180:183], v[18:21]
	v_mfma_f32_16x16x32_bf16 v[14:17], v[156:159], v[188:191], v[14:17]
	v_mfma_f32_16x16x32_bf16 v[10:13], v[164:167], v[188:191], v[10:13]
	v_mfma_f32_16x16x32_bf16 v[6:9], v[156:159], v[196:199], v[6:9]
	v_mfma_f32_16x16x32_bf16 v[2:5], v[164:167], v[196:199], v[2:5]
	v_mfma_f32_16x16x32_bf16 v[30:33], v[160:163], v[176:179], v[30:33]
	v_mfma_f32_16x16x32_bf16 v[26:29], v[168:171], v[176:179], v[26:29]
	v_mfma_f32_16x16x32_bf16 v[22:25], v[160:163], v[184:187], v[22:25]
	v_mfma_f32_16x16x32_bf16 v[18:21], v[168:171], v[184:187], v[18:21]
	v_mfma_f32_16x16x32_bf16 v[14:17], v[160:163], v[192:195], v[14:17]
	v_mfma_f32_16x16x32_bf16 v[10:13], v[168:171], v[192:195], v[10:13]
	v_mfma_f32_16x16x32_bf16 v[6:9], v[160:163], v[200:203], v[6:9]
	v_mfma_f32_16x16x32_bf16 v[2:5], v[168:171], v[200:203], v[2:5]
	v_mfma_f32_16x16x32_bf16 v[58:61], v[204:207], v[172:175], v[58:61]
	v_mfma_f32_16x16x32_bf16 v[62:65], v[212:215], v[172:175], v[62:65]
	v_mfma_f32_16x16x32_bf16 v[66:69], v[204:207], v[180:183], v[66:69]
	v_mfma_f32_16x16x32_bf16 v[74:77], v[212:215], v[180:183], v[74:77]
	v_mfma_f32_16x16x32_bf16 v[78:81], v[204:207], v[188:191], v[78:81]
	v_mfma_f32_16x16x32_bf16 v[82:85], v[212:215], v[188:191], v[82:85]
	v_mfma_f32_16x16x32_bf16 v[90:93], v[204:207], v[196:199], v[90:93]
	v_mfma_f32_16x16x32_bf16 v[94:97], v[212:215], v[196:199], v[94:97]
	v_mfma_f32_16x16x32_bf16 v[58:61], v[208:211], v[176:179], v[58:61]
	v_mfma_f32_16x16x32_bf16 v[62:65], v[216:219], v[176:179], v[62:65]
	v_mfma_f32_16x16x32_bf16 v[66:69], v[208:211], v[184:187], v[66:69]
	v_mfma_f32_16x16x32_bf16 v[74:77], v[216:219], v[184:187], v[74:77]
	v_mfma_f32_16x16x32_bf16 v[78:81], v[208:211], v[192:195], v[78:81]
	v_mfma_f32_16x16x32_bf16 v[82:85], v[216:219], v[192:195], v[82:85]
	v_mfma_f32_16x16x32_bf16 v[90:93], v[208:211], v[200:203], v[90:93]
	v_mfma_f32_16x16x32_bf16 v[94:97], v[216:219], v[200:203], v[94:97]
	s_barrier
	s_cbranch_scc0 .LBB0_1312
	s_setprio 0
	s_add_u32 s38, s38, 0x162b80
	s_addc_u32 s39, s39, 0
	v_add_u32_e32 v130, 0, v153
	v_add_u32_e32 v141, 0, v152
	s_mov_b32 m0, s59
	ds_read_b128 v[144:147], v130
	ds_read_b128 v[148:151], v130 offset:1024
	ds_read_b128 v[156:159], v130 offset:2048
	ds_read_b128 v[160:163], v130 offset:3072
	ds_read_b128 v[164:167], v141
	ds_read_b128 v[168:171], v141 offset:1024
	ds_read_b128 v[172:175], v141 offset:2048
	ds_read_b128 v[176:179], v141 offset:3072
	ds_read_b128 v[180:183], v141 offset:4096
	ds_read_b128 v[184:187], v141 offset:5120
	ds_read_b128 v[188:191], v141 offset:6144
	ds_read_b128 v[192:195], v141 offset:7168
	global_load_lds_dwordx4 v140, s[38:39]
	s_mov_b32 m0, s60
	s_nop 0
	global_load_lds_dwordx4 v142, s[38:39]
	s_waitcnt vmcnt(8)
	s_barrier
	s_waitcnt lgkmcnt(0)
	s_setprio 1
	s_waitcnt lgkmcnt(0)
	v_mfma_f32_16x16x32_bf16 v[126:129], v[144:147], v[164:167], v[126:129]
	v_mfma_f32_16x16x32_bf16 v[122:125], v[156:159], v[164:167], v[122:125]
	v_mfma_f32_16x16x32_bf16 v[114:117], v[156:159], v[172:175], v[114:117]
	v_mfma_f32_16x16x32_bf16 v[110:113], v[144:147], v[180:183], v[110:113]
	v_mfma_f32_16x16x32_bf16 v[102:105], v[144:147], v[188:191], v[102:105]
	v_mfma_f32_16x16x32_bf16 v[126:129], v[148:151], v[168:171], v[126:129]
	v_mfma_f32_16x16x32_bf16 v[122:125], v[160:163], v[168:171], v[122:125]
	v_mfma_f32_16x16x32_bf16 v[118:121], v[144:147], v[172:175], v[118:121]
	v_mfma_f32_16x16x32_bf16 v[114:117], v[160:163], v[176:179], v[114:117]
	v_mfma_f32_16x16x32_bf16 v[110:113], v[148:151], v[184:187], v[110:113]
	v_mfma_f32_16x16x32_bf16 v[106:109], v[156:159], v[180:183], v[106:109]
	v_mfma_f32_16x16x32_bf16 v[102:105], v[148:151], v[192:195], v[102:105]
	v_mfma_f32_16x16x32_bf16 v[98:101], v[156:159], v[188:191], v[98:101]
	v_mfma_f32_16x16x32_bf16 v[196:199], v[148:151], v[176:179], v[118:121]
	v_mfma_f32_16x16x32_bf16 v[200:203], v[160:163], v[184:187], v[106:109]
	v_mfma_f32_16x16x32_bf16 v[204:207], v[160:163], v[192:195], v[98:101]
	s_setprio 0
	s_barrier
	s_nop 2
	ds_read_b128 v[98:101], v130 offset:16384
	ds_read_b128 v[106:109], v130 offset:17408
	ds_read_b128 v[118:121], v130 offset:18432
	ds_read_b128 v[208:211], v130 offset:19456
	s_barrier
; #define LDA(dst, b, h)                                                                                     \
;   _Pragma("unroll") for (int m = 0; m < 4; ++m) _Pragma("unroll") for (int k = 0; k < 2; ++k) dst[m][k] = \
;       *reinterpret_cast<const bf16x8*>(shmc + aL + (((b) * 2 + (h)) * 16384 + (m * 2 + k) * 1024))
; #define LDB(dst, b, h)                                                                                     \
;   _Pragma("unroll") for (int n = 0; n < 2; ++n) _Pragma("unroll") for (int k = 0; k < 2; ++k) dst[n][k] = \
;       *reinterpret_cast<const bf16x8*>(shmc + bL + (((b) * 2 + (h)) * 16384 + (n * 2 + k) * 1024))
; #define WAIT_V(n) asm volatile("s_waitcnt vmcnt(" #n ")" ::: "memory")
; #define WAIT_L(n) asm volatile("s_waitcnt lgkmcnt(" #n ")" ::: "memory")
; #define BAR __builtin_amdgcn_s_barrier()
; template <int EPI>
; __device__ __forceinline__ void phase_gemm(const Params& p, const GemmDesc& d, char* shmc) {
;     ...
;       BAR; WAIT_L(0); MMA(0, 0, At, B0); BAR;
;       LDB(B1, 0, 1); BAR; WAIT_L(0); MMA(0, 1, At, B1); BAR;
;       LDA(At, 0, 1); WAIT_V(4); BAR; WAIT_L(0); MMA(1, 0, At, B0); MMA(1, 1, At, B1); BAR;
;     }
;     {
;       LDB(B0, 1, 0); LDA(At, 1, 0); WAIT_V(2); BAR; WAIT_L(0); MMA(0, 0, At, B0); BAR;
	s_waitcnt lgkmcnt(0)
	s_setprio 1
	s_waitcnt lgkmcnt(0)
	v_mfma_f32_16x16x32_bf16 v[86:89], v[98:101], v[164:167], v[86:89]
	v_mfma_f32_16x16x32_bf16 v[70:73], v[118:121], v[164:167], v[70:73]
	v_mfma_f32_16x16x32_bf16 v[54:57], v[98:101], v[172:175], v[54:57]
	v_mfma_f32_16x16x32_bf16 v[50:53], v[118:121], v[172:175], v[50:53]
	v_mfma_f32_16x16x32_bf16 v[46:49], v[98:101], v[180:183], v[46:49]
	v_mfma_f32_16x16x32_bf16 v[42:45], v[118:121], v[180:183], v[42:45]
	v_mfma_f32_16x16x32_bf16 v[38:41], v[98:101], v[188:191], v[38:41]
	v_mfma_f32_16x16x32_bf16 v[34:37], v[118:121], v[188:191], v[34:37]
	v_mfma_f32_16x16x32_bf16 v[86:89], v[106:109], v[168:171], v[86:89]
	v_mfma_f32_16x16x32_bf16 v[70:73], v[208:211], v[168:171], v[70:73]
	v_mfma_f32_16x16x32_bf16 v[54:57], v[106:109], v[176:179], v[54:57]
	v_mfma_f32_16x16x32_bf16 v[50:53], v[208:211], v[176:179], v[50:53]
	v_mfma_f32_16x16x32_bf16 v[46:49], v[106:109], v[184:187], v[46:49]
	v_mfma_f32_16x16x32_bf16 v[42:45], v[208:211], v[184:187], v[42:45]
	v_mfma_f32_16x16x32_bf16 v[38:41], v[106:109], v[192:195], v[38:41]
	v_mfma_f32_16x16x32_bf16 v[34:37], v[208:211], v[192:195], v[34:37]
	s_setprio 0
	s_barrier
	ds_read_b128 v[164:167], v141 offset:16384
	ds_read_b128 v[168:171], v141 offset:17408
	ds_read_b128 v[172:175], v141 offset:18432
	ds_read_b128 v[176:179], v141 offset:19456
	ds_read_b128 v[180:183], v141 offset:20480
	ds_read_b128 v[184:187], v141 offset:21504
	ds_read_b128 v[188:191], v141 offset:22528
	ds_read_b128 v[192:195], v141 offset:23552
	s_waitcnt vmcnt(4)
	s_barrier
	s_waitcnt lgkmcnt(0)
	s_setprio 1
	s_waitcnt lgkmcnt(0)
	v_mfma_f32_16x16x32_bf16 v[30:33], v[144:147], v[164:167], v[30:33]
	v_mfma_f32_16x16x32_bf16 v[26:29], v[156:159], v[164:167], v[26:29]
	v_mfma_f32_16x16x32_bf16 v[22:25], v[144:147], v[172:175], v[22:25]
	v_mfma_f32_16x16x32_bf16 v[18:21], v[156:159], v[172:175], v[18:21]
	v_mfma_f32_16x16x32_bf16 v[14:17], v[144:147], v[180:183], v[14:17]
	v_mfma_f32_16x16x32_bf16 v[10:13], v[156:159], v[180:183], v[10:13]
	v_mfma_f32_16x16x32_bf16 v[6:9], v[144:147], v[188:191], v[6:9]
	v_mfma_f32_16x16x32_bf16 v[2:5], v[156:159], v[188:191], v[2:5]
	v_mfma_f32_16x16x32_bf16 v[30:33], v[148:151], v[168:171], v[30:33]
	v_mfma_f32_16x16x32_bf16 v[26:29], v[160:163], v[168:171], v[26:29]
	v_mfma_f32_16x16x32_bf16 v[22:25], v[148:151], v[176:179], v[22:25]
	v_mfma_f32_16x16x32_bf16 v[18:21], v[160:163], v[176:179], v[18:21]
	v_mfma_f32_16x16x32_bf16 v[14:17], v[148:151], v[184:187], v[14:17]
	v_mfma_f32_16x16x32_bf16 v[10:13], v[160:163], v[184:187], v[10:13]
	v_mfma_f32_16x16x32_bf16 v[6:9], v[148:151], v[192:195], v[6:9]
	v_mfma_f32_16x16x32_bf16 v[2:5], v[160:163], v[192:195], v[2:5]
	s_setprio 0
	s_setprio 1
	v_mfma_f32_16x16x32_bf16 v[62:65], v[118:121], v[164:167], v[62:65]
	v_mfma_f32_16x16x32_bf16 v[144:147], v[208:211], v[168:171], v[62:65]
	v_mfma_f32_16x16x32_bf16 v[62:65], v[98:101], v[172:175], v[66:69]
	v_mfma_f32_16x16x32_bf16 v[148:151], v[106:109], v[176:179], v[62:65]
	v_mfma_f32_16x16x32_bf16 v[62:65], v[118:121], v[172:175], v[74:77]
	v_mfma_f32_16x16x32_bf16 v[156:159], v[208:211], v[176:179], v[62:65]
	v_mfma_f32_16x16x32_bf16 v[62:65], v[98:101], v[180:183], v[78:81]
	v_mfma_f32_16x16x32_bf16 v[160:163], v[106:109], v[184:187], v[62:65]
	v_mfma_f32_16x16x32_bf16 v[62:65], v[118:121], v[180:183], v[82:85]
	v_mfma_f32_16x16x32_bf16 v[58:61], v[98:101], v[164:167], v[58:61]
	v_mfma_f32_16x16x32_bf16 v[164:167], v[208:211], v[184:187], v[62:65]
	v_mfma_f32_16x16x32_bf16 v[62:65], v[98:101], v[188:191], v[90:93]
	v_mfma_f32_16x16x32_bf16 v[58:61], v[106:109], v[168:171], v[58:61]
	v_mfma_f32_16x16x32_bf16 v[168:171], v[106:109], v[192:195], v[62:65]
	v_mfma_f32_16x16x32_bf16 v[62:65], v[118:121], v[188:191], v[94:97]
	v_mfma_f32_16x16x32_bf16 v[172:175], v[208:211], v[192:195], v[62:65]
	s_setprio 0
	s_barrier
	ds_read_b128 v[176:179], v130 offset:32768
	ds_read_b128 v[180:183], v130 offset:33792
	ds_read_b128 v[184:187], v130 offset:34816
	ds_read_b128 v[188:191], v130 offset:35840
	s_nop 0
	ds_read_b128 v[62:65], v141 offset:32768
	ds_read_b128 v[78:81], v141 offset:33792
	ds_read_b128 v[94:97], v141 offset:34816
	ds_read_b128 v[192:195], v141 offset:35840
	ds_read_b128 v[208:211], v141 offset:36864
	ds_read_b128 v[212:215], v141 offset:37888
	ds_read_b128 v[216:219], v141 offset:38912
	ds_read_b128 v[220:223], v141 offset:39936
	s_waitcnt vmcnt(2)
	s_barrier
; #define LDA(dst, b, h)                                                                                     \
;   _Pragma("unroll") for (int m = 0; m < 4; ++m) _Pragma("unroll") for (int k = 0; k < 2; ++k) dst[m][k] = \
;       *reinterpret_cast<const bf16x8*>(shmc + aL + (((b) * 2 + (h)) * 16384 + (m * 2 + k) * 1024))
; #define LDB(dst, b, h)                                                                                     \
;   _Pragma("unroll") for (int n = 0; n < 2; ++n) _Pragma("unroll") for (int k = 0; k < 2; ++k) dst[n][k] = \
;       *reinterpret_cast<const bf16x8*>(shmc + bL + (((b) * 2 + (h)) * 16384 + (n * 2 + k) * 1024))
; #define WAIT_V(n) asm volatile("s_waitcnt vmcnt(" #n ")" ::: "memory")
; #define WAIT_L(n) asm volatile("s_waitcnt lgkmcnt(" #n ")" ::: "memory")
; #define BAR __builtin_amdgcn_s_barrier()
; template <int EPI>
; __device__ __forceinline__ void phase_gemm(const Params& p, const GemmDesc& d, char* shmc) {
;     ...
;       LDB(B0, 1, 0); LDA(At, 1, 0); WAIT_V(2); BAR; WAIT_L(0); MMA(0, 0, At, B0); BAR;
;       LDB(B1, 1, 1); WAIT_V(0); BAR; WAIT_L(0); MMA(0, 1, At, B1); BAR;
;       LDA(At, 1, 1); BAR; WAIT_L(0); MMA(1, 0, At, B0); MMA(1, 1, At, B1); BAR;
;     }
;     if (wr == 0) BAR;
	s_waitcnt lgkmcnt(0)
	s_setprio 1
	s_waitcnt lgkmcnt(0)
	v_mfma_f32_16x16x32_bf16 v[66:69], v[176:179], v[62:65], v[126:129]
	v_mfma_f32_16x16x32_bf16 v[126:129], v[180:183], v[78:81], v[66:69]
	v_mfma_f32_16x16x32_bf16 v[66:69], v[184:187], v[62:65], v[122:125]
	v_mfma_f32_16x16x32_bf16 v[118:121], v[188:191], v[78:81], v[66:69]
	v_mfma_f32_16x16x32_bf16 v[66:69], v[176:179], v[94:97], v[196:199]
	v_mfma_f32_16x16x32_bf16 v[106:109], v[180:183], v[192:195], v[66:69]
	v_mfma_f32_16x16x32_bf16 v[66:69], v[184:187], v[94:97], v[114:117]
	v_mfma_f32_16x16x32_bf16 v[98:101], v[188:191], v[192:195], v[66:69]
	v_mfma_f32_16x16x32_bf16 v[66:69], v[176:179], v[208:211], v[110:113]
	v_mfma_f32_16x16x32_bf16 v[90:93], v[180:183], v[212:215], v[66:69]
	v_mfma_f32_16x16x32_bf16 v[66:69], v[184:187], v[208:211], v[200:203]
	v_mfma_f32_16x16x32_bf16 v[82:85], v[188:191], v[212:215], v[66:69]
	v_mfma_f32_16x16x32_bf16 v[66:69], v[176:179], v[216:219], v[102:105]
	v_mfma_f32_16x16x32_bf16 v[74:77], v[180:183], v[220:223], v[66:69]
	v_mfma_f32_16x16x32_bf16 v[66:69], v[184:187], v[216:219], v[204:207]
	v_mfma_f32_16x16x32_bf16 v[66:69], v[188:191], v[220:223], v[66:69]
	s_setprio 0
	s_barrier
	ds_read_b128 v[196:199], v130 offset:49152
	ds_read_b128 v[200:203], v130 offset:50176
	ds_read_b128 v[204:207], v130 offset:51200
	ds_read_b128 v[224:227], v130 offset:52224
	s_waitcnt vmcnt(0)
	s_barrier
	s_waitcnt lgkmcnt(0)
	s_setprio 1
	s_waitcnt lgkmcnt(0)
	v_mfma_f32_16x16x32_bf16 v[86:89], v[196:199], v[62:65], v[86:89]
	v_mfma_f32_16x16x32_bf16 v[62:65], v[204:207], v[62:65], v[70:73]
	v_mfma_f32_16x16x32_bf16 v[54:57], v[196:199], v[94:97], v[54:57]
	v_mfma_f32_16x16x32_bf16 v[50:53], v[204:207], v[94:97], v[50:53]
	v_mfma_f32_16x16x32_bf16 v[46:49], v[196:199], v[208:211], v[46:49]
	v_mfma_f32_16x16x32_bf16 v[42:45], v[204:207], v[208:211], v[42:45]
	v_mfma_f32_16x16x32_bf16 v[38:41], v[196:199], v[216:219], v[38:41]
	v_mfma_f32_16x16x32_bf16 v[34:37], v[204:207], v[216:219], v[34:37]
	v_mfma_f32_16x16x32_bf16 v[122:125], v[200:203], v[78:81], v[86:89]
	v_mfma_f32_16x16x32_bf16 v[114:117], v[224:227], v[78:81], v[62:65]
	v_mfma_f32_16x16x32_bf16 v[110:113], v[200:203], v[192:195], v[54:57]
	v_mfma_f32_16x16x32_bf16 v[102:105], v[224:227], v[192:195], v[50:53]
	v_mfma_f32_16x16x32_bf16 v[94:97], v[200:203], v[212:215], v[46:49]
	v_mfma_f32_16x16x32_bf16 v[86:89], v[224:227], v[212:215], v[42:45]
	v_mfma_f32_16x16x32_bf16 v[78:81], v[200:203], v[220:223], v[38:41]
	v_mfma_f32_16x16x32_bf16 v[70:73], v[224:227], v[220:223], v[34:37]
	s_setprio 0
	s_barrier
	s_nop 0
	ds_read_b128 v[34:37], v141 offset:49152
	ds_read_b128 v[42:45], v141 offset:50176
	ds_read_b128 v[192:195], v141 offset:51200
	ds_read_b128 v[208:211], v141 offset:52224
	ds_read_b128 v[212:215], v141 offset:53248
	ds_read_b128 v[216:219], v141 offset:54272
	ds_read_b128 v[220:223], v141 offset:55296
	ds_read_b128 v[228:231], v141 offset:56320
	s_barrier
	s_waitcnt lgkmcnt(0)
	s_setprio 1
	s_waitcnt lgkmcnt(0)
	v_mfma_f32_16x16x32_bf16 v[30:33], v[176:179], v[34:37], v[30:33]
	v_mfma_f32_16x16x32_bf16 v[26:29], v[184:187], v[34:37], v[26:29]
	v_mfma_f32_16x16x32_bf16 v[22:25], v[176:179], v[192:195], v[22:25]
	v_mfma_f32_16x16x32_bf16 v[18:21], v[184:187], v[192:195], v[18:21]
	v_mfma_f32_16x16x32_bf16 v[14:17], v[176:179], v[212:215], v[14:17]
	v_mfma_f32_16x16x32_bf16 v[10:13], v[184:187], v[212:215], v[10:13]
	v_mfma_f32_16x16x32_bf16 v[6:9], v[176:179], v[220:223], v[6:9]
	v_mfma_f32_16x16x32_bf16 v[2:5], v[184:187], v[220:223], v[2:5]
	v_mfma_f32_16x16x32_bf16 v[62:65], v[180:183], v[42:45], v[30:33]
	v_mfma_f32_16x16x32_bf16 v[54:57], v[188:191], v[42:45], v[26:29]
	v_mfma_f32_16x16x32_bf16 v[46:49], v[180:183], v[208:211], v[22:25]
	v_mfma_f32_16x16x32_bf16 v[38:41], v[188:191], v[208:211], v[18:21]
	v_mfma_f32_16x16x32_bf16 v[30:33], v[180:183], v[216:219], v[14:17]
	v_mfma_f32_16x16x32_bf16 v[22:25], v[188:191], v[216:219], v[10:13]
	v_mfma_f32_16x16x32_bf16 v[14:17], v[180:183], v[228:231], v[6:9]
	v_mfma_f32_16x16x32_bf16 v[6:9], v[188:191], v[228:231], v[2:5]
	s_setprio 0
	s_setprio 1
	v_mfma_f32_16x16x32_bf16 v[2:5], v[196:199], v[34:37], v[58:61]
	v_mfma_f32_16x16x32_bf16 v[58:61], v[200:203], v[42:45], v[2:5]
	v_mfma_f32_16x16x32_bf16 v[2:5], v[204:207], v[34:37], v[144:147]
	v_mfma_f32_16x16x32_bf16 v[50:53], v[224:227], v[42:45], v[2:5]
	v_mfma_f32_16x16x32_bf16 v[2:5], v[196:199], v[192:195], v[148:151]
	v_mfma_f32_16x16x32_bf16 v[42:45], v[200:203], v[208:211], v[2:5]
	v_mfma_f32_16x16x32_bf16 v[2:5], v[204:207], v[192:195], v[156:159]
	v_mfma_f32_16x16x32_bf16 v[34:37], v[224:227], v[208:211], v[2:5]
	v_mfma_f32_16x16x32_bf16 v[2:5], v[196:199], v[212:215], v[160:163]
	v_mfma_f32_16x16x32_bf16 v[26:29], v[200:203], v[216:219], v[2:5]
	v_mfma_f32_16x16x32_bf16 v[2:5], v[204:207], v[212:215], v[164:167]
	v_mfma_f32_16x16x32_bf16 v[18:21], v[224:227], v[216:219], v[2:5]
	v_mfma_f32_16x16x32_bf16 v[2:5], v[196:199], v[220:223], v[168:171]
	v_mfma_f32_16x16x32_bf16 v[10:13], v[200:203], v[228:231], v[2:5]
	v_mfma_f32_16x16x32_bf16 v[2:5], v[204:207], v[220:223], v[172:175]
	v_mfma_f32_16x16x32_bf16 v[2:5], v[224:227], v[228:231], v[2:5]
	s_setprio 0
	s_barrier
	s_and_saveexec_b64 s[38:39], s[4:5]
	s_cbranch_execz .LBB0_1315
	s_barrier
